# GEMM loops: removed 64 provably redundant s_waitcnt lgkmcnt(0) at the head of MFMA clusters
# baseline (speedup 1.0000x reference)
; #define PG8_STAGE(bufoff, gbase, voff) do { _Pragma("unroll") for (int _i = 0; _i < 2; ++_i) \
;         __builtin_amdgcn_global_load_lds((const unsigned*)((const char*)(gbase) + (voff)[_i]), (LAS unsigned*)(lds + (bufoff) + ldsw + _i * 8192), 16, 0, 0); } while (0)
; #define PG8_LDA(dst, b, h) do { _Pragma("unroll") for (int m = 0; m < 4; ++m) _Pragma("unroll") for (int k = 0; k < 2; ++k) dst[m][k] = *(const LAS bf16x8*)(lds + PG8_SA(b, h) + aoff + m * 2048 + k * 1024); } while (0)
; #define PG8_LDB(dst, b, h) do { _Pragma("unroll") for (int n = 0; n < 2; ++n) _Pragma("unroll") for (int k = 0; k < 2; ++k) dst[n][k] = *(const LAS bf16x8*)(lds + PG8_SB(b, h) + boff + n * 2048 + k * 1024); } while (0)
; #define PG8_WAIT_V(n) asm volatile("s_waitcnt vmcnt(" #n ")" ::: "memory")
; #define PG8_WAIT_L(n) asm volatile("s_waitcnt lgkmcnt(" #n ")" ::: "memory")
; #define PG8_BAR __builtin_amdgcn_s_barrier()
; #define PG8_SCHED __builtin_amdgcn_sched_barrier(0)
; template <class Epi, class Sched, bool SWAPD = false>
; __device__ __forceinline__ void gemm_phase(LAS unsigned char* lds, const Gemm g, const Sched& S, const Epi& E) {
;     ...
;         const bool has_next = S.next(ui + 1, nxt);
;         const char* nA = has_next ? (const char*)g.A + nxt.aoff : cA; const char* nB = has_next ? (const char*)g.Bt + nxt.boff : cB;
;         const int nt = cur.nt ? cur.nt : ntK;
;         for (int t = 0; t < nt; t += 2) {
;             const bool last = (t == nt - 2);
;             const char* a1 = cA + (size_t)(t + 1) * kstepA;
;             const char* a2 = last ? nA : cA + (size_t)(t + 2) * kstepA; const char* b2 = last ? nB : cB + (size_t)(t + 2) * kstep;
;             const char* a3 = a2 + kstepA; const char* b3 = b2 + kstep;
;             PG8_LDB(B0, 0, 0); PG8_LDB(B1, 0, 1); PG8_SCHED; PG8_LDA(At, 0, 0); PG8_STAGE(PG8_SA(1, 1), a1 + hstepA, voffA);
;             PG8_WAIT_V(8); PG8_WAIT_L(0); PG8_BAR; PG8_MMA(0, 0, At, B0); PG8_MMA(0, 1, At, B1); PG8_BAR; PG8_SCHED;
;             PG8_LDA(At, 0, 1); PG8_STAGE(PG8_SB(0, 0), b2, voffB); PG8_STAGE(PG8_SB(0, 1), b2 + hstepB, voffB); PG8_STAGE(PG8_SA(0, 0), a2, voffA);
;             PG8_WAIT_V(8); PG8_WAIT_L(0); PG8_BAR; PG8_MMA(1, 0, At, B0); PG8_MMA(1, 1, At, B1); PG8_BAR; PG8_SCHED;
.LBB0_256:
	ds_read_b128 v[148:151], v145
	ds_read_b128 v[152:155], v145 offset:1024
	ds_read_b128 v[156:159], v145 offset:2048
	ds_read_b128 v[160:163], v145 offset:3072
	ds_read_b128 v[164:167], v146
	ds_read_b128 v[168:171], v146 offset:1024
	ds_read_b128 v[172:175], v146 offset:2048
	ds_read_b128 v[176:179], v146 offset:3072
	s_add_u32 s46, s44, 0xfffc0080
	s_addc_u32 s47, s45, -1
	s_cmp_eq_u32 s68, 12
	s_cselect_b32 s51, s13, s47
	s_cselect_b32 s50, s23, s46
	s_cselect_b32 s47, s64, s67
	s_cselect_b32 s46, s65, s66
	v_lshl_add_u64 v[140:141], s[44:45], 0, v[132:133]
	s_add_i32 m0, s31, 0xc000
	ds_read_b128 v[180:183], v147
	ds_read_b128 v[184:187], v147 offset:1024
	ds_read_b128 v[188:191], v147 offset:2048
	ds_read_b128 v[192:195], v147 offset:3072
	ds_read_b128 v[196:199], v147 offset:4096
	ds_read_b128 v[200:203], v147 offset:5120
	ds_read_b128 v[208:211], v147 offset:6144
	ds_read_b128 v[212:215], v147 offset:7168
	global_load_lds_dwordx4 v[140:141], off
	v_lshl_add_u64 v[140:141], s[44:45], 0, v[134:135]
	s_add_i32 m0, s31, 0xe000
	s_nop 0
	global_load_lds_dwordx4 v[140:141], off
	s_waitcnt vmcnt(8)
	s_waitcnt lgkmcnt(0)
	s_barrier
	s_setprio 1
	v_mfma_f32_16x16x32_bf16 v[124:127], v[148:151], v[180:183], v[124:127]
	v_mfma_f32_16x16x32_bf16 v[116:119], v[156:159], v[180:183], v[116:119]
	v_mfma_f32_16x16x32_bf16 v[108:111], v[148:151], v[188:191], v[108:111]
	v_mfma_f32_16x16x32_bf16 v[100:103], v[156:159], v[188:191], v[100:103]
	v_mfma_f32_16x16x32_bf16 v[92:95], v[148:151], v[196:199], v[92:95]
	v_mfma_f32_16x16x32_bf16 v[84:87], v[156:159], v[196:199], v[84:87]
	v_mfma_f32_16x16x32_bf16 v[76:79], v[148:151], v[208:211], v[76:79]
	v_mfma_f32_16x16x32_bf16 v[68:71], v[156:159], v[208:211], v[68:71]
	v_mfma_f32_16x16x32_bf16 v[124:127], v[152:155], v[184:187], v[124:127]
	v_mfma_f32_16x16x32_bf16 v[116:119], v[160:163], v[184:187], v[116:119]
	v_mfma_f32_16x16x32_bf16 v[108:111], v[152:155], v[192:195], v[108:111]
	v_mfma_f32_16x16x32_bf16 v[100:103], v[160:163], v[192:195], v[100:103]
	v_mfma_f32_16x16x32_bf16 v[92:95], v[152:155], v[200:203], v[92:95]
	v_mfma_f32_16x16x32_bf16 v[84:87], v[160:163], v[200:203], v[84:87]
	v_mfma_f32_16x16x32_bf16 v[76:79], v[152:155], v[212:215], v[76:79]
	v_mfma_f32_16x16x32_bf16 v[68:71], v[160:163], v[212:215], v[68:71]
	s_setprio 0
	s_setprio 1
	v_mfma_f32_16x16x32_bf16 v[120:123], v[164:167], v[180:183], v[120:123]
	v_mfma_f32_16x16x32_bf16 v[112:115], v[172:175], v[180:183], v[112:115]
	v_mfma_f32_16x16x32_bf16 v[104:107], v[164:167], v[188:191], v[104:107]
	v_mfma_f32_16x16x32_bf16 v[96:99], v[172:175], v[188:191], v[96:99]
	v_mfma_f32_16x16x32_bf16 v[88:91], v[164:167], v[196:199], v[88:91]
	v_mfma_f32_16x16x32_bf16 v[80:83], v[172:175], v[196:199], v[80:83]
	v_mfma_f32_16x16x32_bf16 v[72:75], v[164:167], v[208:211], v[72:75]
	v_mfma_f32_16x16x32_bf16 v[64:67], v[172:175], v[208:211], v[64:67]
	v_mfma_f32_16x16x32_bf16 v[120:123], v[168:171], v[184:187], v[120:123]
	v_mfma_f32_16x16x32_bf16 v[112:115], v[176:179], v[184:187], v[112:115]
	v_mfma_f32_16x16x32_bf16 v[104:107], v[168:171], v[192:195], v[104:107]
	v_mfma_f32_16x16x32_bf16 v[96:99], v[176:179], v[192:195], v[96:99]
	v_mfma_f32_16x16x32_bf16 v[88:91], v[168:171], v[200:203], v[88:91]
	v_mfma_f32_16x16x32_bf16 v[80:83], v[176:179], v[200:203], v[80:83]
	v_mfma_f32_16x16x32_bf16 v[72:75], v[168:171], v[212:215], v[72:75]
	v_mfma_f32_16x16x32_bf16 v[64:67], v[176:179], v[212:215], v[64:67]
	s_setprio 0
	s_barrier
	s_add_i32 s69, s54, s11
	v_lshl_add_u64 v[140:141], s[46:47], 0, v[130:131]
	s_mov_b32 m0, s69
	ds_read_b128 v[180:183], v147 offset:16384
	ds_read_b128 v[184:187], v147 offset:17408
	ds_read_b128 v[188:191], v147 offset:18432
	ds_read_b128 v[192:195], v147 offset:19456
	ds_read_b128 v[196:199], v147 offset:20480
	ds_read_b128 v[200:203], v147 offset:21504
	ds_read_b128 v[208:211], v147 offset:22528
	ds_read_b128 v[212:215], v147 offset:23552
	global_load_lds_dwordx4 v[140:141], off
	s_add_i32 m0, s69, 0x2000
	s_add_u32 s72, s46, 0x40000
	v_lshl_add_u64 v[204:205], s[46:47], 0, v[128:129]
	s_addc_u32 s73, s47, 0
	s_add_i32 s69, s55, s11
	global_load_lds_dwordx4 v[204:205], off
	v_lshl_add_u64 v[216:217], s[72:73], 0, v[130:131]
	s_mov_b32 m0, s69
	v_lshl_add_u64 v[218:219], s[50:51], 0, v[128:129]
	global_load_lds_dwordx4 v[216:217], off
	v_lshl_add_u64 v[216:217], s[72:73], 0, v[128:129]
	s_add_i32 m0, s69, 0x2000
	s_nop 0
	global_load_lds_dwordx4 v[216:217], off
	v_lshl_add_u64 v[216:217], s[50:51], 0, v[130:131]
	s_mov_b32 m0, s31
	s_nop 0
	global_load_lds_dwordx4 v[216:217], off
	s_mov_b32 m0, s33
	s_nop 0
	global_load_lds_dwordx4 v[218:219], off
	s_waitcnt vmcnt(8)
	s_waitcnt lgkmcnt(0)
	s_barrier
; #define PG8_STAGE(bufoff, gbase, voff) do { _Pragma("unroll") for (int _i = 0; _i < 2; ++_i) \
;         __builtin_amdgcn_global_load_lds((const unsigned*)((const char*)(gbase) + (voff)[_i]), (LAS unsigned*)(lds + (bufoff) + ldsw + _i * 8192), 16, 0, 0); } while (0)
; #define PG8_LDA(dst, b, h) do { _Pragma("unroll") for (int m = 0; m < 4; ++m) _Pragma("unroll") for (int k = 0; k < 2; ++k) dst[m][k] = *(const LAS bf16x8*)(lds + PG8_SA(b, h) + aoff + m * 2048 + k * 1024); } while (0)
; #define PG8_LDB(dst, b, h) do { _Pragma("unroll") for (int n = 0; n < 2; ++n) _Pragma("unroll") for (int k = 0; k < 2; ++k) dst[n][k] = *(const LAS bf16x8*)(lds + PG8_SB(b, h) + boff + n * 2048 + k * 1024); } while (0)
; #define PG8_WAIT_V(n) asm volatile("s_waitcnt vmcnt(" #n ")" ::: "memory")
; #define PG8_WAIT_L(n) asm volatile("s_waitcnt lgkmcnt(" #n ")" ::: "memory")
; #define PG8_BAR __builtin_amdgcn_s_barrier()
; #define PG8_SCHED __builtin_amdgcn_sched_barrier(0)
; template <class Epi, class Sched, bool SWAPD = false>
; __device__ __forceinline__ void gemm_phase(LAS unsigned char* lds, const Gemm g, const Sched& S, const Epi& E) {
;     ...
;             PG8_WAIT_V(8); PG8_WAIT_L(0); PG8_BAR; PG8_MMA(1, 0, At, B0); PG8_MMA(1, 1, At, B1); PG8_BAR; PG8_SCHED;
;             PG8_LDB(B0, 1, 0); PG8_LDB(B1, 1, 1); PG8_SCHED; PG8_LDA(At, 1, 0); PG8_STAGE(PG8_SA(0, 1), a2 + hstepA, voffA);
;             PG8_WAIT_V(8); PG8_WAIT_L(0); PG8_BAR; PG8_MMA(0, 0, At, B0); PG8_MMA(0, 1, At, B1); PG8_BAR; PG8_SCHED;
	s_setprio 1
	v_mfma_f32_16x16x32_bf16 v[60:63], v[148:151], v[180:183], v[60:63]
	v_mfma_f32_16x16x32_bf16 v[52:55], v[156:159], v[180:183], v[52:55]
	v_mfma_f32_16x16x32_bf16 v[44:47], v[148:151], v[188:191], v[44:47]
	v_mfma_f32_16x16x32_bf16 v[36:39], v[156:159], v[188:191], v[36:39]
	v_mfma_f32_16x16x32_bf16 v[28:31], v[148:151], v[196:199], v[28:31]
	v_mfma_f32_16x16x32_bf16 v[20:23], v[156:159], v[196:199], v[20:23]
	v_mfma_f32_16x16x32_bf16 v[12:15], v[148:151], v[208:211], v[12:15]
	v_mfma_f32_16x16x32_bf16 v[4:7], v[156:159], v[208:211], v[4:7]
	v_mfma_f32_16x16x32_bf16 v[60:63], v[152:155], v[184:187], v[60:63]
	v_mfma_f32_16x16x32_bf16 v[52:55], v[160:163], v[184:187], v[52:55]
	v_mfma_f32_16x16x32_bf16 v[44:47], v[152:155], v[192:195], v[44:47]
	v_mfma_f32_16x16x32_bf16 v[36:39], v[160:163], v[192:195], v[36:39]
	v_mfma_f32_16x16x32_bf16 v[28:31], v[152:155], v[200:203], v[28:31]
	v_mfma_f32_16x16x32_bf16 v[20:23], v[160:163], v[200:203], v[20:23]
	v_mfma_f32_16x16x32_bf16 v[12:15], v[152:155], v[212:215], v[12:15]
	v_mfma_f32_16x16x32_bf16 v[4:7], v[160:163], v[212:215], v[4:7]
	s_setprio 0
	s_setprio 1
	v_mfma_f32_16x16x32_bf16 v[56:59], v[164:167], v[180:183], v[56:59]
	v_mfma_f32_16x16x32_bf16 v[48:51], v[172:175], v[180:183], v[48:51]
	v_mfma_f32_16x16x32_bf16 v[40:43], v[164:167], v[188:191], v[40:43]
	v_mfma_f32_16x16x32_bf16 v[32:35], v[172:175], v[188:191], v[32:35]
	v_mfma_f32_16x16x32_bf16 v[24:27], v[164:167], v[196:199], v[24:27]
	v_mfma_f32_16x16x32_bf16 v[16:19], v[172:175], v[196:199], v[16:19]
	v_mfma_f32_16x16x32_bf16 v[8:11], v[164:167], v[208:211], v[8:11]
	v_mfma_f32_16x16x32_bf16 v[0:3], v[172:175], v[208:211], v[0:3]
	v_mfma_f32_16x16x32_bf16 v[56:59], v[168:171], v[184:187], v[56:59]
	v_mfma_f32_16x16x32_bf16 v[48:51], v[176:179], v[184:187], v[48:51]
	v_mfma_f32_16x16x32_bf16 v[40:43], v[168:171], v[192:195], v[40:43]
	v_mfma_f32_16x16x32_bf16 v[32:35], v[176:179], v[192:195], v[32:35]
	v_mfma_f32_16x16x32_bf16 v[24:27], v[168:171], v[200:203], v[24:27]
	v_mfma_f32_16x16x32_bf16 v[16:19], v[176:179], v[200:203], v[16:19]
	v_mfma_f32_16x16x32_bf16 v[8:11], v[168:171], v[212:215], v[8:11]
	v_mfma_f32_16x16x32_bf16 v[0:3], v[176:179], v[212:215], v[0:3]
	s_setprio 0
	s_barrier
	s_add_i32 s69, 0, 0x18000
	s_add_i32 s72, 0, 0x1c000
	v_add_u32_e32 v160, s69, v143
	v_add_u32_e32 v176, s72, v143
	ds_read_b128 v[148:151], v160
	ds_read_b128 v[152:155], v160 offset:1024
	ds_read_b128 v[156:159], v160 offset:2048
	ds_read_b128 v[160:163], v160 offset:3072
	ds_read_b128 v[164:167], v176
	ds_read_b128 v[168:171], v176 offset:1024
	ds_read_b128 v[172:175], v176 offset:2048
	ds_read_b128 v[176:179], v176 offset:3072
	s_add_u32 s50, s50, 0x40000
	s_addc_u32 s51, s51, 0
	s_mov_b32 m0, s34
	v_lshl_add_u64 v[220:221], s[50:51], 0, v[130:131]
	ds_read_b128 v[180:183], v147 offset:32768
	ds_read_b128 v[184:187], v147 offset:33792
	ds_read_b128 v[188:191], v147 offset:34816
	ds_read_b128 v[192:195], v147 offset:35840
	ds_read_b128 v[196:199], v147 offset:36864
	ds_read_b128 v[200:203], v147 offset:37888
	ds_read_b128 v[208:211], v147 offset:38912
	ds_read_b128 v[212:215], v147 offset:39936
	global_load_lds_dwordx4 v[220:221], off
	v_lshl_add_u64 v[220:221], s[50:51], 0, v[128:129]
	s_mov_b32 m0, s35
	s_nop 0
	global_load_lds_dwordx4 v[220:221], off
	s_waitcnt vmcnt(8)
	s_waitcnt lgkmcnt(0)
	s_barrier
	s_setprio 1
	v_mfma_f32_16x16x32_bf16 v[124:127], v[148:151], v[180:183], v[124:127]
	v_mfma_f32_16x16x32_bf16 v[116:119], v[156:159], v[180:183], v[116:119]
	v_mfma_f32_16x16x32_bf16 v[108:111], v[148:151], v[188:191], v[108:111]
	v_mfma_f32_16x16x32_bf16 v[100:103], v[156:159], v[188:191], v[100:103]
	v_mfma_f32_16x16x32_bf16 v[92:95], v[148:151], v[196:199], v[92:95]
	v_mfma_f32_16x16x32_bf16 v[84:87], v[156:159], v[196:199], v[84:87]
	v_mfma_f32_16x16x32_bf16 v[76:79], v[148:151], v[208:211], v[76:79]
	v_mfma_f32_16x16x32_bf16 v[68:71], v[156:159], v[208:211], v[68:71]
	v_mfma_f32_16x16x32_bf16 v[124:127], v[152:155], v[184:187], v[124:127]
	v_mfma_f32_16x16x32_bf16 v[116:119], v[160:163], v[184:187], v[116:119]
	v_mfma_f32_16x16x32_bf16 v[108:111], v[152:155], v[192:195], v[108:111]
	v_mfma_f32_16x16x32_bf16 v[100:103], v[160:163], v[192:195], v[100:103]
	v_mfma_f32_16x16x32_bf16 v[92:95], v[152:155], v[200:203], v[92:95]
	v_mfma_f32_16x16x32_bf16 v[84:87], v[160:163], v[200:203], v[84:87]
	v_mfma_f32_16x16x32_bf16 v[76:79], v[152:155], v[212:215], v[76:79]
	v_mfma_f32_16x16x32_bf16 v[68:71], v[160:163], v[212:215], v[68:71]
	s_setprio 0
	s_setprio 1
	v_mfma_f32_16x16x32_bf16 v[120:123], v[164:167], v[180:183], v[120:123]
	v_mfma_f32_16x16x32_bf16 v[112:115], v[172:175], v[180:183], v[112:115]
	v_mfma_f32_16x16x32_bf16 v[104:107], v[164:167], v[188:191], v[104:107]
	v_mfma_f32_16x16x32_bf16 v[96:99], v[172:175], v[188:191], v[96:99]
	v_mfma_f32_16x16x32_bf16 v[88:91], v[164:167], v[196:199], v[88:91]
	v_mfma_f32_16x16x32_bf16 v[80:83], v[172:175], v[196:199], v[80:83]
	v_mfma_f32_16x16x32_bf16 v[72:75], v[164:167], v[208:211], v[72:75]
	v_mfma_f32_16x16x32_bf16 v[64:67], v[172:175], v[208:211], v[64:67]
	v_mfma_f32_16x16x32_bf16 v[120:123], v[168:171], v[184:187], v[120:123]
	v_mfma_f32_16x16x32_bf16 v[112:115], v[176:179], v[184:187], v[112:115]
	v_mfma_f32_16x16x32_bf16 v[104:107], v[168:171], v[192:195], v[104:107]
	v_mfma_f32_16x16x32_bf16 v[96:99], v[176:179], v[192:195], v[96:99]
	v_mfma_f32_16x16x32_bf16 v[88:91], v[168:171], v[200:203], v[88:91]
	v_mfma_f32_16x16x32_bf16 v[80:83], v[176:179], v[200:203], v[80:83]
	v_mfma_f32_16x16x32_bf16 v[72:75], v[168:171], v[212:215], v[72:75]
	v_mfma_f32_16x16x32_bf16 v[64:67], v[176:179], v[212:215], v[64:67]
	s_setprio 0
	s_barrier
; #define PG8_STAGE(bufoff, gbase, voff) do { _Pragma("unroll") for (int _i = 0; _i < 2; ++_i) \
;         __builtin_amdgcn_global_load_lds((const unsigned*)((const char*)(gbase) + (voff)[_i]), (LAS unsigned*)(lds + (bufoff) + ldsw + _i * 8192), 16, 0, 0); } while (0)
; #define PG8_LDA(dst, b, h) do { _Pragma("unroll") for (int m = 0; m < 4; ++m) _Pragma("unroll") for (int k = 0; k < 2; ++k) dst[m][k] = *(const LAS bf16x8*)(lds + PG8_SA(b, h) + aoff + m * 2048 + k * 1024); } while (0)
; #define PG8_WAIT_V(n) asm volatile("s_waitcnt vmcnt(" #n ")" ::: "memory")
; #define PG8_WAIT_L(n) asm volatile("s_waitcnt lgkmcnt(" #n ")" ::: "memory")
; #define PG8_BAR __builtin_amdgcn_s_barrier()
; #define PG8_SCHED __builtin_amdgcn_sched_barrier(0)
; template <class Epi, class Sched, bool SWAPD = false>
; __device__ __forceinline__ void gemm_phase(LAS unsigned char* lds, const Gemm g, const Sched& S, const Epi& E) {
;     ...
;             PG8_LDA(At, 1, 1); PG8_STAGE(PG8_SB(1, 0), b3, voffB); PG8_STAGE(PG8_SB(1, 1), b3 + hstepB, voffB); PG8_STAGE(PG8_SA(1, 0), a3, voffA);
;             PG8_WAIT_V(8); PG8_WAIT_L(0); PG8_BAR; PG8_MMA(1, 0, At, B0); PG8_MMA(1, 1, At, B1); PG8_BAR; PG8_SCHED;
;         }
;         if (wr == 0) PG8_BAR;
	s_add_i32 s50, s69, s11
	v_lshl_add_u64 v[140:141], v[140:141], 0, s[6:7]
	s_mov_b32 m0, s50
	ds_read_b128 v[180:183], v147 offset:49152
	ds_read_b128 v[184:187], v147 offset:50176
	ds_read_b128 v[188:191], v147 offset:51200
	ds_read_b128 v[192:195], v147 offset:52224
	ds_read_b128 v[196:199], v147 offset:53248
	ds_read_b128 v[200:203], v147 offset:54272
	ds_read_b128 v[208:211], v147 offset:55296
	ds_read_b128 v[212:215], v147 offset:56320
	global_load_lds_dwordx4 v[140:141], off
	s_add_i32 m0, s50, 0x2000
	s_add_u32 s46, s46, 0x40080
	v_lshl_add_u64 v[140:141], v[204:205], 0, s[6:7]
	s_addc_u32 s47, s47, 0
	s_add_i32 s50, s72, s11
	global_load_lds_dwordx4 v[140:141], off
	v_lshl_add_u64 v[140:141], s[46:47], 0, v[130:131]
	s_mov_b32 m0, s50
	s_nop 0
	global_load_lds_dwordx4 v[140:141], off
	v_lshl_add_u64 v[140:141], s[46:47], 0, v[128:129]
	s_add_i32 m0, s50, 0x2000
	s_nop 0
	global_load_lds_dwordx4 v[140:141], off
	v_lshl_add_u64 v[140:141], v[216:217], 0, s[6:7]
	s_mov_b32 m0, s52
	s_nop 0
	global_load_lds_dwordx4 v[140:141], off
	v_lshl_add_u64 v[140:141], v[218:219], 0, s[6:7]
	s_mov_b32 m0, s53
	s_nop 0
	global_load_lds_dwordx4 v[140:141], off
	s_waitcnt vmcnt(8)
	s_waitcnt lgkmcnt(0)
	s_barrier
	s_setprio 1
	v_mfma_f32_16x16x32_bf16 v[60:63], v[148:151], v[180:183], v[60:63]
	v_mfma_f32_16x16x32_bf16 v[52:55], v[156:159], v[180:183], v[52:55]
	v_mfma_f32_16x16x32_bf16 v[44:47], v[148:151], v[188:191], v[44:47]
	v_mfma_f32_16x16x32_bf16 v[36:39], v[156:159], v[188:191], v[36:39]
	v_mfma_f32_16x16x32_bf16 v[28:31], v[148:151], v[196:199], v[28:31]
	v_mfma_f32_16x16x32_bf16 v[20:23], v[156:159], v[196:199], v[20:23]
	v_mfma_f32_16x16x32_bf16 v[12:15], v[148:151], v[208:211], v[12:15]
	v_mfma_f32_16x16x32_bf16 v[4:7], v[156:159], v[208:211], v[4:7]
	v_mfma_f32_16x16x32_bf16 v[60:63], v[152:155], v[184:187], v[60:63]
	v_mfma_f32_16x16x32_bf16 v[52:55], v[160:163], v[184:187], v[52:55]
	v_mfma_f32_16x16x32_bf16 v[44:47], v[152:155], v[192:195], v[44:47]
	v_mfma_f32_16x16x32_bf16 v[36:39], v[160:163], v[192:195], v[36:39]
	v_mfma_f32_16x16x32_bf16 v[28:31], v[152:155], v[200:203], v[28:31]
	v_mfma_f32_16x16x32_bf16 v[20:23], v[160:163], v[200:203], v[20:23]
	v_mfma_f32_16x16x32_bf16 v[12:15], v[152:155], v[212:215], v[12:15]
	v_mfma_f32_16x16x32_bf16 v[4:7], v[160:163], v[212:215], v[4:7]
	s_setprio 0
	s_setprio 1
	v_mfma_f32_16x16x32_bf16 v[56:59], v[164:167], v[180:183], v[56:59]
	v_mfma_f32_16x16x32_bf16 v[48:51], v[172:175], v[180:183], v[48:51]
	v_mfma_f32_16x16x32_bf16 v[40:43], v[164:167], v[188:191], v[40:43]
	v_mfma_f32_16x16x32_bf16 v[32:35], v[172:175], v[188:191], v[32:35]
	v_mfma_f32_16x16x32_bf16 v[24:27], v[164:167], v[196:199], v[24:27]
	v_mfma_f32_16x16x32_bf16 v[16:19], v[172:175], v[196:199], v[16:19]
	v_mfma_f32_16x16x32_bf16 v[8:11], v[164:167], v[208:211], v[8:11]
	v_mfma_f32_16x16x32_bf16 v[0:3], v[172:175], v[208:211], v[0:3]
	v_mfma_f32_16x16x32_bf16 v[56:59], v[168:171], v[184:187], v[56:59]
	v_mfma_f32_16x16x32_bf16 v[48:51], v[176:179], v[184:187], v[48:51]
	v_mfma_f32_16x16x32_bf16 v[40:43], v[168:171], v[192:195], v[40:43]
	v_mfma_f32_16x16x32_bf16 v[32:35], v[176:179], v[192:195], v[32:35]
	v_mfma_f32_16x16x32_bf16 v[24:27], v[168:171], v[200:203], v[24:27]
	v_mfma_f32_16x16x32_bf16 v[16:19], v[176:179], v[200:203], v[16:19]
	v_mfma_f32_16x16x32_bf16 v[8:11], v[168:171], v[212:215], v[8:11]
	v_mfma_f32_16x16x32_bf16 v[0:3], v[176:179], v[212:215], v[0:3]
	s_setprio 0
	s_barrier
	s_add_i32 s68, s68, 2
	s_add_u32 s44, s44, 0x100
	s_addc_u32 s45, s45, 0
	s_add_u32 s66, s66, 0x100
	s_addc_u32 s67, s67, 0
	s_cmp_gt_u32 s68, 13
	s_cbranch_scc0 .LBB0_256
	s_and_b64 vcc, exec, s[8:9]
	s_cbranch_vccz .LBB0_259
	s_barrier

; #define PG8_STAGE(bufoff, gbase, voff) do { _Pragma("unroll") for (int _i = 0; _i < 2; ++_i) \
;         __builtin_amdgcn_global_load_lds((const unsigned*)((const char*)(gbase) + (voff)[_i]), (LAS unsigned*)(lds + (bufoff) + ldsw + _i * 8192), 16, 0, 0); } while (0)
; #define PG8_LDA(dst, b, h) do { _Pragma("unroll") for (int m = 0; m < 4; ++m) _Pragma("unroll") for (int k = 0; k < 2; ++k) dst[m][k] = *(const LAS bf16x8*)(lds + PG8_SA(b, h) + aoff + m * 2048 + k * 1024); } while (0)
; #define PG8_LDB(dst, b, h) do { _Pragma("unroll") for (int n = 0; n < 2; ++n) _Pragma("unroll") for (int k = 0; k < 2; ++k) dst[n][k] = *(const LAS bf16x8*)(lds + PG8_SB(b, h) + boff + n * 2048 + k * 1024); } while (0)
; #define PG8_WAIT_V(n) asm volatile("s_waitcnt vmcnt(" #n ")" ::: "memory")
; #define PG8_WAIT_L(n) asm volatile("s_waitcnt lgkmcnt(" #n ")" ::: "memory")
; #define PG8_BAR __builtin_amdgcn_s_barrier()
; #define PG8_SCHED __builtin_amdgcn_sched_barrier(0)
; template <class Epi, class Sched, bool SWAPD = false>
; __device__ __forceinline__ void gemm_phase(LAS unsigned char* lds, const Gemm g, const Sched& S, const Epi& E) {
;     ...
;         const bool has_next = S.next(ui + 1, nxt);
;         const char* nA = has_next ? (const char*)g.A + nxt.aoff : cA; const char* nB = has_next ? (const char*)g.Bt + nxt.boff : cB;
;         const int nt = cur.nt ? cur.nt : ntK;
;         for (int t = 0; t < nt; t += 2) {
;             const bool last = (t == nt - 2);
;             const char* a1 = cA + (size_t)(t + 1) * kstepA;
;             const char* a2 = last ? nA : cA + (size_t)(t + 2) * kstepA; const char* b2 = last ? nB : cB + (size_t)(t + 2) * kstep;
;             const char* a3 = a2 + kstepA; const char* b3 = b2 + kstep;
;             PG8_LDB(B0, 0, 0); PG8_LDB(B1, 0, 1); PG8_SCHED; PG8_LDA(At, 0, 0); PG8_STAGE(PG8_SA(1, 1), a1 + hstepA, voffA);
;             PG8_WAIT_V(8); PG8_WAIT_L(0); PG8_BAR; PG8_MMA(0, 0, At, B0); PG8_MMA(0, 1, At, B1); PG8_BAR; PG8_SCHED;
;             PG8_LDA(At, 0, 1); PG8_STAGE(PG8_SB(0, 0), b2, voffB); PG8_STAGE(PG8_SB(0, 1), b2 + hstepB, voffB); PG8_STAGE(PG8_SA(0, 0), a2, voffA);
;             PG8_WAIT_V(8); PG8_WAIT_L(0); PG8_BAR; PG8_MMA(1, 0, At, B0); PG8_MMA(1, 1, At, B1); PG8_BAR; PG8_SCHED;
.LBB0_353:
	v_add_u32_e32 v132, s57, v184
	ds_read_b128 v[174:177], v132
	ds_read_b128 v[178:181], v132 offset:1024
	ds_read_b128 v[188:191], v132 offset:2048
	ds_read_b128 v[192:195], v132 offset:3072
	v_add_u32_e32 v132, s64, v184
	ds_read_b128 v[196:199], v132
	ds_read_b128 v[200:203], v132 offset:1024
	ds_read_b128 v[208:211], v132 offset:2048
	ds_read_b128 v[212:215], v132 offset:3072
	s_add_i32 s77, s44, 2
	s_add_u32 s42, s38, 0x100
	s_addc_u32 s43, s39, 0
	s_cmp_eq_u32 s74, s44
	s_cselect_b32 s44, s35, s75
	s_cselect_b32 s47, s29, s43
	s_cselect_b32 s46, s33, s42
	s_cselect_b32 s45, s34, s76
	v_lshl_add_u64 v[182:183], s[38:39], 0, v[166:167]
	s_add_i32 m0, s30, 0xc000
	ds_read_b128 v[216:219], v186
	ds_read_b128 v[220:223], v186 offset:1024
	ds_read_b128 v[224:227], v186 offset:2048
	ds_read_b128 v[228:231], v186 offset:3072
	ds_read_b128 v[232:235], v186 offset:4096
	ds_read_b128 v[236:239], v186 offset:5120
	ds_read_b128 v[240:243], v186 offset:6144
	ds_read_b128 v[244:247], v186 offset:7168
	global_load_lds_dwordx4 v[182:183], off
	v_lshl_add_u64 v[182:183], s[38:39], 0, v[168:169]
	s_add_i32 m0, s30, 0xe000
	s_nop 0
	global_load_lds_dwordx4 v[182:183], off
	s_waitcnt vmcnt(8)
	s_waitcnt lgkmcnt(0)
	s_barrier
	s_setprio 1
	v_mfma_f32_16x16x32_bf16 v[124:127], v[174:177], v[216:219], v[124:127]
	v_mfma_f32_16x16x32_bf16 v[120:123], v[188:191], v[216:219], v[120:123]
	v_mfma_f32_16x16x32_bf16 v[108:111], v[174:177], v[224:227], v[108:111]
	v_mfma_f32_16x16x32_bf16 v[104:107], v[188:191], v[224:227], v[104:107]
	v_mfma_f32_16x16x32_bf16 v[92:95], v[174:177], v[232:235], v[92:95]
	v_mfma_f32_16x16x32_bf16 v[88:91], v[188:191], v[232:235], v[88:91]
	v_mfma_f32_16x16x32_bf16 v[76:79], v[174:177], v[240:243], v[76:79]
	v_mfma_f32_16x16x32_bf16 v[72:75], v[188:191], v[240:243], v[72:75]
	v_mfma_f32_16x16x32_bf16 v[124:127], v[178:181], v[220:223], v[124:127]
	v_mfma_f32_16x16x32_bf16 v[120:123], v[192:195], v[220:223], v[120:123]
	v_mfma_f32_16x16x32_bf16 v[108:111], v[178:181], v[228:231], v[108:111]
	v_mfma_f32_16x16x32_bf16 v[104:107], v[192:195], v[228:231], v[104:107]
	v_mfma_f32_16x16x32_bf16 v[92:95], v[178:181], v[236:239], v[92:95]
	v_mfma_f32_16x16x32_bf16 v[88:91], v[192:195], v[236:239], v[88:91]
	v_mfma_f32_16x16x32_bf16 v[76:79], v[178:181], v[244:247], v[76:79]
	v_mfma_f32_16x16x32_bf16 v[72:75], v[192:195], v[244:247], v[72:75]
	s_setprio 0
	s_setprio 1
	v_mfma_f32_16x16x32_bf16 v[116:119], v[196:199], v[216:219], v[116:119]
	v_mfma_f32_16x16x32_bf16 v[112:115], v[208:211], v[216:219], v[112:115]
	v_mfma_f32_16x16x32_bf16 v[100:103], v[196:199], v[224:227], v[100:103]
	v_mfma_f32_16x16x32_bf16 v[96:99], v[208:211], v[224:227], v[96:99]
	v_mfma_f32_16x16x32_bf16 v[84:87], v[196:199], v[232:235], v[84:87]
	v_mfma_f32_16x16x32_bf16 v[80:83], v[208:211], v[232:235], v[80:83]
	v_mfma_f32_16x16x32_bf16 v[68:71], v[196:199], v[240:243], v[68:71]
	v_mfma_f32_16x16x32_bf16 v[64:67], v[208:211], v[240:243], v[64:67]
	v_mfma_f32_16x16x32_bf16 v[116:119], v[200:203], v[220:223], v[116:119]
	v_mfma_f32_16x16x32_bf16 v[112:115], v[212:215], v[220:223], v[112:115]
	v_mfma_f32_16x16x32_bf16 v[100:103], v[200:203], v[228:231], v[100:103]
	v_mfma_f32_16x16x32_bf16 v[96:99], v[212:215], v[228:231], v[96:99]
	v_mfma_f32_16x16x32_bf16 v[84:87], v[200:203], v[236:239], v[84:87]
	v_mfma_f32_16x16x32_bf16 v[80:83], v[212:215], v[236:239], v[80:83]
	v_mfma_f32_16x16x32_bf16 v[68:71], v[200:203], v[244:247], v[68:71]
	v_mfma_f32_16x16x32_bf16 v[64:67], v[212:215], v[244:247], v[64:67]
	s_setprio 0
	s_barrier
	s_add_i32 s38, s57, s21
	v_lshl_add_u64 v[182:183], s[44:45], 0, v[128:129]
	s_mov_b32 m0, s38
	ds_read_b128 v[216:219], v186 offset:16384
	ds_read_b128 v[220:223], v186 offset:17408
	ds_read_b128 v[224:227], v186 offset:18432
	ds_read_b128 v[228:231], v186 offset:19456
	ds_read_b128 v[232:235], v186 offset:20480
	ds_read_b128 v[236:239], v186 offset:21504
	ds_read_b128 v[240:243], v186 offset:22528
	ds_read_b128 v[244:247], v186 offset:23552
	global_load_lds_dwordx4 v[182:183], off
	s_add_i32 m0, s38, 0x2000
	s_add_u32 s38, s44, 0xb0000
	v_lshl_add_u64 v[204:205], s[44:45], 0, v[130:131]
	s_addc_u32 s39, s45, 0
	s_add_i32 s78, s64, s21
	global_load_lds_dwordx4 v[204:205], off
	v_lshl_add_u64 v[248:249], s[38:39], 0, v[128:129]
	s_mov_b32 m0, s78
	v_lshl_add_u64 v[250:251], s[46:47], 0, v[130:131]
	global_load_lds_dwordx4 v[248:249], off
	v_lshl_add_u64 v[248:249], s[38:39], 0, v[130:131]
	s_add_i32 m0, s78, 0x2000
	s_nop 0
	global_load_lds_dwordx4 v[248:249], off
	v_lshl_add_u64 v[248:249], s[46:47], 0, v[128:129]
	s_mov_b32 m0, s30
	s_nop 0
	global_load_lds_dwordx4 v[248:249], off
	s_mov_b32 m0, s31
	s_nop 0
	global_load_lds_dwordx4 v[250:251], off
	s_waitcnt vmcnt(8)
	s_waitcnt lgkmcnt(0)
	s_barrier
; #define PG8_STAGE(bufoff, gbase, voff) do { _Pragma("unroll") for (int _i = 0; _i < 2; ++_i) \
;         __builtin_amdgcn_global_load_lds((const unsigned*)((const char*)(gbase) + (voff)[_i]), (LAS unsigned*)(lds + (bufoff) + ldsw + _i * 8192), 16, 0, 0); } while (0)
; #define PG8_LDA(dst, b, h) do { _Pragma("unroll") for (int m = 0; m < 4; ++m) _Pragma("unroll") for (int k = 0; k < 2; ++k) dst[m][k] = *(const LAS bf16x8*)(lds + PG8_SA(b, h) + aoff + m * 2048 + k * 1024); } while (0)
; #define PG8_LDB(dst, b, h) do { _Pragma("unroll") for (int n = 0; n < 2; ++n) _Pragma("unroll") for (int k = 0; k < 2; ++k) dst[n][k] = *(const LAS bf16x8*)(lds + PG8_SB(b, h) + boff + n * 2048 + k * 1024); } while (0)
; #define PG8_WAIT_V(n) asm volatile("s_waitcnt vmcnt(" #n ")" ::: "memory")
; #define PG8_WAIT_L(n) asm volatile("s_waitcnt lgkmcnt(" #n ")" ::: "memory")
; #define PG8_BAR __builtin_amdgcn_s_barrier()
; #define PG8_SCHED __builtin_amdgcn_sched_barrier(0)
; template <class Epi, class Sched, bool SWAPD = false>
; __device__ __forceinline__ void gemm_phase(LAS unsigned char* lds, const Gemm g, const Sched& S, const Epi& E) {
;     ...
;             PG8_WAIT_V(8); PG8_WAIT_L(0); PG8_BAR; PG8_MMA(1, 0, At, B0); PG8_MMA(1, 1, At, B1); PG8_BAR; PG8_SCHED;
;             PG8_LDB(B0, 1, 0); PG8_LDB(B1, 1, 1); PG8_SCHED; PG8_LDA(At, 1, 0); PG8_STAGE(PG8_SA(0, 1), a2 + hstepA, voffA);
;             PG8_WAIT_V(8); PG8_WAIT_L(0); PG8_BAR; PG8_MMA(0, 0, At, B0); PG8_MMA(0, 1, At, B1); PG8_BAR; PG8_SCHED;
	s_setprio 1
	v_mfma_f32_16x16x32_bf16 v[60:63], v[174:177], v[216:219], v[60:63]
	v_mfma_f32_16x16x32_bf16 v[56:59], v[188:191], v[216:219], v[56:59]
	v_mfma_f32_16x16x32_bf16 v[44:47], v[174:177], v[224:227], v[44:47]
	v_mfma_f32_16x16x32_bf16 v[40:43], v[188:191], v[224:227], v[40:43]
	v_mfma_f32_16x16x32_bf16 v[28:31], v[174:177], v[232:235], v[28:31]
	v_mfma_f32_16x16x32_bf16 v[24:27], v[188:191], v[232:235], v[24:27]
	v_mfma_f32_16x16x32_bf16 v[12:15], v[174:177], v[240:243], v[12:15]
	v_mfma_f32_16x16x32_bf16 v[8:11], v[188:191], v[240:243], v[8:11]
	v_mfma_f32_16x16x32_bf16 v[60:63], v[178:181], v[220:223], v[60:63]
	v_mfma_f32_16x16x32_bf16 v[56:59], v[192:195], v[220:223], v[56:59]
	v_mfma_f32_16x16x32_bf16 v[44:47], v[178:181], v[228:231], v[44:47]
	v_mfma_f32_16x16x32_bf16 v[40:43], v[192:195], v[228:231], v[40:43]
	v_mfma_f32_16x16x32_bf16 v[28:31], v[178:181], v[236:239], v[28:31]
	v_mfma_f32_16x16x32_bf16 v[24:27], v[192:195], v[236:239], v[24:27]
	v_mfma_f32_16x16x32_bf16 v[12:15], v[178:181], v[244:247], v[12:15]
	v_mfma_f32_16x16x32_bf16 v[8:11], v[192:195], v[244:247], v[8:11]
	s_setprio 0
	s_setprio 1
	v_mfma_f32_16x16x32_bf16 v[52:55], v[196:199], v[216:219], v[52:55]
	v_mfma_f32_16x16x32_bf16 v[48:51], v[208:211], v[216:219], v[48:51]
	v_mfma_f32_16x16x32_bf16 v[36:39], v[196:199], v[224:227], v[36:39]
	v_mfma_f32_16x16x32_bf16 v[32:35], v[208:211], v[224:227], v[32:35]
	v_mfma_f32_16x16x32_bf16 v[20:23], v[196:199], v[232:235], v[20:23]
	v_mfma_f32_16x16x32_bf16 v[16:19], v[208:211], v[232:235], v[16:19]
	v_mfma_f32_16x16x32_bf16 v[4:7], v[196:199], v[240:243], v[4:7]
	v_mfma_f32_16x16x32_bf16 v[0:3], v[208:211], v[240:243], v[0:3]
	v_mfma_f32_16x16x32_bf16 v[52:55], v[200:203], v[220:223], v[52:55]
	v_mfma_f32_16x16x32_bf16 v[48:51], v[212:215], v[220:223], v[48:51]
	v_mfma_f32_16x16x32_bf16 v[36:39], v[200:203], v[228:231], v[36:39]
	v_mfma_f32_16x16x32_bf16 v[32:35], v[212:215], v[228:231], v[32:35]
	v_mfma_f32_16x16x32_bf16 v[20:23], v[200:203], v[236:239], v[20:23]
	v_mfma_f32_16x16x32_bf16 v[16:19], v[212:215], v[236:239], v[16:19]
	v_mfma_f32_16x16x32_bf16 v[4:7], v[200:203], v[244:247], v[4:7]
	v_mfma_f32_16x16x32_bf16 v[0:3], v[212:215], v[244:247], v[0:3]
	s_setprio 0
	s_barrier
	s_add_i32 s78, 0, 0x18000
	v_add_u32_e32 v132, s78, v184
	s_add_i32 s79, 0, 0x1c000
	ds_read_b128 v[174:177], v132
	ds_read_b128 v[178:181], v132 offset:1024
	ds_read_b128 v[188:191], v132 offset:2048
	ds_read_b128 v[192:195], v132 offset:3072
	v_add_u32_e32 v132, s79, v184
	ds_read_b128 v[196:199], v132
	ds_read_b128 v[200:203], v132 offset:1024
	ds_read_b128 v[208:211], v132 offset:2048
	ds_read_b128 v[212:215], v132 offset:3072
	s_add_u32 s38, s46, 0xb0000
	s_addc_u32 s39, s47, 0
	s_mov_b32 m0, s50
	v_lshl_add_u64 v[252:253], s[38:39], 0, v[128:129]
	ds_read_b128 v[216:219], v186 offset:32768
	ds_read_b128 v[220:223], v186 offset:33792
	ds_read_b128 v[224:227], v186 offset:34816
	ds_read_b128 v[228:231], v186 offset:35840
	ds_read_b128 v[232:235], v186 offset:36864
	ds_read_b128 v[236:239], v186 offset:37888
	ds_read_b128 v[240:243], v186 offset:38912
	ds_read_b128 v[244:247], v186 offset:39936
	global_load_lds_dwordx4 v[252:253], off
	v_lshl_add_u64 v[252:253], s[38:39], 0, v[130:131]
	s_mov_b32 m0, s51
	s_nop 0
	global_load_lds_dwordx4 v[252:253], off
	s_waitcnt vmcnt(8)
	s_waitcnt lgkmcnt(0)
	s_barrier
	s_setprio 1
	v_mfma_f32_16x16x32_bf16 v[124:127], v[174:177], v[216:219], v[124:127]
	v_mfma_f32_16x16x32_bf16 v[120:123], v[188:191], v[216:219], v[120:123]
	v_mfma_f32_16x16x32_bf16 v[108:111], v[174:177], v[224:227], v[108:111]
	v_mfma_f32_16x16x32_bf16 v[104:107], v[188:191], v[224:227], v[104:107]
	v_mfma_f32_16x16x32_bf16 v[92:95], v[174:177], v[232:235], v[92:95]
	v_mfma_f32_16x16x32_bf16 v[88:91], v[188:191], v[232:235], v[88:91]
	v_mfma_f32_16x16x32_bf16 v[76:79], v[174:177], v[240:243], v[76:79]
	v_mfma_f32_16x16x32_bf16 v[72:75], v[188:191], v[240:243], v[72:75]
	v_mfma_f32_16x16x32_bf16 v[124:127], v[178:181], v[220:223], v[124:127]
	v_mfma_f32_16x16x32_bf16 v[120:123], v[192:195], v[220:223], v[120:123]
	v_mfma_f32_16x16x32_bf16 v[108:111], v[178:181], v[228:231], v[108:111]
	v_mfma_f32_16x16x32_bf16 v[104:107], v[192:195], v[228:231], v[104:107]
	v_mfma_f32_16x16x32_bf16 v[92:95], v[178:181], v[236:239], v[92:95]
	v_mfma_f32_16x16x32_bf16 v[88:91], v[192:195], v[236:239], v[88:91]
	v_mfma_f32_16x16x32_bf16 v[76:79], v[178:181], v[244:247], v[76:79]
	v_mfma_f32_16x16x32_bf16 v[72:75], v[192:195], v[244:247], v[72:75]
	s_setprio 0
	s_setprio 1
	v_mfma_f32_16x16x32_bf16 v[116:119], v[196:199], v[216:219], v[116:119]
	v_mfma_f32_16x16x32_bf16 v[112:115], v[208:211], v[216:219], v[112:115]
	v_mfma_f32_16x16x32_bf16 v[100:103], v[196:199], v[224:227], v[100:103]
	v_mfma_f32_16x16x32_bf16 v[96:99], v[208:211], v[224:227], v[96:99]
	v_mfma_f32_16x16x32_bf16 v[84:87], v[196:199], v[232:235], v[84:87]
	v_mfma_f32_16x16x32_bf16 v[80:83], v[208:211], v[232:235], v[80:83]
	v_mfma_f32_16x16x32_bf16 v[68:71], v[196:199], v[240:243], v[68:71]
	v_mfma_f32_16x16x32_bf16 v[64:67], v[208:211], v[240:243], v[64:67]
	v_mfma_f32_16x16x32_bf16 v[116:119], v[200:203], v[220:223], v[116:119]
	v_mfma_f32_16x16x32_bf16 v[112:115], v[212:215], v[220:223], v[112:115]
	v_mfma_f32_16x16x32_bf16 v[100:103], v[200:203], v[228:231], v[100:103]
	v_mfma_f32_16x16x32_bf16 v[96:99], v[212:215], v[228:231], v[96:99]
	v_mfma_f32_16x16x32_bf16 v[84:87], v[200:203], v[236:239], v[84:87]
	v_mfma_f32_16x16x32_bf16 v[80:83], v[212:215], v[236:239], v[80:83]
	v_mfma_f32_16x16x32_bf16 v[68:71], v[200:203], v[244:247], v[68:71]
	v_mfma_f32_16x16x32_bf16 v[64:67], v[212:215], v[244:247], v[64:67]
	s_setprio 0
	s_barrier
; #define PG8_STAGE(bufoff, gbase, voff) do { _Pragma("unroll") for (int _i = 0; _i < 2; ++_i) \
;         __builtin_amdgcn_global_load_lds((const unsigned*)((const char*)(gbase) + (voff)[_i]), (LAS unsigned*)(lds + (bufoff) + ldsw + _i * 8192), 16, 0, 0); } while (0)
; #define PG8_LDA(dst, b, h) do { _Pragma("unroll") for (int m = 0; m < 4; ++m) _Pragma("unroll") for (int k = 0; k < 2; ++k) dst[m][k] = *(const LAS bf16x8*)(lds + PG8_SA(b, h) + aoff + m * 2048 + k * 1024); } while (0)
; #define PG8_WAIT_V(n) asm volatile("s_waitcnt vmcnt(" #n ")" ::: "memory")
; #define PG8_WAIT_L(n) asm volatile("s_waitcnt lgkmcnt(" #n ")" ::: "memory")
; #define PG8_BAR __builtin_amdgcn_s_barrier()
; #define PG8_SCHED __builtin_amdgcn_sched_barrier(0)
; template <class Epi, class Sched, bool SWAPD = false>
; __device__ __forceinline__ void gemm_phase(LAS unsigned char* lds, const Gemm g, const Sched& S, const Epi& E) {
;     ...
;             PG8_LDA(At, 1, 1); PG8_STAGE(PG8_SB(1, 0), b3, voffB); PG8_STAGE(PG8_SB(1, 1), b3 + hstepB, voffB); PG8_STAGE(PG8_SA(1, 0), a3, voffA);
;             PG8_WAIT_V(8); PG8_WAIT_L(0); PG8_BAR; PG8_MMA(1, 0, At, B0); PG8_MMA(1, 1, At, B1); PG8_BAR; PG8_SCHED;
;         }
;         if (wr == 0) PG8_BAR;
	s_add_i32 s38, s78, s21
	v_lshl_add_u64 v[182:183], v[182:183], 0, s[8:9]
	s_mov_b32 m0, s38
	ds_read_b128 v[216:219], v186 offset:49152
	ds_read_b128 v[220:223], v186 offset:50176
	ds_read_b128 v[224:227], v186 offset:51200
	ds_read_b128 v[228:231], v186 offset:52224
	ds_read_b128 v[232:235], v186 offset:53248
	ds_read_b128 v[236:239], v186 offset:54272
	ds_read_b128 v[240:243], v186 offset:55296
	ds_read_b128 v[244:247], v186 offset:56320
	global_load_lds_dwordx4 v[182:183], off
	s_add_i32 m0, s38, 0x2000
	s_add_u32 s38, s44, 0xb0080
	v_lshl_add_u64 v[182:183], v[204:205], 0, s[8:9]
	s_addc_u32 s39, s45, 0
	s_add_i32 s44, s79, s21
	global_load_lds_dwordx4 v[182:183], off
	v_lshl_add_u64 v[182:183], s[38:39], 0, v[128:129]
	s_mov_b32 m0, s44
	s_nop 0
	global_load_lds_dwordx4 v[182:183], off
	v_lshl_add_u64 v[182:183], s[38:39], 0, v[130:131]
	s_add_i32 m0, s44, 0x2000
	s_nop 0
	global_load_lds_dwordx4 v[182:183], off
	v_lshl_add_u64 v[182:183], v[248:249], 0, s[8:9]
	s_mov_b32 m0, s54
	s_nop 0
	global_load_lds_dwordx4 v[182:183], off
	v_lshl_add_u64 v[182:183], v[250:251], 0, s[8:9]
	s_mov_b32 m0, s55
	s_nop 0
	global_load_lds_dwordx4 v[182:183], off
	s_waitcnt vmcnt(8)
	s_waitcnt lgkmcnt(0)
	s_barrier
	s_setprio 1
	v_mfma_f32_16x16x32_bf16 v[60:63], v[174:177], v[216:219], v[60:63]
	v_mfma_f32_16x16x32_bf16 v[56:59], v[188:191], v[216:219], v[56:59]
	v_mfma_f32_16x16x32_bf16 v[44:47], v[174:177], v[224:227], v[44:47]
	v_mfma_f32_16x16x32_bf16 v[40:43], v[188:191], v[224:227], v[40:43]
	v_mfma_f32_16x16x32_bf16 v[28:31], v[174:177], v[232:235], v[28:31]
	v_mfma_f32_16x16x32_bf16 v[24:27], v[188:191], v[232:235], v[24:27]
	v_mfma_f32_16x16x32_bf16 v[12:15], v[174:177], v[240:243], v[12:15]
	v_mfma_f32_16x16x32_bf16 v[8:11], v[188:191], v[240:243], v[8:11]
	v_mfma_f32_16x16x32_bf16 v[60:63], v[178:181], v[220:223], v[60:63]
	v_mfma_f32_16x16x32_bf16 v[56:59], v[192:195], v[220:223], v[56:59]
	v_mfma_f32_16x16x32_bf16 v[44:47], v[178:181], v[228:231], v[44:47]
	v_mfma_f32_16x16x32_bf16 v[40:43], v[192:195], v[228:231], v[40:43]
	v_mfma_f32_16x16x32_bf16 v[28:31], v[178:181], v[236:239], v[28:31]
	v_mfma_f32_16x16x32_bf16 v[24:27], v[192:195], v[236:239], v[24:27]
	v_mfma_f32_16x16x32_bf16 v[12:15], v[178:181], v[244:247], v[12:15]
	v_mfma_f32_16x16x32_bf16 v[8:11], v[192:195], v[244:247], v[8:11]
	s_setprio 0
	s_setprio 1
	v_mfma_f32_16x16x32_bf16 v[52:55], v[196:199], v[216:219], v[52:55]
	v_mfma_f32_16x16x32_bf16 v[48:51], v[208:211], v[216:219], v[48:51]
	v_mfma_f32_16x16x32_bf16 v[36:39], v[196:199], v[224:227], v[36:39]
	v_mfma_f32_16x16x32_bf16 v[32:35], v[208:211], v[224:227], v[32:35]
	v_mfma_f32_16x16x32_bf16 v[20:23], v[196:199], v[232:235], v[20:23]
	v_mfma_f32_16x16x32_bf16 v[16:19], v[208:211], v[232:235], v[16:19]
	v_mfma_f32_16x16x32_bf16 v[4:7], v[196:199], v[240:243], v[4:7]
	v_mfma_f32_16x16x32_bf16 v[0:3], v[208:211], v[240:243], v[0:3]
	v_mfma_f32_16x16x32_bf16 v[52:55], v[200:203], v[220:223], v[52:55]
	v_mfma_f32_16x16x32_bf16 v[48:51], v[212:215], v[220:223], v[48:51]
	v_mfma_f32_16x16x32_bf16 v[36:39], v[200:203], v[228:231], v[36:39]
	v_mfma_f32_16x16x32_bf16 v[32:35], v[212:215], v[228:231], v[32:35]
	v_mfma_f32_16x16x32_bf16 v[20:23], v[200:203], v[236:239], v[20:23]
	v_mfma_f32_16x16x32_bf16 v[16:19], v[212:215], v[236:239], v[16:19]
	v_mfma_f32_16x16x32_bf16 v[4:7], v[200:203], v[244:247], v[4:7]
	v_mfma_f32_16x16x32_bf16 v[0:3], v[212:215], v[244:247], v[0:3]
	s_setprio 0
	s_barrier
	s_add_u32 s75, s75, 0x100
	s_addc_u32 s76, s76, 0
	s_cmp_ge_i32 s77, s0
	s_mov_b64 s[38:39], s[42:43]
	s_mov_b32 s44, s77
	s_cbranch_scc0 .LBB0_353
	s_and_b64 vcc, exec, s[10:11]
	s_cbranch_vccz .LBB0_359

; #define PG8_STAGE(bufoff, gbase, voff) do { _Pragma("unroll") for (int _i = 0; _i < 2; ++_i) \
;         __builtin_amdgcn_global_load_lds((const unsigned*)((const char*)(gbase) + (voff)[_i]), (LAS unsigned*)(lds + (bufoff) + ldsw + _i * 8192), 16, 0, 0); } while (0)
; #define PG8_LDA(dst, b, h) do { _Pragma("unroll") for (int m = 0; m < 4; ++m) _Pragma("unroll") for (int k = 0; k < 2; ++k) dst[m][k] = *(const LAS bf16x8*)(lds + PG8_SA(b, h) + aoff + m * 2048 + k * 1024); } while (0)
; #define PG8_LDB(dst, b, h) do { _Pragma("unroll") for (int n = 0; n < 2; ++n) _Pragma("unroll") for (int k = 0; k < 2; ++k) dst[n][k] = *(const LAS bf16x8*)(lds + PG8_SB(b, h) + boff + n * 2048 + k * 1024); } while (0)
; #define PG8_WAIT_V(n) asm volatile("s_waitcnt vmcnt(" #n ")" ::: "memory")
; #define PG8_WAIT_L(n) asm volatile("s_waitcnt lgkmcnt(" #n ")" ::: "memory")
; #define PG8_BAR __builtin_amdgcn_s_barrier()
; #define PG8_SCHED __builtin_amdgcn_sched_barrier(0)
; template <class Epi, class Sched, bool SWAPD = false>
; __device__ __forceinline__ void gemm_phase(LAS unsigned char* lds, const Gemm g, const Sched& S, const Epi& E) {
;     ...
;         const bool has_next = S.next(ui + 1, nxt);
;         const char* nA = has_next ? (const char*)g.A + nxt.aoff : cA; const char* nB = has_next ? (const char*)g.Bt + nxt.boff : cB;
;         const int nt = cur.nt ? cur.nt : ntK;
;         for (int t = 0; t < nt; t += 2) {
;             const bool last = (t == nt - 2);
;             const char* a1 = cA + (size_t)(t + 1) * kstepA;
;             const char* a2 = last ? nA : cA + (size_t)(t + 2) * kstepA; const char* b2 = last ? nB : cB + (size_t)(t + 2) * kstep;
;             const char* a3 = a2 + kstepA; const char* b3 = b2 + kstep;
;             PG8_LDB(B0, 0, 0); PG8_LDB(B1, 0, 1); PG8_SCHED; PG8_LDA(At, 0, 0); PG8_STAGE(PG8_SA(1, 1), a1 + hstepA, voffA);
;             PG8_WAIT_V(8); PG8_WAIT_L(0); PG8_BAR; PG8_MMA(0, 0, At, B0); PG8_MMA(0, 1, At, B1); PG8_BAR; PG8_SCHED;
;             PG8_LDA(At, 0, 1); PG8_STAGE(PG8_SB(0, 0), b2, voffB); PG8_STAGE(PG8_SB(0, 1), b2 + hstepB, voffB); PG8_STAGE(PG8_SA(0, 0), a2, voffA);
;             PG8_WAIT_V(8); PG8_WAIT_L(0); PG8_BAR; PG8_MMA(1, 0, At, B0); PG8_MMA(1, 1, At, B1); PG8_BAR; PG8_SCHED;
.LBB0_486:
	ds_read_b128 v[152:155], v149
	ds_read_b128 v[156:159], v149 offset:1024
	ds_read_b128 v[160:163], v149 offset:2048
	ds_read_b128 v[164:167], v149 offset:3072
	ds_read_b128 v[168:171], v150
	ds_read_b128 v[172:175], v150 offset:1024
	ds_read_b128 v[176:179], v150 offset:2048
	ds_read_b128 v[180:183], v150 offset:3072
	s_add_u32 s42, s40, 0xfffc0080
	s_addc_u32 s43, s41, -1
	s_cmp_eq_u32 s66, 12
	s_cselect_b32 s45, s7, s43
	s_cselect_b32 s44, s13, s42
	s_cselect_b32 s43, s25, s65
	s_cselect_b32 s42, s57, s64
	v_lshl_add_u64 v[204:205], s[40:41], 0, v[138:139]
	s_add_i32 m0, s30, 0xc000
	ds_read_b128 v[184:187], v151
	ds_read_b128 v[188:191], v151 offset:1024
	ds_read_b128 v[192:195], v151 offset:2048
	ds_read_b128 v[196:199], v151 offset:3072
	ds_read_b128 v[200:203], v151 offset:4096
	ds_read_b128 v[208:211], v151 offset:5120
	ds_read_b128 v[212:215], v151 offset:6144
	ds_read_b128 v[216:219], v151 offset:7168
	global_load_lds_dwordx4 v[204:205], off
	v_lshl_add_u64 v[204:205], s[40:41], 0, v[140:141]
	s_add_i32 m0, s30, 0xe000
	s_nop 0
	global_load_lds_dwordx4 v[204:205], off
	s_waitcnt vmcnt(8)
	s_waitcnt lgkmcnt(0)
	s_barrier
	s_setprio 1
	v_mfma_f32_16x16x32_bf16 v[124:127], v[152:155], v[184:187], v[124:127]
	v_mfma_f32_16x16x32_bf16 v[120:123], v[160:163], v[184:187], v[120:123]
	v_mfma_f32_16x16x32_bf16 v[108:111], v[152:155], v[192:195], v[108:111]
	v_mfma_f32_16x16x32_bf16 v[104:107], v[160:163], v[192:195], v[104:107]
	v_mfma_f32_16x16x32_bf16 v[92:95], v[152:155], v[200:203], v[92:95]
	v_mfma_f32_16x16x32_bf16 v[88:91], v[160:163], v[200:203], v[88:91]
	v_mfma_f32_16x16x32_bf16 v[76:79], v[152:155], v[212:215], v[76:79]
	v_mfma_f32_16x16x32_bf16 v[72:75], v[160:163], v[212:215], v[72:75]
	v_mfma_f32_16x16x32_bf16 v[124:127], v[156:159], v[188:191], v[124:127]
	v_mfma_f32_16x16x32_bf16 v[120:123], v[164:167], v[188:191], v[120:123]
	v_mfma_f32_16x16x32_bf16 v[108:111], v[156:159], v[196:199], v[108:111]
	v_mfma_f32_16x16x32_bf16 v[104:107], v[164:167], v[196:199], v[104:107]
	v_mfma_f32_16x16x32_bf16 v[92:95], v[156:159], v[208:211], v[92:95]
	v_mfma_f32_16x16x32_bf16 v[88:91], v[164:167], v[208:211], v[88:91]
	v_mfma_f32_16x16x32_bf16 v[76:79], v[156:159], v[216:219], v[76:79]
	v_mfma_f32_16x16x32_bf16 v[72:75], v[164:167], v[216:219], v[72:75]
	s_setprio 0
	s_setprio 1
	v_mfma_f32_16x16x32_bf16 v[116:119], v[168:171], v[184:187], v[116:119]
	v_mfma_f32_16x16x32_bf16 v[112:115], v[176:179], v[184:187], v[112:115]
	v_mfma_f32_16x16x32_bf16 v[100:103], v[168:171], v[192:195], v[100:103]
	v_mfma_f32_16x16x32_bf16 v[96:99], v[176:179], v[192:195], v[96:99]
	v_mfma_f32_16x16x32_bf16 v[84:87], v[168:171], v[200:203], v[84:87]
	v_mfma_f32_16x16x32_bf16 v[80:83], v[176:179], v[200:203], v[80:83]
	v_mfma_f32_16x16x32_bf16 v[68:71], v[168:171], v[212:215], v[68:71]
	v_mfma_f32_16x16x32_bf16 v[64:67], v[176:179], v[212:215], v[64:67]
	v_mfma_f32_16x16x32_bf16 v[116:119], v[172:175], v[188:191], v[116:119]
	v_mfma_f32_16x16x32_bf16 v[112:115], v[180:183], v[188:191], v[112:115]
	v_mfma_f32_16x16x32_bf16 v[100:103], v[172:175], v[196:199], v[100:103]
	v_mfma_f32_16x16x32_bf16 v[96:99], v[180:183], v[196:199], v[96:99]
	v_mfma_f32_16x16x32_bf16 v[84:87], v[172:175], v[208:211], v[84:87]
	v_mfma_f32_16x16x32_bf16 v[80:83], v[180:183], v[208:211], v[80:83]
	v_mfma_f32_16x16x32_bf16 v[68:71], v[172:175], v[216:219], v[68:71]
	v_mfma_f32_16x16x32_bf16 v[64:67], v[180:183], v[216:219], v[64:67]
	s_setprio 0
	s_barrier
	s_add_i32 s67, s35, s21
	v_lshl_add_u64 v[204:205], s[42:43], 0, v[128:129]
	s_mov_b32 m0, s67
	ds_read_b128 v[184:187], v151 offset:16384
	ds_read_b128 v[188:191], v151 offset:17408
	ds_read_b128 v[192:195], v151 offset:18432
	ds_read_b128 v[196:199], v151 offset:19456
	ds_read_b128 v[200:203], v151 offset:20480
	ds_read_b128 v[208:211], v151 offset:21504
	ds_read_b128 v[212:215], v151 offset:22528
	ds_read_b128 v[216:219], v151 offset:23552
	global_load_lds_dwordx4 v[204:205], off
	s_add_i32 m0, s67, 0x2000
	s_add_u32 s68, s42, 0x40000
	v_lshl_add_u64 v[220:221], s[42:43], 0, v[130:131]
	s_addc_u32 s69, s43, 0
	s_add_i32 s67, s53, s21
	global_load_lds_dwordx4 v[220:221], off
	v_lshl_add_u64 v[222:223], s[68:69], 0, v[128:129]
	s_mov_b32 m0, s67
	v_lshl_add_u64 v[224:225], s[44:45], 0, v[130:131]
	global_load_lds_dwordx4 v[222:223], off
	v_lshl_add_u64 v[222:223], s[68:69], 0, v[130:131]
	s_add_i32 m0, s67, 0x2000
	s_nop 0
	global_load_lds_dwordx4 v[222:223], off
	v_lshl_add_u64 v[222:223], s[44:45], 0, v[128:129]
	s_mov_b32 m0, s30
	s_nop 0
	global_load_lds_dwordx4 v[222:223], off
	s_mov_b32 m0, s31
	s_nop 0
	global_load_lds_dwordx4 v[224:225], off
	s_waitcnt vmcnt(8)
	s_waitcnt lgkmcnt(0)
	s_barrier
; #define PG8_STAGE(bufoff, gbase, voff) do { _Pragma("unroll") for (int _i = 0; _i < 2; ++_i) \
;         __builtin_amdgcn_global_load_lds((const unsigned*)((const char*)(gbase) + (voff)[_i]), (LAS unsigned*)(lds + (bufoff) + ldsw + _i * 8192), 16, 0, 0); } while (0)
; #define PG8_LDA(dst, b, h) do { _Pragma("unroll") for (int m = 0; m < 4; ++m) _Pragma("unroll") for (int k = 0; k < 2; ++k) dst[m][k] = *(const LAS bf16x8*)(lds + PG8_SA(b, h) + aoff + m * 2048 + k * 1024); } while (0)
; #define PG8_LDB(dst, b, h) do { _Pragma("unroll") for (int n = 0; n < 2; ++n) _Pragma("unroll") for (int k = 0; k < 2; ++k) dst[n][k] = *(const LAS bf16x8*)(lds + PG8_SB(b, h) + boff + n * 2048 + k * 1024); } while (0)
; #define PG8_WAIT_V(n) asm volatile("s_waitcnt vmcnt(" #n ")" ::: "memory")
; #define PG8_WAIT_L(n) asm volatile("s_waitcnt lgkmcnt(" #n ")" ::: "memory")
; #define PG8_BAR __builtin_amdgcn_s_barrier()
; #define PG8_SCHED __builtin_amdgcn_sched_barrier(0)
; template <class Epi, class Sched, bool SWAPD = false>
; __device__ __forceinline__ void gemm_phase(LAS unsigned char* lds, const Gemm g, const Sched& S, const Epi& E) {
;     ...
;             PG8_WAIT_V(8); PG8_WAIT_L(0); PG8_BAR; PG8_MMA(1, 0, At, B0); PG8_MMA(1, 1, At, B1); PG8_BAR; PG8_SCHED;
;             PG8_LDB(B0, 1, 0); PG8_LDB(B1, 1, 1); PG8_SCHED; PG8_LDA(At, 1, 0); PG8_STAGE(PG8_SA(0, 1), a2 + hstepA, voffA);
;             PG8_WAIT_V(8); PG8_WAIT_L(0); PG8_BAR; PG8_MMA(0, 0, At, B0); PG8_MMA(0, 1, At, B1); PG8_BAR; PG8_SCHED;
	s_setprio 1
	v_mfma_f32_16x16x32_bf16 v[60:63], v[152:155], v[184:187], v[60:63]
	v_mfma_f32_16x16x32_bf16 v[56:59], v[160:163], v[184:187], v[56:59]
	v_mfma_f32_16x16x32_bf16 v[44:47], v[152:155], v[192:195], v[44:47]
	v_mfma_f32_16x16x32_bf16 v[40:43], v[160:163], v[192:195], v[40:43]
	v_mfma_f32_16x16x32_bf16 v[28:31], v[152:155], v[200:203], v[28:31]
	v_mfma_f32_16x16x32_bf16 v[24:27], v[160:163], v[200:203], v[24:27]
	v_mfma_f32_16x16x32_bf16 v[12:15], v[152:155], v[212:215], v[12:15]
	v_mfma_f32_16x16x32_bf16 v[8:11], v[160:163], v[212:215], v[8:11]
	v_mfma_f32_16x16x32_bf16 v[60:63], v[156:159], v[188:191], v[60:63]
	v_mfma_f32_16x16x32_bf16 v[56:59], v[164:167], v[188:191], v[56:59]
	v_mfma_f32_16x16x32_bf16 v[44:47], v[156:159], v[196:199], v[44:47]
	v_mfma_f32_16x16x32_bf16 v[40:43], v[164:167], v[196:199], v[40:43]
	v_mfma_f32_16x16x32_bf16 v[28:31], v[156:159], v[208:211], v[28:31]
	v_mfma_f32_16x16x32_bf16 v[24:27], v[164:167], v[208:211], v[24:27]
	v_mfma_f32_16x16x32_bf16 v[12:15], v[156:159], v[216:219], v[12:15]
	v_mfma_f32_16x16x32_bf16 v[8:11], v[164:167], v[216:219], v[8:11]
	s_setprio 0
	s_setprio 1
	v_mfma_f32_16x16x32_bf16 v[52:55], v[168:171], v[184:187], v[52:55]
	v_mfma_f32_16x16x32_bf16 v[48:51], v[176:179], v[184:187], v[48:51]
	v_mfma_f32_16x16x32_bf16 v[36:39], v[168:171], v[192:195], v[36:39]
	v_mfma_f32_16x16x32_bf16 v[32:35], v[176:179], v[192:195], v[32:35]
	v_mfma_f32_16x16x32_bf16 v[20:23], v[168:171], v[200:203], v[20:23]
	v_mfma_f32_16x16x32_bf16 v[16:19], v[176:179], v[200:203], v[16:19]
	v_mfma_f32_16x16x32_bf16 v[4:7], v[168:171], v[212:215], v[4:7]
	v_mfma_f32_16x16x32_bf16 v[0:3], v[176:179], v[212:215], v[0:3]
	v_mfma_f32_16x16x32_bf16 v[52:55], v[172:175], v[188:191], v[52:55]
	v_mfma_f32_16x16x32_bf16 v[48:51], v[180:183], v[188:191], v[48:51]
	v_mfma_f32_16x16x32_bf16 v[36:39], v[172:175], v[196:199], v[36:39]
	v_mfma_f32_16x16x32_bf16 v[32:35], v[180:183], v[196:199], v[32:35]
	v_mfma_f32_16x16x32_bf16 v[20:23], v[172:175], v[208:211], v[20:23]
	v_mfma_f32_16x16x32_bf16 v[16:19], v[180:183], v[208:211], v[16:19]
	v_mfma_f32_16x16x32_bf16 v[4:7], v[172:175], v[216:219], v[4:7]
	v_mfma_f32_16x16x32_bf16 v[0:3], v[180:183], v[216:219], v[0:3]
	s_setprio 0
	s_barrier
	s_add_i32 s67, 0, 0x18000
	v_add_u32_e32 v132, s67, v146
	s_add_i32 s68, 0, 0x1c000
	ds_read_b128 v[152:155], v132
	ds_read_b128 v[156:159], v132 offset:1024
	ds_read_b128 v[160:163], v132 offset:2048
	ds_read_b128 v[164:167], v132 offset:3072
	v_add_u32_e32 v132, s68, v146
	ds_read_b128 v[168:171], v132
	ds_read_b128 v[172:175], v132 offset:1024
	ds_read_b128 v[176:179], v132 offset:2048
	ds_read_b128 v[180:183], v132 offset:3072
	s_add_u32 s44, s44, 0x40000
	s_addc_u32 s45, s45, 0
	s_mov_b32 m0, s33
	v_lshl_add_u64 v[226:227], s[44:45], 0, v[128:129]
	ds_read_b128 v[184:187], v151 offset:32768
	ds_read_b128 v[188:191], v151 offset:33792
	ds_read_b128 v[192:195], v151 offset:34816
	ds_read_b128 v[196:199], v151 offset:35840
	ds_read_b128 v[200:203], v151 offset:36864
	ds_read_b128 v[208:211], v151 offset:37888
	ds_read_b128 v[212:215], v151 offset:38912
	ds_read_b128 v[216:219], v151 offset:39936
	global_load_lds_dwordx4 v[226:227], off
	v_lshl_add_u64 v[226:227], s[44:45], 0, v[130:131]
	s_mov_b32 m0, s46
	s_nop 0
	global_load_lds_dwordx4 v[226:227], off
	s_waitcnt vmcnt(8)
	s_waitcnt lgkmcnt(0)
	s_barrier
	s_setprio 1
	v_mfma_f32_16x16x32_bf16 v[124:127], v[152:155], v[184:187], v[124:127]
	v_mfma_f32_16x16x32_bf16 v[120:123], v[160:163], v[184:187], v[120:123]
	v_mfma_f32_16x16x32_bf16 v[108:111], v[152:155], v[192:195], v[108:111]
	v_mfma_f32_16x16x32_bf16 v[104:107], v[160:163], v[192:195], v[104:107]
	v_mfma_f32_16x16x32_bf16 v[92:95], v[152:155], v[200:203], v[92:95]
	v_mfma_f32_16x16x32_bf16 v[88:91], v[160:163], v[200:203], v[88:91]
	v_mfma_f32_16x16x32_bf16 v[76:79], v[152:155], v[212:215], v[76:79]
	v_mfma_f32_16x16x32_bf16 v[72:75], v[160:163], v[212:215], v[72:75]
	v_mfma_f32_16x16x32_bf16 v[124:127], v[156:159], v[188:191], v[124:127]
	v_mfma_f32_16x16x32_bf16 v[120:123], v[164:167], v[188:191], v[120:123]
	v_mfma_f32_16x16x32_bf16 v[108:111], v[156:159], v[196:199], v[108:111]
	v_mfma_f32_16x16x32_bf16 v[104:107], v[164:167], v[196:199], v[104:107]
	v_mfma_f32_16x16x32_bf16 v[92:95], v[156:159], v[208:211], v[92:95]
	v_mfma_f32_16x16x32_bf16 v[88:91], v[164:167], v[208:211], v[88:91]
	v_mfma_f32_16x16x32_bf16 v[76:79], v[156:159], v[216:219], v[76:79]
	v_mfma_f32_16x16x32_bf16 v[72:75], v[164:167], v[216:219], v[72:75]
	s_setprio 0
	s_setprio 1
	v_mfma_f32_16x16x32_bf16 v[116:119], v[168:171], v[184:187], v[116:119]
	v_mfma_f32_16x16x32_bf16 v[112:115], v[176:179], v[184:187], v[112:115]
	v_mfma_f32_16x16x32_bf16 v[100:103], v[168:171], v[192:195], v[100:103]
	v_mfma_f32_16x16x32_bf16 v[96:99], v[176:179], v[192:195], v[96:99]
	v_mfma_f32_16x16x32_bf16 v[84:87], v[168:171], v[200:203], v[84:87]
	v_mfma_f32_16x16x32_bf16 v[80:83], v[176:179], v[200:203], v[80:83]
	v_mfma_f32_16x16x32_bf16 v[68:71], v[168:171], v[212:215], v[68:71]
	v_mfma_f32_16x16x32_bf16 v[64:67], v[176:179], v[212:215], v[64:67]
	v_mfma_f32_16x16x32_bf16 v[116:119], v[172:175], v[188:191], v[116:119]
	v_mfma_f32_16x16x32_bf16 v[112:115], v[180:183], v[188:191], v[112:115]
	v_mfma_f32_16x16x32_bf16 v[100:103], v[172:175], v[196:199], v[100:103]
	v_mfma_f32_16x16x32_bf16 v[96:99], v[180:183], v[196:199], v[96:99]
	v_mfma_f32_16x16x32_bf16 v[84:87], v[172:175], v[208:211], v[84:87]
	v_mfma_f32_16x16x32_bf16 v[80:83], v[180:183], v[208:211], v[80:83]
	v_mfma_f32_16x16x32_bf16 v[68:71], v[172:175], v[216:219], v[68:71]
	v_mfma_f32_16x16x32_bf16 v[64:67], v[180:183], v[216:219], v[64:67]
	s_setprio 0
	s_barrier
; #define PG8_STAGE(bufoff, gbase, voff) do { _Pragma("unroll") for (int _i = 0; _i < 2; ++_i) \
;         __builtin_amdgcn_global_load_lds((const unsigned*)((const char*)(gbase) + (voff)[_i]), (LAS unsigned*)(lds + (bufoff) + ldsw + _i * 8192), 16, 0, 0); } while (0)
; #define PG8_LDA(dst, b, h) do { _Pragma("unroll") for (int m = 0; m < 4; ++m) _Pragma("unroll") for (int k = 0; k < 2; ++k) dst[m][k] = *(const LAS bf16x8*)(lds + PG8_SA(b, h) + aoff + m * 2048 + k * 1024); } while (0)
; #define PG8_WAIT_V(n) asm volatile("s_waitcnt vmcnt(" #n ")" ::: "memory")
; #define PG8_WAIT_L(n) asm volatile("s_waitcnt lgkmcnt(" #n ")" ::: "memory")
; #define PG8_BAR __builtin_amdgcn_s_barrier()
; #define PG8_SCHED __builtin_amdgcn_sched_barrier(0)
; template <class Epi, class Sched, bool SWAPD = false>
; __device__ __forceinline__ void gemm_phase(LAS unsigned char* lds, const Gemm g, const Sched& S, const Epi& E) {
;     ...
;             PG8_LDA(At, 1, 1); PG8_STAGE(PG8_SB(1, 0), b3, voffB); PG8_STAGE(PG8_SB(1, 1), b3 + hstepB, voffB); PG8_STAGE(PG8_SA(1, 0), a3, voffA);
;             PG8_WAIT_V(8); PG8_WAIT_L(0); PG8_BAR; PG8_MMA(1, 0, At, B0); PG8_MMA(1, 1, At, B1); PG8_BAR; PG8_SCHED;
;         }
;         if (wr == 0) PG8_BAR;
	s_add_i32 s44, s67, s21
	v_lshl_add_u64 v[204:205], v[204:205], 0, s[8:9]
	s_mov_b32 m0, s44
	ds_read_b128 v[184:187], v151 offset:49152
	ds_read_b128 v[188:191], v151 offset:50176
	ds_read_b128 v[192:195], v151 offset:51200
	ds_read_b128 v[196:199], v151 offset:52224
	ds_read_b128 v[200:203], v151 offset:53248
	ds_read_b128 v[208:211], v151 offset:54272
	ds_read_b128 v[212:215], v151 offset:55296
	ds_read_b128 v[216:219], v151 offset:56320
	global_load_lds_dwordx4 v[204:205], off
	s_add_i32 m0, s44, 0x2000
	s_add_u32 s42, s42, 0x40080
	v_lshl_add_u64 v[204:205], v[220:221], 0, s[8:9]
	s_addc_u32 s43, s43, 0
	s_add_i32 s44, s68, s21
	global_load_lds_dwordx4 v[204:205], off
	v_lshl_add_u64 v[204:205], s[42:43], 0, v[128:129]
	s_mov_b32 m0, s44
	s_nop 0
	global_load_lds_dwordx4 v[204:205], off
	v_lshl_add_u64 v[204:205], s[42:43], 0, v[130:131]
	s_add_i32 m0, s44, 0x2000
	s_nop 0
	global_load_lds_dwordx4 v[204:205], off
	v_lshl_add_u64 v[204:205], v[222:223], 0, s[8:9]
	s_mov_b32 m0, s51
	s_nop 0
	global_load_lds_dwordx4 v[204:205], off
	v_lshl_add_u64 v[204:205], v[224:225], 0, s[8:9]
	s_mov_b32 m0, s52
	s_nop 0
	global_load_lds_dwordx4 v[204:205], off
	s_waitcnt vmcnt(8)
	s_waitcnt lgkmcnt(0)
	s_barrier
	s_setprio 1
	v_mfma_f32_16x16x32_bf16 v[60:63], v[152:155], v[184:187], v[60:63]
	v_mfma_f32_16x16x32_bf16 v[56:59], v[160:163], v[184:187], v[56:59]
	v_mfma_f32_16x16x32_bf16 v[44:47], v[152:155], v[192:195], v[44:47]
	v_mfma_f32_16x16x32_bf16 v[40:43], v[160:163], v[192:195], v[40:43]
	v_mfma_f32_16x16x32_bf16 v[28:31], v[152:155], v[200:203], v[28:31]
	v_mfma_f32_16x16x32_bf16 v[24:27], v[160:163], v[200:203], v[24:27]
	v_mfma_f32_16x16x32_bf16 v[12:15], v[152:155], v[212:215], v[12:15]
	v_mfma_f32_16x16x32_bf16 v[8:11], v[160:163], v[212:215], v[8:11]
	v_mfma_f32_16x16x32_bf16 v[60:63], v[156:159], v[188:191], v[60:63]
	v_mfma_f32_16x16x32_bf16 v[56:59], v[164:167], v[188:191], v[56:59]
	v_mfma_f32_16x16x32_bf16 v[44:47], v[156:159], v[196:199], v[44:47]
	v_mfma_f32_16x16x32_bf16 v[40:43], v[164:167], v[196:199], v[40:43]
	v_mfma_f32_16x16x32_bf16 v[28:31], v[156:159], v[208:211], v[28:31]
	v_mfma_f32_16x16x32_bf16 v[24:27], v[164:167], v[208:211], v[24:27]
	v_mfma_f32_16x16x32_bf16 v[12:15], v[156:159], v[216:219], v[12:15]
	v_mfma_f32_16x16x32_bf16 v[8:11], v[164:167], v[216:219], v[8:11]
	s_setprio 0
	s_setprio 1
	v_mfma_f32_16x16x32_bf16 v[52:55], v[168:171], v[184:187], v[52:55]
	v_mfma_f32_16x16x32_bf16 v[48:51], v[176:179], v[184:187], v[48:51]
	v_mfma_f32_16x16x32_bf16 v[36:39], v[168:171], v[192:195], v[36:39]
	v_mfma_f32_16x16x32_bf16 v[32:35], v[176:179], v[192:195], v[32:35]
	v_mfma_f32_16x16x32_bf16 v[20:23], v[168:171], v[200:203], v[20:23]
	v_mfma_f32_16x16x32_bf16 v[16:19], v[176:179], v[200:203], v[16:19]
	v_mfma_f32_16x16x32_bf16 v[4:7], v[168:171], v[212:215], v[4:7]
	v_mfma_f32_16x16x32_bf16 v[0:3], v[176:179], v[212:215], v[0:3]
	v_mfma_f32_16x16x32_bf16 v[52:55], v[172:175], v[188:191], v[52:55]
	v_mfma_f32_16x16x32_bf16 v[48:51], v[180:183], v[188:191], v[48:51]
	v_mfma_f32_16x16x32_bf16 v[36:39], v[172:175], v[196:199], v[36:39]
	v_mfma_f32_16x16x32_bf16 v[32:35], v[180:183], v[196:199], v[32:35]
	v_mfma_f32_16x16x32_bf16 v[20:23], v[172:175], v[208:211], v[20:23]
	v_mfma_f32_16x16x32_bf16 v[16:19], v[180:183], v[208:211], v[16:19]
	v_mfma_f32_16x16x32_bf16 v[4:7], v[172:175], v[216:219], v[4:7]
	v_mfma_f32_16x16x32_bf16 v[0:3], v[180:183], v[216:219], v[0:3]
	s_setprio 0
	s_barrier
	s_add_i32 s66, s66, 2
	s_add_u32 s40, s40, 0x100
	s_addc_u32 s41, s41, 0
	s_add_u32 s64, s64, 0x100
	s_addc_u32 s65, s65, 0
	s_cmp_gt_u32 s66, 13
	s_cbranch_scc0 .LBB0_486
	s_and_b64 vcc, exec, s[10:11]
	s_cbranch_vccz .LBB0_489
	s_barrier

; #define PG8_STAGE(bufoff, gbase, voff) do { _Pragma("unroll") for (int _i = 0; _i < 2; ++_i) \
;         __builtin_amdgcn_global_load_lds((const unsigned*)((const char*)(gbase) + (voff)[_i]), (LAS unsigned*)(lds + (bufoff) + ldsw + _i * 8192), 16, 0, 0); } while (0)
; #define PG8_LDA(dst, b, h) do { _Pragma("unroll") for (int m = 0; m < 4; ++m) _Pragma("unroll") for (int k = 0; k < 2; ++k) dst[m][k] = *(const LAS bf16x8*)(lds + PG8_SA(b, h) + aoff + m * 2048 + k * 1024); } while (0)
; #define PG8_LDB(dst, b, h) do { _Pragma("unroll") for (int n = 0; n < 2; ++n) _Pragma("unroll") for (int k = 0; k < 2; ++k) dst[n][k] = *(const LAS bf16x8*)(lds + PG8_SB(b, h) + boff + n * 2048 + k * 1024); } while (0)
; #define PG8_WAIT_V(n) asm volatile("s_waitcnt vmcnt(" #n ")" ::: "memory")
; #define PG8_WAIT_L(n) asm volatile("s_waitcnt lgkmcnt(" #n ")" ::: "memory")
; #define PG8_BAR __builtin_amdgcn_s_barrier()
; #define PG8_SCHED __builtin_amdgcn_sched_barrier(0)
; template <class Epi, class Sched, bool SWAPD = false>
; __device__ __forceinline__ void gemm_phase(LAS unsigned char* lds, const Gemm g, const Sched& S, const Epi& E) {
;     ...
;         const bool has_next = S.next(ui + 1, nxt);
;         const char* nA = has_next ? (const char*)g.A + nxt.aoff : cA; const char* nB = has_next ? (const char*)g.Bt + nxt.boff : cB;
;         const int nt = cur.nt ? cur.nt : ntK;
;         for (int t = 0; t < nt; t += 2) {
;             const bool last = (t == nt - 2);
;             const char* a1 = cA + (size_t)(t + 1) * kstepA;
;             const char* a2 = last ? nA : cA + (size_t)(t + 2) * kstepA; const char* b2 = last ? nB : cB + (size_t)(t + 2) * kstep;
;             const char* a3 = a2 + kstepA; const char* b3 = b2 + kstep;
;             PG8_LDB(B0, 0, 0); PG8_LDB(B1, 0, 1); PG8_SCHED; PG8_LDA(At, 0, 0); PG8_STAGE(PG8_SA(1, 1), a1 + hstepA, voffA);
;             PG8_WAIT_V(8); PG8_WAIT_L(0); PG8_BAR; PG8_MMA(0, 0, At, B0); PG8_MMA(0, 1, At, B1); PG8_BAR; PG8_SCHED;
;             PG8_LDA(At, 0, 1); PG8_STAGE(PG8_SB(0, 0), b2, voffB); PG8_STAGE(PG8_SB(0, 1), b2 + hstepB, voffB); PG8_STAGE(PG8_SA(0, 0), a2, voffA);
;             PG8_WAIT_V(8); PG8_WAIT_L(0); PG8_BAR; PG8_MMA(1, 0, At, B0); PG8_MMA(1, 1, At, B1); PG8_BAR; PG8_SCHED;
.LBB0_633:
	ds_read_b128 v[152:155], v148
	ds_read_b128 v[156:159], v148 offset:1024
	ds_read_b128 v[160:163], v148 offset:2048
	ds_read_b128 v[164:167], v148 offset:3072
	ds_read_b128 v[168:171], v149
	ds_read_b128 v[172:175], v149 offset:1024
	ds_read_b128 v[176:179], v149 offset:2048
	ds_read_b128 v[180:183], v149 offset:3072
	s_add_u32 s52, s50, 0x100
	s_addc_u32 s53, s51, 0
	s_cmp_eq_u32 s81, 4
	s_cselect_b32 s57, s75, s53
	s_cselect_b32 s56, s76, s52
	s_cselect_b32 s55, s77, s80
	s_cselect_b32 s54, s78, s79
	v_lshl_add_u64 v[204:205], s[50:51], 0, v[138:139]
	s_add_i32 m0, s33, 0xc000
	ds_read_b128 v[184:187], v150
	ds_read_b128 v[188:191], v150 offset:1024
	ds_read_b128 v[192:195], v150 offset:2048
	ds_read_b128 v[196:199], v150 offset:3072
	ds_read_b128 v[200:203], v150 offset:4096
	ds_read_b128 v[208:211], v150 offset:5120
	ds_read_b128 v[212:215], v150 offset:6144
	ds_read_b128 v[216:219], v150 offset:7168
	global_load_lds_dwordx4 v[204:205], off
	v_lshl_add_u64 v[204:205], s[50:51], 0, v[140:141]
	s_add_i32 m0, s33, 0xe000
	s_nop 0
	global_load_lds_dwordx4 v[204:205], off
	s_waitcnt vmcnt(8)
	s_waitcnt lgkmcnt(0)
	s_barrier
	s_setprio 1
	v_mfma_f32_16x16x32_bf16 v[124:127], v[152:155], v[184:187], v[124:127]
	v_mfma_f32_16x16x32_bf16 v[120:123], v[160:163], v[184:187], v[120:123]
	v_mfma_f32_16x16x32_bf16 v[116:119], v[152:155], v[192:195], v[116:119]
	v_mfma_f32_16x16x32_bf16 v[112:115], v[160:163], v[192:195], v[112:115]
	v_mfma_f32_16x16x32_bf16 v[104:107], v[152:155], v[200:203], v[104:107]
	v_mfma_f32_16x16x32_bf16 v[96:99], v[160:163], v[200:203], v[96:99]
	v_mfma_f32_16x16x32_bf16 v[88:91], v[152:155], v[212:215], v[88:91]
	v_mfma_f32_16x16x32_bf16 v[80:83], v[160:163], v[212:215], v[80:83]
	v_mfma_f32_16x16x32_bf16 v[124:127], v[156:159], v[188:191], v[124:127]
	v_mfma_f32_16x16x32_bf16 v[120:123], v[164:167], v[188:191], v[120:123]
	v_mfma_f32_16x16x32_bf16 v[116:119], v[156:159], v[196:199], v[116:119]
	v_mfma_f32_16x16x32_bf16 v[112:115], v[164:167], v[196:199], v[112:115]
	v_mfma_f32_16x16x32_bf16 v[104:107], v[156:159], v[208:211], v[104:107]
	v_mfma_f32_16x16x32_bf16 v[96:99], v[164:167], v[208:211], v[96:99]
	v_mfma_f32_16x16x32_bf16 v[88:91], v[156:159], v[216:219], v[88:91]
	v_mfma_f32_16x16x32_bf16 v[80:83], v[164:167], v[216:219], v[80:83]
	s_setprio 0
	s_setprio 1
	v_mfma_f32_16x16x32_bf16 v[108:111], v[168:171], v[184:187], v[108:111]
	v_mfma_f32_16x16x32_bf16 v[100:103], v[176:179], v[184:187], v[100:103]
	v_mfma_f32_16x16x32_bf16 v[92:95], v[168:171], v[192:195], v[92:95]
	v_mfma_f32_16x16x32_bf16 v[84:87], v[176:179], v[192:195], v[84:87]
	v_mfma_f32_16x16x32_bf16 v[76:79], v[168:171], v[200:203], v[76:79]
	v_mfma_f32_16x16x32_bf16 v[72:75], v[176:179], v[200:203], v[72:75]
	v_mfma_f32_16x16x32_bf16 v[68:71], v[168:171], v[212:215], v[68:71]
	v_mfma_f32_16x16x32_bf16 v[64:67], v[176:179], v[212:215], v[64:67]
	v_mfma_f32_16x16x32_bf16 v[108:111], v[172:175], v[188:191], v[108:111]
	v_mfma_f32_16x16x32_bf16 v[100:103], v[180:183], v[188:191], v[100:103]
	v_mfma_f32_16x16x32_bf16 v[92:95], v[172:175], v[196:199], v[92:95]
	v_mfma_f32_16x16x32_bf16 v[84:87], v[180:183], v[196:199], v[84:87]
	v_mfma_f32_16x16x32_bf16 v[76:79], v[172:175], v[208:211], v[76:79]
	v_mfma_f32_16x16x32_bf16 v[72:75], v[180:183], v[208:211], v[72:75]
	v_mfma_f32_16x16x32_bf16 v[68:71], v[172:175], v[216:219], v[68:71]
	v_mfma_f32_16x16x32_bf16 v[64:67], v[180:183], v[216:219], v[64:67]
	s_setprio 0
	s_barrier
	s_add_i32 s50, s64, s21
	v_lshl_add_u64 v[204:205], s[54:55], 0, v[132:133]
	s_mov_b32 m0, s50
	ds_read_b128 v[184:187], v150 offset:16384
	ds_read_b128 v[188:191], v150 offset:17408
	ds_read_b128 v[192:195], v150 offset:18432
	ds_read_b128 v[196:199], v150 offset:19456
	ds_read_b128 v[200:203], v150 offset:20480
	ds_read_b128 v[208:211], v150 offset:21504
	ds_read_b128 v[212:215], v150 offset:22528
	ds_read_b128 v[216:219], v150 offset:23552
	global_load_lds_dwordx4 v[204:205], off
	s_add_i32 m0, s50, 0x2000
	s_add_u32 s50, s54, 0x20000
	v_lshl_add_u64 v[220:221], s[54:55], 0, v[128:129]
	s_addc_u32 s51, s55, 0
	s_add_i32 s82, s65, s21
	global_load_lds_dwordx4 v[220:221], off
	v_lshl_add_u64 v[222:223], s[50:51], 0, v[132:133]
	s_mov_b32 m0, s82
	v_lshl_add_u64 v[224:225], s[56:57], 0, v[130:131]
	global_load_lds_dwordx4 v[222:223], off
	v_lshl_add_u64 v[222:223], s[50:51], 0, v[128:129]
	s_add_i32 m0, s82, 0x2000
	s_nop 0
	global_load_lds_dwordx4 v[222:223], off
	v_lshl_add_u64 v[222:223], s[56:57], 0, v[134:135]
	s_mov_b32 m0, s33
	s_nop 0
	global_load_lds_dwordx4 v[222:223], off
	s_mov_b32 m0, s34
	s_nop 0
	global_load_lds_dwordx4 v[224:225], off
	s_waitcnt vmcnt(8)
	s_waitcnt lgkmcnt(0)
	s_barrier
; #define PG8_STAGE(bufoff, gbase, voff) do { _Pragma("unroll") for (int _i = 0; _i < 2; ++_i) \
;         __builtin_amdgcn_global_load_lds((const unsigned*)((const char*)(gbase) + (voff)[_i]), (LAS unsigned*)(lds + (bufoff) + ldsw + _i * 8192), 16, 0, 0); } while (0)
; #define PG8_LDA(dst, b, h) do { _Pragma("unroll") for (int m = 0; m < 4; ++m) _Pragma("unroll") for (int k = 0; k < 2; ++k) dst[m][k] = *(const LAS bf16x8*)(lds + PG8_SA(b, h) + aoff + m * 2048 + k * 1024); } while (0)
; #define PG8_LDB(dst, b, h) do { _Pragma("unroll") for (int n = 0; n < 2; ++n) _Pragma("unroll") for (int k = 0; k < 2; ++k) dst[n][k] = *(const LAS bf16x8*)(lds + PG8_SB(b, h) + boff + n * 2048 + k * 1024); } while (0)
; #define PG8_WAIT_V(n) asm volatile("s_waitcnt vmcnt(" #n ")" ::: "memory")
; #define PG8_WAIT_L(n) asm volatile("s_waitcnt lgkmcnt(" #n ")" ::: "memory")
; #define PG8_BAR __builtin_amdgcn_s_barrier()
; #define PG8_SCHED __builtin_amdgcn_sched_barrier(0)
; template <class Epi, class Sched, bool SWAPD = false>
; __device__ __forceinline__ void gemm_phase(LAS unsigned char* lds, const Gemm g, const Sched& S, const Epi& E) {
;     ...
;             PG8_WAIT_V(8); PG8_WAIT_L(0); PG8_BAR; PG8_MMA(1, 0, At, B0); PG8_MMA(1, 1, At, B1); PG8_BAR; PG8_SCHED;
;             PG8_LDB(B0, 1, 0); PG8_LDB(B1, 1, 1); PG8_SCHED; PG8_LDA(At, 1, 0); PG8_STAGE(PG8_SA(0, 1), a2 + hstepA, voffA);
;             PG8_WAIT_V(8); PG8_WAIT_L(0); PG8_BAR; PG8_MMA(0, 0, At, B0); PG8_MMA(0, 1, At, B1); PG8_BAR; PG8_SCHED;
	s_setprio 1
	v_mfma_f32_16x16x32_bf16 v[60:63], v[152:155], v[184:187], v[60:63]
	v_mfma_f32_16x16x32_bf16 v[56:59], v[160:163], v[184:187], v[56:59]
	v_mfma_f32_16x16x32_bf16 v[52:55], v[152:155], v[192:195], v[52:55]
	v_mfma_f32_16x16x32_bf16 v[48:51], v[160:163], v[192:195], v[48:51]
	v_mfma_f32_16x16x32_bf16 v[40:43], v[152:155], v[200:203], v[40:43]
	v_mfma_f32_16x16x32_bf16 v[32:35], v[160:163], v[200:203], v[32:35]
	v_mfma_f32_16x16x32_bf16 v[24:27], v[152:155], v[212:215], v[24:27]
	v_mfma_f32_16x16x32_bf16 v[16:19], v[160:163], v[212:215], v[16:19]
	v_mfma_f32_16x16x32_bf16 v[60:63], v[156:159], v[188:191], v[60:63]
	v_mfma_f32_16x16x32_bf16 v[56:59], v[164:167], v[188:191], v[56:59]
	v_mfma_f32_16x16x32_bf16 v[52:55], v[156:159], v[196:199], v[52:55]
	v_mfma_f32_16x16x32_bf16 v[48:51], v[164:167], v[196:199], v[48:51]
	v_mfma_f32_16x16x32_bf16 v[40:43], v[156:159], v[208:211], v[40:43]
	v_mfma_f32_16x16x32_bf16 v[32:35], v[164:167], v[208:211], v[32:35]
	v_mfma_f32_16x16x32_bf16 v[24:27], v[156:159], v[216:219], v[24:27]
	v_mfma_f32_16x16x32_bf16 v[16:19], v[164:167], v[216:219], v[16:19]
	s_setprio 0
	s_setprio 1
	v_mfma_f32_16x16x32_bf16 v[44:47], v[168:171], v[184:187], v[44:47]
	v_mfma_f32_16x16x32_bf16 v[36:39], v[176:179], v[184:187], v[36:39]
	v_mfma_f32_16x16x32_bf16 v[28:31], v[168:171], v[192:195], v[28:31]
	v_mfma_f32_16x16x32_bf16 v[20:23], v[176:179], v[192:195], v[20:23]
	v_mfma_f32_16x16x32_bf16 v[12:15], v[168:171], v[200:203], v[12:15]
	v_mfma_f32_16x16x32_bf16 v[8:11], v[176:179], v[200:203], v[8:11]
	v_mfma_f32_16x16x32_bf16 v[4:7], v[168:171], v[212:215], v[4:7]
	v_mfma_f32_16x16x32_bf16 v[0:3], v[176:179], v[212:215], v[0:3]
	v_mfma_f32_16x16x32_bf16 v[44:47], v[172:175], v[188:191], v[44:47]
	v_mfma_f32_16x16x32_bf16 v[36:39], v[180:183], v[188:191], v[36:39]
	v_mfma_f32_16x16x32_bf16 v[28:31], v[172:175], v[196:199], v[28:31]
	v_mfma_f32_16x16x32_bf16 v[20:23], v[180:183], v[196:199], v[20:23]
	v_mfma_f32_16x16x32_bf16 v[12:15], v[172:175], v[208:211], v[12:15]
	v_mfma_f32_16x16x32_bf16 v[8:11], v[180:183], v[208:211], v[8:11]
	v_mfma_f32_16x16x32_bf16 v[4:7], v[172:175], v[216:219], v[4:7]
	v_mfma_f32_16x16x32_bf16 v[0:3], v[180:183], v[216:219], v[0:3]
	s_setprio 0
	s_barrier
	s_add_i32 s82, 0, 0x18000
	v_add_u32_e32 v151, s82, v147
	s_add_i32 s83, 0, 0x1c000
	ds_read_b128 v[152:155], v151
	ds_read_b128 v[156:159], v151 offset:1024
	ds_read_b128 v[160:163], v151 offset:2048
	ds_read_b128 v[164:167], v151 offset:3072
	v_add_u32_e32 v151, s83, v147
	ds_read_b128 v[168:171], v151
	ds_read_b128 v[172:175], v151 offset:1024
	ds_read_b128 v[176:179], v151 offset:2048
	ds_read_b128 v[180:183], v151 offset:3072
	s_add_u32 s50, s56, 0x30000
	s_addc_u32 s51, s57, 0
	s_mov_b32 m0, s35
	v_lshl_add_u64 v[226:227], s[50:51], 0, v[134:135]
	ds_read_b128 v[184:187], v150 offset:32768
	ds_read_b128 v[188:191], v150 offset:33792
	ds_read_b128 v[192:195], v150 offset:34816
	ds_read_b128 v[196:199], v150 offset:35840
	ds_read_b128 v[200:203], v150 offset:36864
	ds_read_b128 v[208:211], v150 offset:37888
	ds_read_b128 v[212:215], v150 offset:38912
	ds_read_b128 v[216:219], v150 offset:39936
	global_load_lds_dwordx4 v[226:227], off
	v_lshl_add_u64 v[226:227], s[50:51], 0, v[130:131]
	s_mov_b32 m0, s58
	s_nop 0
	global_load_lds_dwordx4 v[226:227], off
	s_waitcnt vmcnt(8)
	s_waitcnt lgkmcnt(0)
	s_barrier
	s_setprio 1
	v_mfma_f32_16x16x32_bf16 v[124:127], v[152:155], v[184:187], v[124:127]
	v_mfma_f32_16x16x32_bf16 v[120:123], v[160:163], v[184:187], v[120:123]
	v_mfma_f32_16x16x32_bf16 v[116:119], v[152:155], v[192:195], v[116:119]
	v_mfma_f32_16x16x32_bf16 v[112:115], v[160:163], v[192:195], v[112:115]
	v_mfma_f32_16x16x32_bf16 v[104:107], v[152:155], v[200:203], v[104:107]
	v_mfma_f32_16x16x32_bf16 v[96:99], v[160:163], v[200:203], v[96:99]
	v_mfma_f32_16x16x32_bf16 v[88:91], v[152:155], v[212:215], v[88:91]
	v_mfma_f32_16x16x32_bf16 v[80:83], v[160:163], v[212:215], v[80:83]
	v_mfma_f32_16x16x32_bf16 v[124:127], v[156:159], v[188:191], v[124:127]
	v_mfma_f32_16x16x32_bf16 v[120:123], v[164:167], v[188:191], v[120:123]
	v_mfma_f32_16x16x32_bf16 v[116:119], v[156:159], v[196:199], v[116:119]
	v_mfma_f32_16x16x32_bf16 v[112:115], v[164:167], v[196:199], v[112:115]
	v_mfma_f32_16x16x32_bf16 v[104:107], v[156:159], v[208:211], v[104:107]
	v_mfma_f32_16x16x32_bf16 v[96:99], v[164:167], v[208:211], v[96:99]
	v_mfma_f32_16x16x32_bf16 v[88:91], v[156:159], v[216:219], v[88:91]
	v_mfma_f32_16x16x32_bf16 v[80:83], v[164:167], v[216:219], v[80:83]
	s_setprio 0
	s_setprio 1
	v_mfma_f32_16x16x32_bf16 v[108:111], v[168:171], v[184:187], v[108:111]
	v_mfma_f32_16x16x32_bf16 v[100:103], v[176:179], v[184:187], v[100:103]
	v_mfma_f32_16x16x32_bf16 v[92:95], v[168:171], v[192:195], v[92:95]
	v_mfma_f32_16x16x32_bf16 v[84:87], v[176:179], v[192:195], v[84:87]
	v_mfma_f32_16x16x32_bf16 v[76:79], v[168:171], v[200:203], v[76:79]
	v_mfma_f32_16x16x32_bf16 v[72:75], v[176:179], v[200:203], v[72:75]
	v_mfma_f32_16x16x32_bf16 v[68:71], v[168:171], v[212:215], v[68:71]
	v_mfma_f32_16x16x32_bf16 v[64:67], v[176:179], v[212:215], v[64:67]
	v_mfma_f32_16x16x32_bf16 v[108:111], v[172:175], v[188:191], v[108:111]
	v_mfma_f32_16x16x32_bf16 v[100:103], v[180:183], v[188:191], v[100:103]
	v_mfma_f32_16x16x32_bf16 v[92:95], v[172:175], v[196:199], v[92:95]
	v_mfma_f32_16x16x32_bf16 v[84:87], v[180:183], v[196:199], v[84:87]
	v_mfma_f32_16x16x32_bf16 v[76:79], v[172:175], v[208:211], v[76:79]
	v_mfma_f32_16x16x32_bf16 v[72:75], v[180:183], v[208:211], v[72:75]
	v_mfma_f32_16x16x32_bf16 v[68:71], v[172:175], v[216:219], v[68:71]
	v_mfma_f32_16x16x32_bf16 v[64:67], v[180:183], v[216:219], v[64:67]
	s_setprio 0
	s_barrier
; #define PG8_STAGE(bufoff, gbase, voff) do { _Pragma("unroll") for (int _i = 0; _i < 2; ++_i) \
;         __builtin_amdgcn_global_load_lds((const unsigned*)((const char*)(gbase) + (voff)[_i]), (LAS unsigned*)(lds + (bufoff) + ldsw + _i * 8192), 16, 0, 0); } while (0)
; #define PG8_LDA(dst, b, h) do { _Pragma("unroll") for (int m = 0; m < 4; ++m) _Pragma("unroll") for (int k = 0; k < 2; ++k) dst[m][k] = *(const LAS bf16x8*)(lds + PG8_SA(b, h) + aoff + m * 2048 + k * 1024); } while (0)
; #define PG8_WAIT_V(n) asm volatile("s_waitcnt vmcnt(" #n ")" ::: "memory")
; #define PG8_WAIT_L(n) asm volatile("s_waitcnt lgkmcnt(" #n ")" ::: "memory")
; #define PG8_BAR __builtin_amdgcn_s_barrier()
; #define PG8_SCHED __builtin_amdgcn_sched_barrier(0)
; template <class Epi, class Sched, bool SWAPD = false>
; __device__ __forceinline__ void gemm_phase(LAS unsigned char* lds, const Gemm g, const Sched& S, const Epi& E) {
;     ...
;             PG8_LDA(At, 1, 1); PG8_STAGE(PG8_SB(1, 0), b3, voffB); PG8_STAGE(PG8_SB(1, 1), b3 + hstepB, voffB); PG8_STAGE(PG8_SA(1, 0), a3, voffA);
;             PG8_WAIT_V(8); PG8_WAIT_L(0); PG8_BAR; PG8_MMA(1, 0, At, B0); PG8_MMA(1, 1, At, B1); PG8_BAR; PG8_SCHED;
;         }
;         if (wr == 0) PG8_BAR;
	s_add_i32 s50, s82, s21
	v_lshl_add_u64 v[204:205], v[204:205], 0, s[10:11]
	s_mov_b32 m0, s50
	ds_read_b128 v[184:187], v150 offset:49152
	ds_read_b128 v[188:191], v150 offset:50176
	ds_read_b128 v[192:195], v150 offset:51200
	ds_read_b128 v[196:199], v150 offset:52224
	ds_read_b128 v[200:203], v150 offset:53248
	ds_read_b128 v[208:211], v150 offset:54272
	ds_read_b128 v[212:215], v150 offset:55296
	ds_read_b128 v[216:219], v150 offset:56320
	global_load_lds_dwordx4 v[204:205], off
	s_add_i32 m0, s50, 0x2000
	s_add_u32 s50, s54, 0x20080
	v_lshl_add_u64 v[204:205], v[220:221], 0, s[10:11]
	s_addc_u32 s51, s55, 0
	s_add_i32 s54, s83, s21
	global_load_lds_dwordx4 v[204:205], off
	v_lshl_add_u64 v[204:205], s[50:51], 0, v[132:133]
	s_mov_b32 m0, s54
	s_nop 0
	global_load_lds_dwordx4 v[204:205], off
	v_lshl_add_u64 v[204:205], s[50:51], 0, v[128:129]
	s_add_i32 m0, s54, 0x2000
	s_nop 0
	global_load_lds_dwordx4 v[204:205], off
	v_lshl_add_u64 v[204:205], v[222:223], 0, s[10:11]
	s_mov_b32 m0, s60
	s_nop 0
	global_load_lds_dwordx4 v[204:205], off
	v_lshl_add_u64 v[204:205], v[224:225], 0, s[10:11]
	s_mov_b32 m0, s61
	s_nop 0
	global_load_lds_dwordx4 v[204:205], off
	s_waitcnt vmcnt(8)
	s_waitcnt lgkmcnt(0)
	s_barrier
	s_setprio 1
	v_mfma_f32_16x16x32_bf16 v[60:63], v[152:155], v[184:187], v[60:63]
	v_mfma_f32_16x16x32_bf16 v[56:59], v[160:163], v[184:187], v[56:59]
	v_mfma_f32_16x16x32_bf16 v[52:55], v[152:155], v[192:195], v[52:55]
	v_mfma_f32_16x16x32_bf16 v[48:51], v[160:163], v[192:195], v[48:51]
	v_mfma_f32_16x16x32_bf16 v[40:43], v[152:155], v[200:203], v[40:43]
	v_mfma_f32_16x16x32_bf16 v[32:35], v[160:163], v[200:203], v[32:35]
	v_mfma_f32_16x16x32_bf16 v[24:27], v[152:155], v[212:215], v[24:27]
	v_mfma_f32_16x16x32_bf16 v[16:19], v[160:163], v[212:215], v[16:19]
	v_mfma_f32_16x16x32_bf16 v[60:63], v[156:159], v[188:191], v[60:63]
	v_mfma_f32_16x16x32_bf16 v[56:59], v[164:167], v[188:191], v[56:59]
	v_mfma_f32_16x16x32_bf16 v[52:55], v[156:159], v[196:199], v[52:55]
	v_mfma_f32_16x16x32_bf16 v[48:51], v[164:167], v[196:199], v[48:51]
	v_mfma_f32_16x16x32_bf16 v[40:43], v[156:159], v[208:211], v[40:43]
	v_mfma_f32_16x16x32_bf16 v[32:35], v[164:167], v[208:211], v[32:35]
	v_mfma_f32_16x16x32_bf16 v[24:27], v[156:159], v[216:219], v[24:27]
	v_mfma_f32_16x16x32_bf16 v[16:19], v[164:167], v[216:219], v[16:19]
	s_setprio 0
	s_setprio 1
	v_mfma_f32_16x16x32_bf16 v[44:47], v[168:171], v[184:187], v[44:47]
	v_mfma_f32_16x16x32_bf16 v[36:39], v[176:179], v[184:187], v[36:39]
	v_mfma_f32_16x16x32_bf16 v[28:31], v[168:171], v[192:195], v[28:31]
	v_mfma_f32_16x16x32_bf16 v[20:23], v[176:179], v[192:195], v[20:23]
	v_mfma_f32_16x16x32_bf16 v[12:15], v[168:171], v[200:203], v[12:15]
	v_mfma_f32_16x16x32_bf16 v[8:11], v[176:179], v[200:203], v[8:11]
	v_mfma_f32_16x16x32_bf16 v[4:7], v[168:171], v[212:215], v[4:7]
	v_mfma_f32_16x16x32_bf16 v[0:3], v[176:179], v[212:215], v[0:3]
	v_mfma_f32_16x16x32_bf16 v[44:47], v[172:175], v[188:191], v[44:47]
	v_mfma_f32_16x16x32_bf16 v[36:39], v[180:183], v[188:191], v[36:39]
	v_mfma_f32_16x16x32_bf16 v[28:31], v[172:175], v[196:199], v[28:31]
	v_mfma_f32_16x16x32_bf16 v[20:23], v[180:183], v[196:199], v[20:23]
	v_mfma_f32_16x16x32_bf16 v[12:15], v[172:175], v[208:211], v[12:15]
	v_mfma_f32_16x16x32_bf16 v[8:11], v[180:183], v[208:211], v[8:11]
	v_mfma_f32_16x16x32_bf16 v[4:7], v[172:175], v[216:219], v[4:7]
	v_mfma_f32_16x16x32_bf16 v[0:3], v[180:183], v[216:219], v[0:3]
	s_setprio 0
	s_barrier
	s_add_i32 s81, s81, 2
	s_add_u32 s79, s79, 0x100
	s_addc_u32 s80, s80, 0
	s_cmp_gt_u32 s81, 5
	s_mov_b64 s[50:51], s[52:53]
	s_cbranch_scc0 .LBB0_633
	s_and_b64 vcc, exec, s[12:13]
	s_cbranch_vccz .LBB0_636
	s_barrier

; #define PG8_STAGE(bufoff, gbase, voff) do { _Pragma("unroll") for (int _i = 0; _i < 2; ++_i) \
;         __builtin_amdgcn_global_load_lds((const unsigned*)((const char*)(gbase) + (voff)[_i]), (LAS unsigned*)(lds + (bufoff) + ldsw + _i * 8192), 16, 0, 0); } while (0)
; #define PG8_LDA(dst, b, h) do { _Pragma("unroll") for (int m = 0; m < 4; ++m) _Pragma("unroll") for (int k = 0; k < 2; ++k) dst[m][k] = *(const LAS bf16x8*)(lds + PG8_SA(b, h) + aoff + m * 2048 + k * 1024); } while (0)
; #define PG8_LDB(dst, b, h) do { _Pragma("unroll") for (int n = 0; n < 2; ++n) _Pragma("unroll") for (int k = 0; k < 2; ++k) dst[n][k] = *(const LAS bf16x8*)(lds + PG8_SB(b, h) + boff + n * 2048 + k * 1024); } while (0)
; #define PG8_WAIT_V(n) asm volatile("s_waitcnt vmcnt(" #n ")" ::: "memory")
; #define PG8_WAIT_L(n) asm volatile("s_waitcnt lgkmcnt(" #n ")" ::: "memory")
; #define PG8_BAR __builtin_amdgcn_s_barrier()
; #define PG8_SCHED __builtin_amdgcn_sched_barrier(0)
; template <class Epi, class Sched, bool SWAPD = false>
; __device__ __forceinline__ void gemm_phase(LAS unsigned char* lds, const Gemm g, const Sched& S, const Epi& E) {
;     ...
;         const bool has_next = S.next(ui + 1, nxt);
;         const char* nA = has_next ? (const char*)g.A + nxt.aoff : cA; const char* nB = has_next ? (const char*)g.Bt + nxt.boff : cB;
;         const int nt = cur.nt ? cur.nt : ntK;
;         for (int t = 0; t < nt; t += 2) {
;             const bool last = (t == nt - 2);
;             const char* a1 = cA + (size_t)(t + 1) * kstepA;
;             const char* a2 = last ? nA : cA + (size_t)(t + 2) * kstepA; const char* b2 = last ? nB : cB + (size_t)(t + 2) * kstep;
;             const char* a3 = a2 + kstepA; const char* b3 = b2 + kstep;
;             PG8_LDB(B0, 0, 0); PG8_LDB(B1, 0, 1); PG8_SCHED; PG8_LDA(At, 0, 0); PG8_STAGE(PG8_SA(1, 1), a1 + hstepA, voffA);
;             PG8_WAIT_V(8); PG8_WAIT_L(0); PG8_BAR; PG8_MMA(0, 0, At, B0); PG8_MMA(0, 1, At, B1); PG8_BAR; PG8_SCHED;
;             PG8_LDA(At, 0, 1); PG8_STAGE(PG8_SB(0, 0), b2, voffB); PG8_STAGE(PG8_SB(0, 1), b2 + hstepB, voffB); PG8_STAGE(PG8_SA(0, 0), a2, voffA);
;             PG8_WAIT_V(8); PG8_WAIT_L(0); PG8_BAR; PG8_MMA(1, 0, At, B0); PG8_MMA(1, 1, At, B1); PG8_BAR; PG8_SCHED;
.LBB0_766:
	ds_read_b128 v[150:153], v146
	ds_read_b128 v[154:157], v146 offset:1024
	ds_read_b128 v[158:161], v146 offset:2048
	ds_read_b128 v[162:165], v146 offset:3072
	ds_read_b128 v[166:169], v147
	ds_read_b128 v[170:173], v147 offset:1024
	ds_read_b128 v[174:177], v147 offset:2048
	ds_read_b128 v[178:181], v147 offset:3072
	s_add_u32 s42, s40, 0x100
	s_addc_u32 s43, s41, 0
	s_cmp_eq_u32 s67, 8
	s_cselect_b32 s47, s61, s43
	s_cselect_b32 s46, s62, s42
	s_cselect_b32 s45, s63, s66
	s_cselect_b32 s44, s64, s65
	v_lshl_add_u64 v[142:143], s[40:41], 0, v[134:135]
	s_add_i32 m0, s33, 0xc000
	ds_read_b128 v[182:185], v148
	ds_read_b128 v[186:189], v148 offset:1024
	ds_read_b128 v[190:193], v148 offset:2048
	ds_read_b128 v[194:197], v148 offset:3072
	ds_read_b128 v[198:201], v148 offset:4096
	ds_read_b128 v[202:205], v148 offset:5120
	ds_read_b128 v[208:211], v148 offset:6144
	ds_read_b128 v[212:215], v148 offset:7168
	global_load_lds_dwordx4 v[142:143], off
	v_lshl_add_u64 v[142:143], s[40:41], 0, v[136:137]
	s_add_i32 m0, s33, 0xe000
	s_nop 0
	global_load_lds_dwordx4 v[142:143], off
	s_waitcnt vmcnt(8)
	s_waitcnt lgkmcnt(0)
	s_barrier
	s_setprio 1
	v_mfma_f32_16x16x32_bf16 v[124:127], v[150:153], v[182:185], v[124:127]
	v_mfma_f32_16x16x32_bf16 v[120:123], v[158:161], v[182:185], v[120:123]
	v_mfma_f32_16x16x32_bf16 v[108:111], v[150:153], v[190:193], v[108:111]
	v_mfma_f32_16x16x32_bf16 v[104:107], v[158:161], v[190:193], v[104:107]
	v_mfma_f32_16x16x32_bf16 v[92:95], v[150:153], v[198:201], v[92:95]
	v_mfma_f32_16x16x32_bf16 v[88:91], v[158:161], v[198:201], v[88:91]
	v_mfma_f32_16x16x32_bf16 v[76:79], v[150:153], v[208:211], v[76:79]
	v_mfma_f32_16x16x32_bf16 v[72:75], v[158:161], v[208:211], v[72:75]
	v_mfma_f32_16x16x32_bf16 v[124:127], v[154:157], v[186:189], v[124:127]
	v_mfma_f32_16x16x32_bf16 v[120:123], v[162:165], v[186:189], v[120:123]
	v_mfma_f32_16x16x32_bf16 v[108:111], v[154:157], v[194:197], v[108:111]
	v_mfma_f32_16x16x32_bf16 v[104:107], v[162:165], v[194:197], v[104:107]
	v_mfma_f32_16x16x32_bf16 v[92:95], v[154:157], v[202:205], v[92:95]
	v_mfma_f32_16x16x32_bf16 v[88:91], v[162:165], v[202:205], v[88:91]
	v_mfma_f32_16x16x32_bf16 v[76:79], v[154:157], v[212:215], v[76:79]
	v_mfma_f32_16x16x32_bf16 v[72:75], v[162:165], v[212:215], v[72:75]
	s_setprio 0
	s_setprio 1
	v_mfma_f32_16x16x32_bf16 v[116:119], v[166:169], v[182:185], v[116:119]
	v_mfma_f32_16x16x32_bf16 v[112:115], v[174:177], v[182:185], v[112:115]
	v_mfma_f32_16x16x32_bf16 v[100:103], v[166:169], v[190:193], v[100:103]
	v_mfma_f32_16x16x32_bf16 v[96:99], v[174:177], v[190:193], v[96:99]
	v_mfma_f32_16x16x32_bf16 v[84:87], v[166:169], v[198:201], v[84:87]
	v_mfma_f32_16x16x32_bf16 v[80:83], v[174:177], v[198:201], v[80:83]
	v_mfma_f32_16x16x32_bf16 v[68:71], v[166:169], v[208:211], v[68:71]
	v_mfma_f32_16x16x32_bf16 v[64:67], v[174:177], v[208:211], v[64:67]
	v_mfma_f32_16x16x32_bf16 v[116:119], v[170:173], v[186:189], v[116:119]
	v_mfma_f32_16x16x32_bf16 v[112:115], v[178:181], v[186:189], v[112:115]
	v_mfma_f32_16x16x32_bf16 v[100:103], v[170:173], v[194:197], v[100:103]
	v_mfma_f32_16x16x32_bf16 v[96:99], v[178:181], v[194:197], v[96:99]
	v_mfma_f32_16x16x32_bf16 v[84:87], v[170:173], v[202:205], v[84:87]
	v_mfma_f32_16x16x32_bf16 v[80:83], v[178:181], v[202:205], v[80:83]
	v_mfma_f32_16x16x32_bf16 v[68:71], v[170:173], v[212:215], v[68:71]
	v_mfma_f32_16x16x32_bf16 v[64:67], v[178:181], v[212:215], v[64:67]
	s_setprio 0
	s_barrier
	s_add_i32 s40, s57, s21
	v_lshl_add_u64 v[142:143], s[44:45], 0, v[130:131]
	s_mov_b32 m0, s40
	ds_read_b128 v[182:185], v148 offset:16384
	ds_read_b128 v[186:189], v148 offset:17408
	ds_read_b128 v[190:193], v148 offset:18432
	ds_read_b128 v[194:197], v148 offset:19456
	ds_read_b128 v[198:201], v148 offset:20480
	ds_read_b128 v[202:205], v148 offset:21504
	ds_read_b128 v[208:211], v148 offset:22528
	ds_read_b128 v[212:215], v148 offset:23552
	global_load_lds_dwordx4 v[142:143], off
	s_add_i32 m0, s40, 0x2000
	s_add_u32 s40, s44, 0x30000
	v_lshl_add_u64 v[216:217], s[44:45], 0, v[128:129]
	s_addc_u32 s41, s45, 0
	s_add_i32 s68, s58, s21
	global_load_lds_dwordx4 v[216:217], off
	v_lshl_add_u64 v[218:219], s[40:41], 0, v[130:131]
	s_mov_b32 m0, s68
	v_lshl_add_u64 v[220:221], s[46:47], 0, v[128:129]
	global_load_lds_dwordx4 v[218:219], off
	v_lshl_add_u64 v[218:219], s[40:41], 0, v[128:129]
	s_add_i32 m0, s68, 0x2000
	s_nop 0
	global_load_lds_dwordx4 v[218:219], off
	v_lshl_add_u64 v[218:219], s[46:47], 0, v[130:131]
	s_mov_b32 m0, s33
	s_nop 0
	global_load_lds_dwordx4 v[218:219], off
	s_mov_b32 m0, s50
	s_nop 0
	global_load_lds_dwordx4 v[220:221], off
	s_waitcnt vmcnt(8)
	s_waitcnt lgkmcnt(0)
	s_barrier
; #define PG8_STAGE(bufoff, gbase, voff) do { _Pragma("unroll") for (int _i = 0; _i < 2; ++_i) \
;         __builtin_amdgcn_global_load_lds((const unsigned*)((const char*)(gbase) + (voff)[_i]), (LAS unsigned*)(lds + (bufoff) + ldsw + _i * 8192), 16, 0, 0); } while (0)
; #define PG8_LDA(dst, b, h) do { _Pragma("unroll") for (int m = 0; m < 4; ++m) _Pragma("unroll") for (int k = 0; k < 2; ++k) dst[m][k] = *(const LAS bf16x8*)(lds + PG8_SA(b, h) + aoff + m * 2048 + k * 1024); } while (0)
; #define PG8_LDB(dst, b, h) do { _Pragma("unroll") for (int n = 0; n < 2; ++n) _Pragma("unroll") for (int k = 0; k < 2; ++k) dst[n][k] = *(const LAS bf16x8*)(lds + PG8_SB(b, h) + boff + n * 2048 + k * 1024); } while (0)
; #define PG8_WAIT_V(n) asm volatile("s_waitcnt vmcnt(" #n ")" ::: "memory")
; #define PG8_WAIT_L(n) asm volatile("s_waitcnt lgkmcnt(" #n ")" ::: "memory")
; #define PG8_BAR __builtin_amdgcn_s_barrier()
; #define PG8_SCHED __builtin_amdgcn_sched_barrier(0)
; template <class Epi, class Sched, bool SWAPD = false>
; __device__ __forceinline__ void gemm_phase(LAS unsigned char* lds, const Gemm g, const Sched& S, const Epi& E) {
;     ...
;             PG8_WAIT_V(8); PG8_WAIT_L(0); PG8_BAR; PG8_MMA(1, 0, At, B0); PG8_MMA(1, 1, At, B1); PG8_BAR; PG8_SCHED;
;             PG8_LDB(B0, 1, 0); PG8_LDB(B1, 1, 1); PG8_SCHED; PG8_LDA(At, 1, 0); PG8_STAGE(PG8_SA(0, 1), a2 + hstepA, voffA);
;             PG8_WAIT_V(8); PG8_WAIT_L(0); PG8_BAR; PG8_MMA(0, 0, At, B0); PG8_MMA(0, 1, At, B1); PG8_BAR; PG8_SCHED;
	s_setprio 1
	v_mfma_f32_16x16x32_bf16 v[60:63], v[150:153], v[182:185], v[60:63]
	v_mfma_f32_16x16x32_bf16 v[56:59], v[158:161], v[182:185], v[56:59]
	v_mfma_f32_16x16x32_bf16 v[44:47], v[150:153], v[190:193], v[44:47]
	v_mfma_f32_16x16x32_bf16 v[40:43], v[158:161], v[190:193], v[40:43]
	v_mfma_f32_16x16x32_bf16 v[28:31], v[150:153], v[198:201], v[28:31]
	v_mfma_f32_16x16x32_bf16 v[24:27], v[158:161], v[198:201], v[24:27]
	v_mfma_f32_16x16x32_bf16 v[12:15], v[150:153], v[208:211], v[12:15]
	v_mfma_f32_16x16x32_bf16 v[8:11], v[158:161], v[208:211], v[8:11]
	v_mfma_f32_16x16x32_bf16 v[60:63], v[154:157], v[186:189], v[60:63]
	v_mfma_f32_16x16x32_bf16 v[56:59], v[162:165], v[186:189], v[56:59]
	v_mfma_f32_16x16x32_bf16 v[44:47], v[154:157], v[194:197], v[44:47]
	v_mfma_f32_16x16x32_bf16 v[40:43], v[162:165], v[194:197], v[40:43]
	v_mfma_f32_16x16x32_bf16 v[28:31], v[154:157], v[202:205], v[28:31]
	v_mfma_f32_16x16x32_bf16 v[24:27], v[162:165], v[202:205], v[24:27]
	v_mfma_f32_16x16x32_bf16 v[12:15], v[154:157], v[212:215], v[12:15]
	v_mfma_f32_16x16x32_bf16 v[8:11], v[162:165], v[212:215], v[8:11]
	s_setprio 0
	s_setprio 1
	v_mfma_f32_16x16x32_bf16 v[52:55], v[166:169], v[182:185], v[52:55]
	v_mfma_f32_16x16x32_bf16 v[48:51], v[174:177], v[182:185], v[48:51]
	v_mfma_f32_16x16x32_bf16 v[36:39], v[166:169], v[190:193], v[36:39]
	v_mfma_f32_16x16x32_bf16 v[32:35], v[174:177], v[190:193], v[32:35]
	v_mfma_f32_16x16x32_bf16 v[20:23], v[166:169], v[198:201], v[20:23]
	v_mfma_f32_16x16x32_bf16 v[16:19], v[174:177], v[198:201], v[16:19]
	v_mfma_f32_16x16x32_bf16 v[4:7], v[166:169], v[208:211], v[4:7]
	v_mfma_f32_16x16x32_bf16 v[0:3], v[174:177], v[208:211], v[0:3]
	v_mfma_f32_16x16x32_bf16 v[52:55], v[170:173], v[186:189], v[52:55]
	v_mfma_f32_16x16x32_bf16 v[48:51], v[178:181], v[186:189], v[48:51]
	v_mfma_f32_16x16x32_bf16 v[36:39], v[170:173], v[194:197], v[36:39]
	v_mfma_f32_16x16x32_bf16 v[32:35], v[178:181], v[194:197], v[32:35]
	v_mfma_f32_16x16x32_bf16 v[20:23], v[170:173], v[202:205], v[20:23]
	v_mfma_f32_16x16x32_bf16 v[16:19], v[178:181], v[202:205], v[16:19]
	v_mfma_f32_16x16x32_bf16 v[4:7], v[170:173], v[212:215], v[4:7]
	v_mfma_f32_16x16x32_bf16 v[0:3], v[178:181], v[212:215], v[0:3]
	s_setprio 0
	s_barrier
	s_add_i32 s68, 0, 0x18000
	v_add_u32_e32 v149, s68, v144
	s_add_i32 s69, 0, 0x1c000
	ds_read_b128 v[150:153], v149
	ds_read_b128 v[154:157], v149 offset:1024
	ds_read_b128 v[158:161], v149 offset:2048
	ds_read_b128 v[162:165], v149 offset:3072
	v_add_u32_e32 v149, s69, v144
	ds_read_b128 v[166:169], v149
	ds_read_b128 v[170:173], v149 offset:1024
	ds_read_b128 v[174:177], v149 offset:2048
	ds_read_b128 v[178:181], v149 offset:3072
	s_add_u32 s40, s46, 0x30000
	s_addc_u32 s41, s47, 0
	s_mov_b32 m0, s51
	v_lshl_add_u64 v[222:223], s[40:41], 0, v[130:131]
	ds_read_b128 v[182:185], v148 offset:32768
	ds_read_b128 v[186:189], v148 offset:33792
	ds_read_b128 v[190:193], v148 offset:34816
	ds_read_b128 v[194:197], v148 offset:35840
	ds_read_b128 v[198:201], v148 offset:36864
	ds_read_b128 v[202:205], v148 offset:37888
	ds_read_b128 v[208:211], v148 offset:38912
	ds_read_b128 v[212:215], v148 offset:39936
	global_load_lds_dwordx4 v[222:223], off
	v_lshl_add_u64 v[222:223], s[40:41], 0, v[128:129]
	s_mov_b32 m0, s52
	s_nop 0
	global_load_lds_dwordx4 v[222:223], off
	s_waitcnt vmcnt(8)
	s_waitcnt lgkmcnt(0)
	s_barrier
	s_setprio 1
	v_mfma_f32_16x16x32_bf16 v[124:127], v[150:153], v[182:185], v[124:127]
	v_mfma_f32_16x16x32_bf16 v[120:123], v[158:161], v[182:185], v[120:123]
	v_mfma_f32_16x16x32_bf16 v[108:111], v[150:153], v[190:193], v[108:111]
	v_mfma_f32_16x16x32_bf16 v[104:107], v[158:161], v[190:193], v[104:107]
	v_mfma_f32_16x16x32_bf16 v[92:95], v[150:153], v[198:201], v[92:95]
	v_mfma_f32_16x16x32_bf16 v[88:91], v[158:161], v[198:201], v[88:91]
	v_mfma_f32_16x16x32_bf16 v[76:79], v[150:153], v[208:211], v[76:79]
	v_mfma_f32_16x16x32_bf16 v[72:75], v[158:161], v[208:211], v[72:75]
	v_mfma_f32_16x16x32_bf16 v[124:127], v[154:157], v[186:189], v[124:127]
	v_mfma_f32_16x16x32_bf16 v[120:123], v[162:165], v[186:189], v[120:123]
	v_mfma_f32_16x16x32_bf16 v[108:111], v[154:157], v[194:197], v[108:111]
	v_mfma_f32_16x16x32_bf16 v[104:107], v[162:165], v[194:197], v[104:107]
	v_mfma_f32_16x16x32_bf16 v[92:95], v[154:157], v[202:205], v[92:95]
	v_mfma_f32_16x16x32_bf16 v[88:91], v[162:165], v[202:205], v[88:91]
	v_mfma_f32_16x16x32_bf16 v[76:79], v[154:157], v[212:215], v[76:79]
	v_mfma_f32_16x16x32_bf16 v[72:75], v[162:165], v[212:215], v[72:75]
	s_setprio 0
	s_setprio 1
	v_mfma_f32_16x16x32_bf16 v[116:119], v[166:169], v[182:185], v[116:119]
	v_mfma_f32_16x16x32_bf16 v[112:115], v[174:177], v[182:185], v[112:115]
	v_mfma_f32_16x16x32_bf16 v[100:103], v[166:169], v[190:193], v[100:103]
	v_mfma_f32_16x16x32_bf16 v[96:99], v[174:177], v[190:193], v[96:99]
	v_mfma_f32_16x16x32_bf16 v[84:87], v[166:169], v[198:201], v[84:87]
	v_mfma_f32_16x16x32_bf16 v[80:83], v[174:177], v[198:201], v[80:83]
	v_mfma_f32_16x16x32_bf16 v[68:71], v[166:169], v[208:211], v[68:71]
	v_mfma_f32_16x16x32_bf16 v[64:67], v[174:177], v[208:211], v[64:67]
	v_mfma_f32_16x16x32_bf16 v[116:119], v[170:173], v[186:189], v[116:119]
	v_mfma_f32_16x16x32_bf16 v[112:115], v[178:181], v[186:189], v[112:115]
	v_mfma_f32_16x16x32_bf16 v[100:103], v[170:173], v[194:197], v[100:103]
	v_mfma_f32_16x16x32_bf16 v[96:99], v[178:181], v[194:197], v[96:99]
	v_mfma_f32_16x16x32_bf16 v[84:87], v[170:173], v[202:205], v[84:87]
	v_mfma_f32_16x16x32_bf16 v[80:83], v[178:181], v[202:205], v[80:83]
	v_mfma_f32_16x16x32_bf16 v[68:71], v[170:173], v[212:215], v[68:71]
	v_mfma_f32_16x16x32_bf16 v[64:67], v[178:181], v[212:215], v[64:67]
	s_setprio 0
	s_barrier
; #define PG8_STAGE(bufoff, gbase, voff) do { _Pragma("unroll") for (int _i = 0; _i < 2; ++_i) \
;         __builtin_amdgcn_global_load_lds((const unsigned*)((const char*)(gbase) + (voff)[_i]), (LAS unsigned*)(lds + (bufoff) + ldsw + _i * 8192), 16, 0, 0); } while (0)
; #define PG8_LDA(dst, b, h) do { _Pragma("unroll") for (int m = 0; m < 4; ++m) _Pragma("unroll") for (int k = 0; k < 2; ++k) dst[m][k] = *(const LAS bf16x8*)(lds + PG8_SA(b, h) + aoff + m * 2048 + k * 1024); } while (0)
; #define PG8_WAIT_V(n) asm volatile("s_waitcnt vmcnt(" #n ")" ::: "memory")
; #define PG8_WAIT_L(n) asm volatile("s_waitcnt lgkmcnt(" #n ")" ::: "memory")
; #define PG8_BAR __builtin_amdgcn_s_barrier()
; #define PG8_SCHED __builtin_amdgcn_sched_barrier(0)
; template <class Epi, class Sched, bool SWAPD = false>
; __device__ __forceinline__ void gemm_phase(LAS unsigned char* lds, const Gemm g, const Sched& S, const Epi& E) {
;     ...
;             PG8_LDA(At, 1, 1); PG8_STAGE(PG8_SB(1, 0), b3, voffB); PG8_STAGE(PG8_SB(1, 1), b3 + hstepB, voffB); PG8_STAGE(PG8_SA(1, 0), a3, voffA);
;             PG8_WAIT_V(8); PG8_WAIT_L(0); PG8_BAR; PG8_MMA(1, 0, At, B0); PG8_MMA(1, 1, At, B1); PG8_BAR; PG8_SCHED;
;         }
;         if (wr == 0) PG8_BAR;
	s_add_i32 s40, s68, s21
	v_lshl_add_u64 v[142:143], v[142:143], 0, s[12:13]
	s_mov_b32 m0, s40
	ds_read_b128 v[182:185], v148 offset:49152
	ds_read_b128 v[186:189], v148 offset:50176
	ds_read_b128 v[190:193], v148 offset:51200
	ds_read_b128 v[194:197], v148 offset:52224
	ds_read_b128 v[198:201], v148 offset:53248
	ds_read_b128 v[202:205], v148 offset:54272
	ds_read_b128 v[208:211], v148 offset:55296
	ds_read_b128 v[212:215], v148 offset:56320
	global_load_lds_dwordx4 v[142:143], off
	s_add_i32 m0, s40, 0x2000
	s_add_u32 s40, s44, 0x30080
	v_lshl_add_u64 v[142:143], v[216:217], 0, s[12:13]
	s_addc_u32 s41, s45, 0
	s_add_i32 s44, s69, s21
	global_load_lds_dwordx4 v[142:143], off
	v_lshl_add_u64 v[142:143], s[40:41], 0, v[130:131]
	s_mov_b32 m0, s44
	s_nop 0
	global_load_lds_dwordx4 v[142:143], off
	v_lshl_add_u64 v[142:143], s[40:41], 0, v[128:129]
	s_add_i32 m0, s44, 0x2000
	s_nop 0
	global_load_lds_dwordx4 v[142:143], off
	v_lshl_add_u64 v[142:143], v[218:219], 0, s[12:13]
	s_mov_b32 m0, s54
	s_nop 0
	global_load_lds_dwordx4 v[142:143], off
	v_lshl_add_u64 v[142:143], v[220:221], 0, s[12:13]
	s_mov_b32 m0, s55
	s_nop 0
	global_load_lds_dwordx4 v[142:143], off
	s_waitcnt vmcnt(8)
	s_waitcnt lgkmcnt(0)
	s_barrier
	s_setprio 1
	v_mfma_f32_16x16x32_bf16 v[60:63], v[150:153], v[182:185], v[60:63]
	v_mfma_f32_16x16x32_bf16 v[56:59], v[158:161], v[182:185], v[56:59]
	v_mfma_f32_16x16x32_bf16 v[44:47], v[150:153], v[190:193], v[44:47]
	v_mfma_f32_16x16x32_bf16 v[40:43], v[158:161], v[190:193], v[40:43]
	v_mfma_f32_16x16x32_bf16 v[28:31], v[150:153], v[198:201], v[28:31]
	v_mfma_f32_16x16x32_bf16 v[24:27], v[158:161], v[198:201], v[24:27]
	v_mfma_f32_16x16x32_bf16 v[12:15], v[150:153], v[208:211], v[12:15]
	v_mfma_f32_16x16x32_bf16 v[8:11], v[158:161], v[208:211], v[8:11]
	v_mfma_f32_16x16x32_bf16 v[60:63], v[154:157], v[186:189], v[60:63]
	v_mfma_f32_16x16x32_bf16 v[56:59], v[162:165], v[186:189], v[56:59]
	v_mfma_f32_16x16x32_bf16 v[44:47], v[154:157], v[194:197], v[44:47]
	v_mfma_f32_16x16x32_bf16 v[40:43], v[162:165], v[194:197], v[40:43]
	v_mfma_f32_16x16x32_bf16 v[28:31], v[154:157], v[202:205], v[28:31]
	v_mfma_f32_16x16x32_bf16 v[24:27], v[162:165], v[202:205], v[24:27]
	v_mfma_f32_16x16x32_bf16 v[12:15], v[154:157], v[212:215], v[12:15]
	v_mfma_f32_16x16x32_bf16 v[8:11], v[162:165], v[212:215], v[8:11]
	s_setprio 0
	s_setprio 1
	v_mfma_f32_16x16x32_bf16 v[52:55], v[166:169], v[182:185], v[52:55]
	v_mfma_f32_16x16x32_bf16 v[48:51], v[174:177], v[182:185], v[48:51]
	v_mfma_f32_16x16x32_bf16 v[36:39], v[166:169], v[190:193], v[36:39]
	v_mfma_f32_16x16x32_bf16 v[32:35], v[174:177], v[190:193], v[32:35]
	v_mfma_f32_16x16x32_bf16 v[20:23], v[166:169], v[198:201], v[20:23]
	v_mfma_f32_16x16x32_bf16 v[16:19], v[174:177], v[198:201], v[16:19]
	v_mfma_f32_16x16x32_bf16 v[4:7], v[166:169], v[208:211], v[4:7]
	v_mfma_f32_16x16x32_bf16 v[0:3], v[174:177], v[208:211], v[0:3]
	v_mfma_f32_16x16x32_bf16 v[52:55], v[170:173], v[186:189], v[52:55]
	v_mfma_f32_16x16x32_bf16 v[48:51], v[178:181], v[186:189], v[48:51]
	v_mfma_f32_16x16x32_bf16 v[36:39], v[170:173], v[194:197], v[36:39]
	v_mfma_f32_16x16x32_bf16 v[32:35], v[178:181], v[194:197], v[32:35]
	v_mfma_f32_16x16x32_bf16 v[20:23], v[170:173], v[202:205], v[20:23]
	v_mfma_f32_16x16x32_bf16 v[16:19], v[178:181], v[202:205], v[16:19]
	v_mfma_f32_16x16x32_bf16 v[4:7], v[170:173], v[212:215], v[4:7]
	v_mfma_f32_16x16x32_bf16 v[0:3], v[178:181], v[212:215], v[0:3]
	s_setprio 0
	s_barrier
	s_add_i32 s67, s67, 2
	s_add_u32 s65, s65, 0x100
	s_addc_u32 s66, s66, 0
	s_cmp_gt_u32 s67, 9
	s_mov_b64 s[40:41], s[42:43]
	s_cbranch_scc0 .LBB0_766
	s_and_b64 vcc, exec, s[24:25]
	s_cbranch_vccz .LBB0_769
	s_barrier

; #define PG8_STAGE(bufoff, gbase, voff) do { _Pragma("unroll") for (int _i = 0; _i < 2; ++_i) \
;         __builtin_amdgcn_global_load_lds((const unsigned*)((const char*)(gbase) + (voff)[_i]), (LAS unsigned*)(lds + (bufoff) + ldsw + _i * 8192), 16, 0, 0); } while (0)
; #define PG8_LDA(dst, b, h) do { _Pragma("unroll") for (int m = 0; m < 4; ++m) _Pragma("unroll") for (int k = 0; k < 2; ++k) dst[m][k] = *(const LAS bf16x8*)(lds + PG8_SA(b, h) + aoff + m * 2048 + k * 1024); } while (0)
; #define PG8_LDB(dst, b, h) do { _Pragma("unroll") for (int n = 0; n < 2; ++n) _Pragma("unroll") for (int k = 0; k < 2; ++k) dst[n][k] = *(const LAS bf16x8*)(lds + PG8_SB(b, h) + boff + n * 2048 + k * 1024); } while (0)
; #define PG8_WAIT_V(n) asm volatile("s_waitcnt vmcnt(" #n ")" ::: "memory")
; #define PG8_WAIT_L(n) asm volatile("s_waitcnt lgkmcnt(" #n ")" ::: "memory")
; #define PG8_BAR __builtin_amdgcn_s_barrier()
; #define PG8_SCHED __builtin_amdgcn_sched_barrier(0)
; template <class Epi, class Sched, bool SWAPD = false>
; __device__ __forceinline__ void gemm_phase(LAS unsigned char* lds, const Gemm g, const Sched& S, const Epi& E) {
;     ...
;         const bool has_next = S.next(ui + 1, nxt);
;         const char* nA = has_next ? (const char*)g.A + nxt.aoff : cA; const char* nB = has_next ? (const char*)g.Bt + nxt.boff : cB;
;         const int nt = cur.nt ? cur.nt : ntK;
;         for (int t = 0; t < nt; t += 2) {
;             const bool last = (t == nt - 2);
;             const char* a1 = cA + (size_t)(t + 1) * kstepA;
;             const char* a2 = last ? nA : cA + (size_t)(t + 2) * kstepA; const char* b2 = last ? nB : cB + (size_t)(t + 2) * kstep;
;             const char* a3 = a2 + kstepA; const char* b3 = b2 + kstep;
;             PG8_LDB(B0, 0, 0); PG8_LDB(B1, 0, 1); PG8_SCHED; PG8_LDA(At, 0, 0); PG8_STAGE(PG8_SA(1, 1), a1 + hstepA, voffA);
;             PG8_WAIT_V(8); PG8_WAIT_L(0); PG8_BAR; PG8_MMA(0, 0, At, B0); PG8_MMA(0, 1, At, B1); PG8_BAR; PG8_SCHED;
;             PG8_LDA(At, 0, 1); PG8_STAGE(PG8_SB(0, 0), b2, voffB); PG8_STAGE(PG8_SB(0, 1), b2 + hstepB, voffB); PG8_STAGE(PG8_SA(0, 0), a2, voffA);
;             PG8_WAIT_V(8); PG8_WAIT_L(0); PG8_BAR; PG8_MMA(1, 0, At, B0); PG8_MMA(1, 1, At, B1); PG8_BAR; PG8_SCHED;
.LBB0_842:
	ds_read_b128 v[146:149], v153
	ds_read_b128 v[156:159], v153 offset:1024
	ds_read_b128 v[160:163], v153 offset:2048
	ds_read_b128 v[164:167], v153 offset:3072
	ds_read_b128 v[168:171], v154
	ds_read_b128 v[172:175], v154 offset:1024
	ds_read_b128 v[176:179], v154 offset:2048
	ds_read_b128 v[180:183], v154 offset:3072
	s_add_u32 s44, s42, 0x800000
	s_addc_u32 s45, s43, 0
	s_cmp_eq_u32 s62, 4
	s_cselect_b32 s52, s25, s44
	s_cselect_b32 s53, s23, s45
	s_cselect_b32 s50, s59, s60
	s_cselect_b32 s51, s35, s61
	s_add_u32 s46, s52, 0x400000
	s_addc_u32 s47, s53, 0
	v_lshl_add_u64 v[204:205], s[42:43], 0, v[138:139]
	s_add_i32 m0, s30, 0xc000
	ds_read_b128 v[184:187], v155
	ds_read_b128 v[188:191], v155 offset:1024
	ds_read_b128 v[192:195], v155 offset:2048
	ds_read_b128 v[196:199], v155 offset:3072
	ds_read_b128 v[200:203], v155 offset:4096
	ds_read_b128 v[208:211], v155 offset:5120
	ds_read_b128 v[212:215], v155 offset:6144
	ds_read_b128 v[216:219], v155 offset:7168
	global_load_lds_dwordx4 v[204:205], off
	v_lshl_add_u64 v[204:205], s[42:43], 0, v[140:141]
	s_add_i32 m0, s30, 0xe000
	s_nop 0
	global_load_lds_dwordx4 v[204:205], off
	s_waitcnt vmcnt(8)
	s_waitcnt lgkmcnt(0)
	s_barrier
	s_setprio 1
	v_mfma_f32_16x16x32_bf16 v[124:127], v[146:149], v[184:187], v[124:127]
	v_mfma_f32_16x16x32_bf16 v[120:123], v[160:163], v[184:187], v[120:123]
	v_mfma_f32_16x16x32_bf16 v[108:111], v[146:149], v[192:195], v[108:111]
	v_mfma_f32_16x16x32_bf16 v[104:107], v[160:163], v[192:195], v[104:107]
	v_mfma_f32_16x16x32_bf16 v[92:95], v[146:149], v[200:203], v[92:95]
	v_mfma_f32_16x16x32_bf16 v[88:91], v[160:163], v[200:203], v[88:91]
	v_mfma_f32_16x16x32_bf16 v[76:79], v[146:149], v[212:215], v[76:79]
	v_mfma_f32_16x16x32_bf16 v[72:75], v[160:163], v[212:215], v[72:75]
	v_mfma_f32_16x16x32_bf16 v[124:127], v[156:159], v[188:191], v[124:127]
	v_mfma_f32_16x16x32_bf16 v[120:123], v[164:167], v[188:191], v[120:123]
	v_mfma_f32_16x16x32_bf16 v[108:111], v[156:159], v[196:199], v[108:111]
	v_mfma_f32_16x16x32_bf16 v[104:107], v[164:167], v[196:199], v[104:107]
	v_mfma_f32_16x16x32_bf16 v[92:95], v[156:159], v[208:211], v[92:95]
	v_mfma_f32_16x16x32_bf16 v[88:91], v[164:167], v[208:211], v[88:91]
	v_mfma_f32_16x16x32_bf16 v[76:79], v[156:159], v[216:219], v[76:79]
	v_mfma_f32_16x16x32_bf16 v[72:75], v[164:167], v[216:219], v[72:75]
	s_setprio 0
	s_setprio 1
	v_mfma_f32_16x16x32_bf16 v[116:119], v[168:171], v[184:187], v[116:119]
	v_mfma_f32_16x16x32_bf16 v[112:115], v[176:179], v[184:187], v[112:115]
	v_mfma_f32_16x16x32_bf16 v[100:103], v[168:171], v[192:195], v[100:103]
	v_mfma_f32_16x16x32_bf16 v[96:99], v[176:179], v[192:195], v[96:99]
	v_mfma_f32_16x16x32_bf16 v[84:87], v[168:171], v[200:203], v[84:87]
	v_mfma_f32_16x16x32_bf16 v[80:83], v[176:179], v[200:203], v[80:83]
	v_mfma_f32_16x16x32_bf16 v[68:71], v[168:171], v[212:215], v[68:71]
	v_mfma_f32_16x16x32_bf16 v[64:67], v[176:179], v[212:215], v[64:67]
	v_mfma_f32_16x16x32_bf16 v[116:119], v[172:175], v[188:191], v[116:119]
	v_mfma_f32_16x16x32_bf16 v[112:115], v[180:183], v[188:191], v[112:115]
	v_mfma_f32_16x16x32_bf16 v[100:103], v[172:175], v[196:199], v[100:103]
	v_mfma_f32_16x16x32_bf16 v[96:99], v[180:183], v[196:199], v[96:99]
	v_mfma_f32_16x16x32_bf16 v[84:87], v[172:175], v[208:211], v[84:87]
	v_mfma_f32_16x16x32_bf16 v[80:83], v[180:183], v[208:211], v[80:83]
	v_mfma_f32_16x16x32_bf16 v[68:71], v[172:175], v[216:219], v[68:71]
	v_mfma_f32_16x16x32_bf16 v[64:67], v[180:183], v[216:219], v[64:67]
	s_setprio 0
	s_barrier
	s_add_i32 s42, s57, s21
	v_lshl_add_u64 v[204:205], s[50:51], 0, v[130:131]
	s_mov_b32 m0, s42
	ds_read_b128 v[184:187], v155 offset:16384
	ds_read_b128 v[188:191], v155 offset:17408
	ds_read_b128 v[192:195], v155 offset:18432
	ds_read_b128 v[196:199], v155 offset:19456
	ds_read_b128 v[200:203], v155 offset:20480
	ds_read_b128 v[208:211], v155 offset:21504
	ds_read_b128 v[212:215], v155 offset:22528
	ds_read_b128 v[216:219], v155 offset:23552
	global_load_lds_dwordx4 v[204:205], off
	s_add_i32 m0, s42, 0x2000
	s_add_u32 s42, s50, 0x20000
	v_lshl_add_u64 v[220:221], s[50:51], 0, v[134:135]
	s_addc_u32 s43, s51, 0
	s_add_i32 s63, s58, s21
	global_load_lds_dwordx4 v[220:221], off
	v_lshl_add_u64 v[222:223], s[42:43], 0, v[130:131]
	s_mov_b32 m0, s63
	s_nop 0
	global_load_lds_dwordx4 v[222:223], off
	v_lshl_add_u64 v[222:223], s[42:43], 0, v[134:135]
	s_add_i32 m0, s63, 0x2000
	s_nop 0
	global_load_lds_dwordx4 v[222:223], off
	v_lshl_add_u64 v[222:223], s[52:53], 0, v[128:129]
	s_mov_b32 m0, s30
	s_nop 0
	global_load_lds_dwordx4 v[222:223], off
	v_lshl_add_u64 v[222:223], s[52:53], 0, v[132:133]
	s_mov_b32 m0, s31
	s_nop 0
	global_load_lds_dwordx4 v[222:223], off
	s_waitcnt vmcnt(8)
	s_waitcnt lgkmcnt(0)
	s_barrier
; #define PG8_STAGE(bufoff, gbase, voff) do { _Pragma("unroll") for (int _i = 0; _i < 2; ++_i) \
;         __builtin_amdgcn_global_load_lds((const unsigned*)((const char*)(gbase) + (voff)[_i]), (LAS unsigned*)(lds + (bufoff) + ldsw + _i * 8192), 16, 0, 0); } while (0)
; #define PG8_LDA(dst, b, h) do { _Pragma("unroll") for (int m = 0; m < 4; ++m) _Pragma("unroll") for (int k = 0; k < 2; ++k) dst[m][k] = *(const LAS bf16x8*)(lds + PG8_SA(b, h) + aoff + m * 2048 + k * 1024); } while (0)
; #define PG8_LDB(dst, b, h) do { _Pragma("unroll") for (int n = 0; n < 2; ++n) _Pragma("unroll") for (int k = 0; k < 2; ++k) dst[n][k] = *(const LAS bf16x8*)(lds + PG8_SB(b, h) + boff + n * 2048 + k * 1024); } while (0)
; #define PG8_WAIT_V(n) asm volatile("s_waitcnt vmcnt(" #n ")" ::: "memory")
; #define PG8_WAIT_L(n) asm volatile("s_waitcnt lgkmcnt(" #n ")" ::: "memory")
; #define PG8_BAR __builtin_amdgcn_s_barrier()
; #define PG8_SCHED __builtin_amdgcn_sched_barrier(0)
; template <class Epi, class Sched, bool SWAPD = false>
; __device__ __forceinline__ void gemm_phase(LAS unsigned char* lds, const Gemm g, const Sched& S, const Epi& E) {
;     ...
;             PG8_WAIT_V(8); PG8_WAIT_L(0); PG8_BAR; PG8_MMA(1, 0, At, B0); PG8_MMA(1, 1, At, B1); PG8_BAR; PG8_SCHED;
;             PG8_LDB(B0, 1, 0); PG8_LDB(B1, 1, 1); PG8_SCHED; PG8_LDA(At, 1, 0); PG8_STAGE(PG8_SA(0, 1), a2 + hstepA, voffA);
;             PG8_WAIT_V(8); PG8_WAIT_L(0); PG8_BAR; PG8_MMA(0, 0, At, B0); PG8_MMA(0, 1, At, B1); PG8_BAR; PG8_SCHED;
	s_setprio 1
	v_mfma_f32_16x16x32_bf16 v[60:63], v[146:149], v[184:187], v[60:63]
	v_mfma_f32_16x16x32_bf16 v[56:59], v[160:163], v[184:187], v[56:59]
	v_mfma_f32_16x16x32_bf16 v[44:47], v[146:149], v[192:195], v[44:47]
	v_mfma_f32_16x16x32_bf16 v[40:43], v[160:163], v[192:195], v[40:43]
	v_mfma_f32_16x16x32_bf16 v[28:31], v[146:149], v[200:203], v[28:31]
	v_mfma_f32_16x16x32_bf16 v[24:27], v[160:163], v[200:203], v[24:27]
	v_mfma_f32_16x16x32_bf16 v[12:15], v[146:149], v[212:215], v[12:15]
	v_mfma_f32_16x16x32_bf16 v[8:11], v[160:163], v[212:215], v[8:11]
	v_mfma_f32_16x16x32_bf16 v[60:63], v[156:159], v[188:191], v[60:63]
	v_mfma_f32_16x16x32_bf16 v[56:59], v[164:167], v[188:191], v[56:59]
	v_mfma_f32_16x16x32_bf16 v[44:47], v[156:159], v[196:199], v[44:47]
	v_mfma_f32_16x16x32_bf16 v[40:43], v[164:167], v[196:199], v[40:43]
	v_mfma_f32_16x16x32_bf16 v[28:31], v[156:159], v[208:211], v[28:31]
	v_mfma_f32_16x16x32_bf16 v[24:27], v[164:167], v[208:211], v[24:27]
	v_mfma_f32_16x16x32_bf16 v[12:15], v[156:159], v[216:219], v[12:15]
	v_mfma_f32_16x16x32_bf16 v[8:11], v[164:167], v[216:219], v[8:11]
	s_setprio 0
	s_setprio 1
	v_mfma_f32_16x16x32_bf16 v[52:55], v[168:171], v[184:187], v[52:55]
	v_mfma_f32_16x16x32_bf16 v[48:51], v[176:179], v[184:187], v[48:51]
	v_mfma_f32_16x16x32_bf16 v[36:39], v[168:171], v[192:195], v[36:39]
	v_mfma_f32_16x16x32_bf16 v[32:35], v[176:179], v[192:195], v[32:35]
	v_mfma_f32_16x16x32_bf16 v[20:23], v[168:171], v[200:203], v[20:23]
	v_mfma_f32_16x16x32_bf16 v[16:19], v[176:179], v[200:203], v[16:19]
	v_mfma_f32_16x16x32_bf16 v[4:7], v[168:171], v[212:215], v[4:7]
	v_mfma_f32_16x16x32_bf16 v[0:3], v[176:179], v[212:215], v[0:3]
	v_mfma_f32_16x16x32_bf16 v[52:55], v[172:175], v[188:191], v[52:55]
	v_mfma_f32_16x16x32_bf16 v[48:51], v[180:183], v[188:191], v[48:51]
	v_mfma_f32_16x16x32_bf16 v[36:39], v[172:175], v[196:199], v[36:39]
	v_mfma_f32_16x16x32_bf16 v[32:35], v[180:183], v[196:199], v[32:35]
	v_mfma_f32_16x16x32_bf16 v[20:23], v[172:175], v[208:211], v[20:23]
	v_mfma_f32_16x16x32_bf16 v[16:19], v[180:183], v[208:211], v[16:19]
	v_mfma_f32_16x16x32_bf16 v[4:7], v[172:175], v[216:219], v[4:7]
	v_mfma_f32_16x16x32_bf16 v[0:3], v[180:183], v[216:219], v[0:3]
	s_setprio 0
	s_barrier
	s_add_i32 s63, 0, 0x18000
	s_add_i32 s64, 0, 0x1c000
	v_add_u32_e32 v164, s63, v151
	v_add_u32_e32 v180, s64, v151
	ds_read_b128 v[146:149], v164
	ds_read_b128 v[156:159], v164 offset:1024
	ds_read_b128 v[160:163], v164 offset:2048
	ds_read_b128 v[164:167], v164 offset:3072
	ds_read_b128 v[168:171], v180
	ds_read_b128 v[172:175], v180 offset:1024
	ds_read_b128 v[176:179], v180 offset:2048
	ds_read_b128 v[180:183], v180 offset:3072
	s_add_u32 s42, s52, 0x1000
	s_addc_u32 s43, s53, 0
	s_mov_b32 m0, s33
	v_lshl_add_u64 v[222:223], s[42:43], 0, v[128:129]
	ds_read_b128 v[184:187], v155 offset:32768
	ds_read_b128 v[188:191], v155 offset:33792
	ds_read_b128 v[192:195], v155 offset:34816
	ds_read_b128 v[196:199], v155 offset:35840
	ds_read_b128 v[200:203], v155 offset:36864
	ds_read_b128 v[208:211], v155 offset:37888
	ds_read_b128 v[212:215], v155 offset:38912
	ds_read_b128 v[216:219], v155 offset:39936
	global_load_lds_dwordx4 v[222:223], off
	v_lshl_add_u64 v[222:223], s[42:43], 0, v[132:133]
	s_mov_b32 m0, s41
	s_nop 0
	global_load_lds_dwordx4 v[222:223], off
	s_waitcnt vmcnt(8)
	s_waitcnt lgkmcnt(0)
	s_barrier
	s_setprio 1
	v_mfma_f32_16x16x32_bf16 v[124:127], v[146:149], v[184:187], v[124:127]
	v_mfma_f32_16x16x32_bf16 v[120:123], v[160:163], v[184:187], v[120:123]
	v_mfma_f32_16x16x32_bf16 v[108:111], v[146:149], v[192:195], v[108:111]
	v_mfma_f32_16x16x32_bf16 v[104:107], v[160:163], v[192:195], v[104:107]
	v_mfma_f32_16x16x32_bf16 v[92:95], v[146:149], v[200:203], v[92:95]
	v_mfma_f32_16x16x32_bf16 v[88:91], v[160:163], v[200:203], v[88:91]
	v_mfma_f32_16x16x32_bf16 v[76:79], v[146:149], v[212:215], v[76:79]
	v_mfma_f32_16x16x32_bf16 v[72:75], v[160:163], v[212:215], v[72:75]
	v_mfma_f32_16x16x32_bf16 v[124:127], v[156:159], v[188:191], v[124:127]
	v_mfma_f32_16x16x32_bf16 v[120:123], v[164:167], v[188:191], v[120:123]
	v_mfma_f32_16x16x32_bf16 v[108:111], v[156:159], v[196:199], v[108:111]
	v_mfma_f32_16x16x32_bf16 v[104:107], v[164:167], v[196:199], v[104:107]
	v_mfma_f32_16x16x32_bf16 v[92:95], v[156:159], v[208:211], v[92:95]
	v_mfma_f32_16x16x32_bf16 v[88:91], v[164:167], v[208:211], v[88:91]
	v_mfma_f32_16x16x32_bf16 v[76:79], v[156:159], v[216:219], v[76:79]
	v_mfma_f32_16x16x32_bf16 v[72:75], v[164:167], v[216:219], v[72:75]
	s_setprio 0
	s_setprio 1
	v_mfma_f32_16x16x32_bf16 v[116:119], v[168:171], v[184:187], v[116:119]
	v_mfma_f32_16x16x32_bf16 v[112:115], v[176:179], v[184:187], v[112:115]
	v_mfma_f32_16x16x32_bf16 v[100:103], v[168:171], v[192:195], v[100:103]
	v_mfma_f32_16x16x32_bf16 v[96:99], v[176:179], v[192:195], v[96:99]
	v_mfma_f32_16x16x32_bf16 v[84:87], v[168:171], v[200:203], v[84:87]
	v_mfma_f32_16x16x32_bf16 v[80:83], v[176:179], v[200:203], v[80:83]
	v_mfma_f32_16x16x32_bf16 v[68:71], v[168:171], v[212:215], v[68:71]
	v_mfma_f32_16x16x32_bf16 v[64:67], v[176:179], v[212:215], v[64:67]
	v_mfma_f32_16x16x32_bf16 v[116:119], v[172:175], v[188:191], v[116:119]
	v_mfma_f32_16x16x32_bf16 v[112:115], v[180:183], v[188:191], v[112:115]
	v_mfma_f32_16x16x32_bf16 v[100:103], v[172:175], v[196:199], v[100:103]
	v_mfma_f32_16x16x32_bf16 v[96:99], v[180:183], v[196:199], v[96:99]
	v_mfma_f32_16x16x32_bf16 v[84:87], v[172:175], v[208:211], v[84:87]
	v_mfma_f32_16x16x32_bf16 v[80:83], v[180:183], v[208:211], v[80:83]
	v_mfma_f32_16x16x32_bf16 v[68:71], v[172:175], v[216:219], v[68:71]
	v_mfma_f32_16x16x32_bf16 v[64:67], v[180:183], v[216:219], v[64:67]
	s_setprio 0
	s_barrier
; #define PG8_STAGE(bufoff, gbase, voff) do { _Pragma("unroll") for (int _i = 0; _i < 2; ++_i) \
;         __builtin_amdgcn_global_load_lds((const unsigned*)((const char*)(gbase) + (voff)[_i]), (LAS unsigned*)(lds + (bufoff) + ldsw + _i * 8192), 16, 0, 0); } while (0)
; #define PG8_LDA(dst, b, h) do { _Pragma("unroll") for (int m = 0; m < 4; ++m) _Pragma("unroll") for (int k = 0; k < 2; ++k) dst[m][k] = *(const LAS bf16x8*)(lds + PG8_SA(b, h) + aoff + m * 2048 + k * 1024); } while (0)
; #define PG8_WAIT_V(n) asm volatile("s_waitcnt vmcnt(" #n ")" ::: "memory")
; #define PG8_WAIT_L(n) asm volatile("s_waitcnt lgkmcnt(" #n ")" ::: "memory")
; #define PG8_BAR __builtin_amdgcn_s_barrier()
; #define PG8_SCHED __builtin_amdgcn_sched_barrier(0)
; template <class Epi, class Sched, bool SWAPD = false>
; __device__ __forceinline__ void gemm_phase(LAS unsigned char* lds, const Gemm g, const Sched& S, const Epi& E) {
;     ...
;             PG8_LDA(At, 1, 1); PG8_STAGE(PG8_SB(1, 0), b3, voffB); PG8_STAGE(PG8_SB(1, 1), b3 + hstepB, voffB); PG8_STAGE(PG8_SA(1, 0), a3, voffA);
;             PG8_WAIT_V(8); PG8_WAIT_L(0); PG8_BAR; PG8_MMA(1, 0, At, B0); PG8_MMA(1, 1, At, B1); PG8_BAR; PG8_SCHED;
;         }
;         if (wr == 0) PG8_BAR;
	s_add_i32 s42, s63, s21
	v_lshl_add_u64 v[204:205], v[204:205], 0, s[10:11]
	s_mov_b32 m0, s42
	ds_read_b128 v[184:187], v155 offset:49152
	ds_read_b128 v[188:191], v155 offset:50176
	ds_read_b128 v[192:195], v155 offset:51200
	ds_read_b128 v[196:199], v155 offset:52224
	ds_read_b128 v[200:203], v155 offset:53248
	ds_read_b128 v[208:211], v155 offset:54272
	ds_read_b128 v[212:215], v155 offset:55296
	ds_read_b128 v[216:219], v155 offset:56320
	global_load_lds_dwordx4 v[204:205], off
	s_add_i32 m0, s42, 0x2000
	s_add_u32 s42, s50, 0x20080
	v_lshl_add_u64 v[204:205], v[220:221], 0, s[10:11]
	s_addc_u32 s43, s51, 0
	s_add_i32 s50, s64, s21
	global_load_lds_dwordx4 v[204:205], off
	v_lshl_add_u64 v[204:205], s[42:43], 0, v[130:131]
	s_mov_b32 m0, s50
	s_nop 0
	global_load_lds_dwordx4 v[204:205], off
	v_lshl_add_u64 v[204:205], s[42:43], 0, v[134:135]
	s_add_i32 m0, s50, 0x2000
	s_nop 0
	global_load_lds_dwordx4 v[204:205], off
	v_lshl_add_u64 v[204:205], s[46:47], 0, v[128:129]
	s_mov_b32 m0, s55
	s_nop 0
	global_load_lds_dwordx4 v[204:205], off
	v_lshl_add_u64 v[204:205], s[46:47], 0, v[132:133]
	s_mov_b32 m0, s56
	s_nop 0
	global_load_lds_dwordx4 v[204:205], off
	s_waitcnt vmcnt(8)
	s_waitcnt lgkmcnt(0)
	s_barrier
	s_setprio 1
	v_mfma_f32_16x16x32_bf16 v[60:63], v[146:149], v[184:187], v[60:63]
	v_mfma_f32_16x16x32_bf16 v[56:59], v[160:163], v[184:187], v[56:59]
	v_mfma_f32_16x16x32_bf16 v[44:47], v[146:149], v[192:195], v[44:47]
	v_mfma_f32_16x16x32_bf16 v[40:43], v[160:163], v[192:195], v[40:43]
	v_mfma_f32_16x16x32_bf16 v[28:31], v[146:149], v[200:203], v[28:31]
	v_mfma_f32_16x16x32_bf16 v[24:27], v[160:163], v[200:203], v[24:27]
	v_mfma_f32_16x16x32_bf16 v[12:15], v[146:149], v[212:215], v[12:15]
	v_mfma_f32_16x16x32_bf16 v[8:11], v[160:163], v[212:215], v[8:11]
	v_mfma_f32_16x16x32_bf16 v[60:63], v[156:159], v[188:191], v[60:63]
	v_mfma_f32_16x16x32_bf16 v[56:59], v[164:167], v[188:191], v[56:59]
	v_mfma_f32_16x16x32_bf16 v[44:47], v[156:159], v[196:199], v[44:47]
	v_mfma_f32_16x16x32_bf16 v[40:43], v[164:167], v[196:199], v[40:43]
	v_mfma_f32_16x16x32_bf16 v[28:31], v[156:159], v[208:211], v[28:31]
	v_mfma_f32_16x16x32_bf16 v[24:27], v[164:167], v[208:211], v[24:27]
	v_mfma_f32_16x16x32_bf16 v[12:15], v[156:159], v[216:219], v[12:15]
	v_mfma_f32_16x16x32_bf16 v[8:11], v[164:167], v[216:219], v[8:11]
	s_setprio 0
	s_setprio 1
	v_mfma_f32_16x16x32_bf16 v[52:55], v[168:171], v[184:187], v[52:55]
	v_mfma_f32_16x16x32_bf16 v[48:51], v[176:179], v[184:187], v[48:51]
	v_mfma_f32_16x16x32_bf16 v[36:39], v[168:171], v[192:195], v[36:39]
	v_mfma_f32_16x16x32_bf16 v[32:35], v[176:179], v[192:195], v[32:35]
	v_mfma_f32_16x16x32_bf16 v[20:23], v[168:171], v[200:203], v[20:23]
	v_mfma_f32_16x16x32_bf16 v[16:19], v[176:179], v[200:203], v[16:19]
	v_mfma_f32_16x16x32_bf16 v[4:7], v[168:171], v[212:215], v[4:7]
	v_mfma_f32_16x16x32_bf16 v[0:3], v[176:179], v[212:215], v[0:3]
	v_mfma_f32_16x16x32_bf16 v[52:55], v[172:175], v[188:191], v[52:55]
	v_mfma_f32_16x16x32_bf16 v[48:51], v[180:183], v[188:191], v[48:51]
	v_mfma_f32_16x16x32_bf16 v[36:39], v[172:175], v[196:199], v[36:39]
	v_mfma_f32_16x16x32_bf16 v[32:35], v[180:183], v[196:199], v[32:35]
	v_mfma_f32_16x16x32_bf16 v[20:23], v[172:175], v[208:211], v[20:23]
	v_mfma_f32_16x16x32_bf16 v[16:19], v[180:183], v[208:211], v[16:19]
	v_mfma_f32_16x16x32_bf16 v[4:7], v[172:175], v[216:219], v[4:7]
	v_mfma_f32_16x16x32_bf16 v[0:3], v[180:183], v[216:219], v[0:3]
	s_setprio 0
	s_barrier
	s_add_i32 s62, s62, 2
	s_add_u32 s60, s60, 0x100
	s_addc_u32 s61, s61, 0
	s_cmp_gt_u32 s62, 5
	s_mov_b64 s[42:43], s[44:45]
	s_cbranch_scc0 .LBB0_842
	s_and_b64 vcc, exec, s[12:13]
	s_cbranch_vccz .LBB0_845
	s_barrier

; #define PG8_STAGE(bufoff, gbase, voff) do { _Pragma("unroll") for (int _i = 0; _i < 2; ++_i) \
;         __builtin_amdgcn_global_load_lds((const unsigned*)((const char*)(gbase) + (voff)[_i]), (LAS unsigned*)(lds + (bufoff) + ldsw + _i * 8192), 16, 0, 0); } while (0)
; #define PG8_LDA(dst, b, h) do { _Pragma("unroll") for (int m = 0; m < 4; ++m) _Pragma("unroll") for (int k = 0; k < 2; ++k) dst[m][k] = *(const LAS bf16x8*)(lds + PG8_SA(b, h) + aoff + m * 2048 + k * 1024); } while (0)
; #define PG8_LDB(dst, b, h) do { _Pragma("unroll") for (int n = 0; n < 2; ++n) _Pragma("unroll") for (int k = 0; k < 2; ++k) dst[n][k] = *(const LAS bf16x8*)(lds + PG8_SB(b, h) + boff + n * 2048 + k * 1024); } while (0)
; #define PG8_WAIT_V(n) asm volatile("s_waitcnt vmcnt(" #n ")" ::: "memory")
; #define PG8_WAIT_L(n) asm volatile("s_waitcnt lgkmcnt(" #n ")" ::: "memory")
; #define PG8_BAR __builtin_amdgcn_s_barrier()
; #define PG8_SCHED __builtin_amdgcn_sched_barrier(0)
; template <class Epi, class Sched, bool SWAPD = false>
; __device__ __forceinline__ void gemm_phase(LAS unsigned char* lds, const Gemm g, const Sched& S, const Epi& E) {
;     ...
;         const bool has_next = S.next(ui + 1, nxt);
;         const char* nA = has_next ? (const char*)g.A + nxt.aoff : cA; const char* nB = has_next ? (const char*)g.Bt + nxt.boff : cB;
;         const int nt = cur.nt ? cur.nt : ntK;
;         for (int t = 0; t < nt; t += 2) {
;             const bool last = (t == nt - 2);
;             const char* a1 = cA + (size_t)(t + 1) * kstepA;
;             const char* a2 = last ? nA : cA + (size_t)(t + 2) * kstepA; const char* b2 = last ? nB : cB + (size_t)(t + 2) * kstep;
;             const char* a3 = a2 + kstepA; const char* b3 = b2 + kstep;
;             PG8_LDB(B0, 0, 0); PG8_LDB(B1, 0, 1); PG8_SCHED; PG8_LDA(At, 0, 0); PG8_STAGE(PG8_SA(1, 1), a1 + hstepA, voffA);
;             PG8_WAIT_V(8); PG8_WAIT_L(0); PG8_BAR; PG8_MMA(0, 0, At, B0); PG8_MMA(0, 1, At, B1); PG8_BAR; PG8_SCHED;
;             PG8_LDA(At, 0, 1); PG8_STAGE(PG8_SB(0, 0), b2, voffB); PG8_STAGE(PG8_SB(0, 1), b2 + hstepB, voffB); PG8_STAGE(PG8_SA(0, 0), a2, voffA);
;             PG8_WAIT_V(8); PG8_WAIT_L(0); PG8_BAR; PG8_MMA(1, 0, At, B0); PG8_MMA(1, 1, At, B1); PG8_BAR; PG8_SCHED;
.LBB0_918:
	ds_read_b128 v[128:131], v200
	ds_read_b128 v[132:135], v200 offset:1024
	ds_read_b128 v[136:139], v200 offset:2048
	ds_read_b128 v[140:143], v200 offset:3072
	ds_read_b128 v[144:147], v201
	ds_read_b128 v[148:151], v201 offset:1024
	ds_read_b128 v[152:155], v201 offset:2048
	ds_read_b128 v[156:159], v201 offset:3072
	s_add_u32 s44, s42, 0xfffc0080
	s_addc_u32 s45, s43, -1
	s_cmp_eq_u32 s60, 12
	s_cselect_b32 s47, s23, s45
	s_cselect_b32 s46, s25, s44
	s_cselect_b32 s45, s35, s59
	s_cselect_b32 s44, s41, s58
	v_lshl_add_u64 v[196:197], s[42:43], 0, v[180:181]
	s_add_i32 m0, s30, 0xc000
	ds_read_b128 v[188:191], v202
	ds_read_b128 v[192:195], v202 offset:1024
	ds_read_b128 v[208:211], v202 offset:2048
	ds_read_b128 v[212:215], v202 offset:3072
	ds_read_b128 v[216:219], v202 offset:4096
	ds_read_b128 v[220:223], v202 offset:5120
	ds_read_b128 v[224:227], v202 offset:6144
	ds_read_b128 v[228:231], v202 offset:7168
	global_load_lds_dwordx4 v[196:197], off
	v_lshl_add_u64 v[196:197], s[42:43], 0, v[182:183]
	s_add_i32 m0, s30, 0xe000
	s_nop 0
	global_load_lds_dwordx4 v[196:197], off
	s_waitcnt vmcnt(8)
	s_waitcnt lgkmcnt(0)
	s_barrier
	s_setprio 1
	v_mfma_f32_16x16x32_bf16 v[124:127], v[128:131], v[188:191], v[124:127]
	v_mfma_f32_16x16x32_bf16 v[120:123], v[136:139], v[188:191], v[120:123]
	v_mfma_f32_16x16x32_bf16 v[116:119], v[128:131], v[208:211], v[116:119]
	v_mfma_f32_16x16x32_bf16 v[112:115], v[136:139], v[208:211], v[112:115]
	v_mfma_f32_16x16x32_bf16 v[92:95], v[128:131], v[216:219], v[92:95]
	v_mfma_f32_16x16x32_bf16 v[88:91], v[136:139], v[216:219], v[88:91]
	v_mfma_f32_16x16x32_bf16 v[76:79], v[128:131], v[224:227], v[76:79]
	v_mfma_f32_16x16x32_bf16 v[72:75], v[136:139], v[224:227], v[72:75]
	v_mfma_f32_16x16x32_bf16 v[124:127], v[132:135], v[192:195], v[124:127]
	v_mfma_f32_16x16x32_bf16 v[120:123], v[140:143], v[192:195], v[120:123]
	v_mfma_f32_16x16x32_bf16 v[116:119], v[132:135], v[212:215], v[116:119]
	v_mfma_f32_16x16x32_bf16 v[112:115], v[140:143], v[212:215], v[112:115]
	v_mfma_f32_16x16x32_bf16 v[92:95], v[132:135], v[220:223], v[92:95]
	v_mfma_f32_16x16x32_bf16 v[88:91], v[140:143], v[220:223], v[88:91]
	v_mfma_f32_16x16x32_bf16 v[76:79], v[132:135], v[228:231], v[76:79]
	v_mfma_f32_16x16x32_bf16 v[72:75], v[140:143], v[228:231], v[72:75]
	s_setprio 0
	s_setprio 1
	v_mfma_f32_16x16x32_bf16 v[108:111], v[144:147], v[188:191], v[108:111]
	v_mfma_f32_16x16x32_bf16 v[104:107], v[152:155], v[188:191], v[104:107]
	v_mfma_f32_16x16x32_bf16 v[100:103], v[144:147], v[208:211], v[100:103]
	v_mfma_f32_16x16x32_bf16 v[96:99], v[152:155], v[208:211], v[96:99]
	v_mfma_f32_16x16x32_bf16 v[84:87], v[144:147], v[216:219], v[84:87]
	v_mfma_f32_16x16x32_bf16 v[80:83], v[152:155], v[216:219], v[80:83]
	v_mfma_f32_16x16x32_bf16 v[68:71], v[144:147], v[224:227], v[68:71]
	v_mfma_f32_16x16x32_bf16 v[64:67], v[152:155], v[224:227], v[64:67]
	v_mfma_f32_16x16x32_bf16 v[108:111], v[148:151], v[192:195], v[108:111]
	v_mfma_f32_16x16x32_bf16 v[104:107], v[156:159], v[192:195], v[104:107]
	v_mfma_f32_16x16x32_bf16 v[100:103], v[148:151], v[212:215], v[100:103]
	v_mfma_f32_16x16x32_bf16 v[96:99], v[156:159], v[212:215], v[96:99]
	v_mfma_f32_16x16x32_bf16 v[84:87], v[148:151], v[220:223], v[84:87]
	v_mfma_f32_16x16x32_bf16 v[80:83], v[156:159], v[220:223], v[80:83]
	v_mfma_f32_16x16x32_bf16 v[68:71], v[148:151], v[228:231], v[68:71]
	v_mfma_f32_16x16x32_bf16 v[64:67], v[156:159], v[228:231], v[64:67]
	s_setprio 0
	s_barrier
	s_add_i32 s61, s56, s21
	v_lshl_add_u64 v[196:197], s[44:45], 0, v[160:161]
	s_mov_b32 m0, s61
	ds_read_b128 v[188:191], v202 offset:16384
	ds_read_b128 v[192:195], v202 offset:17408
	ds_read_b128 v[208:211], v202 offset:18432
	ds_read_b128 v[212:215], v202 offset:19456
	ds_read_b128 v[216:219], v202 offset:20480
	ds_read_b128 v[220:223], v202 offset:21504
	ds_read_b128 v[224:227], v202 offset:22528
	ds_read_b128 v[228:231], v202 offset:23552
	global_load_lds_dwordx4 v[196:197], off
	s_add_i32 m0, s61, 0x2000
	s_add_u32 s62, s44, 0x40000
	v_lshl_add_u64 v[204:205], s[44:45], 0, v[162:163]
	s_addc_u32 s63, s45, 0
	s_add_i32 s61, s57, s21
	global_load_lds_dwordx4 v[204:205], off
	v_lshl_add_u64 v[232:233], s[62:63], 0, v[160:161]
	s_mov_b32 m0, s61
	v_lshl_add_u64 v[234:235], s[46:47], 0, v[162:163]
	global_load_lds_dwordx4 v[232:233], off
	v_lshl_add_u64 v[232:233], s[62:63], 0, v[162:163]
	s_add_i32 m0, s61, 0x2000
	s_nop 0
	global_load_lds_dwordx4 v[232:233], off
	v_lshl_add_u64 v[232:233], s[46:47], 0, v[160:161]
	s_mov_b32 m0, s30
	s_nop 0
	global_load_lds_dwordx4 v[232:233], off
	s_mov_b32 m0, s31
	s_nop 0
	global_load_lds_dwordx4 v[234:235], off
	s_waitcnt vmcnt(8)
	s_waitcnt lgkmcnt(0)
	s_barrier
; #define PG8_STAGE(bufoff, gbase, voff) do { _Pragma("unroll") for (int _i = 0; _i < 2; ++_i) \
;         __builtin_amdgcn_global_load_lds((const unsigned*)((const char*)(gbase) + (voff)[_i]), (LAS unsigned*)(lds + (bufoff) + ldsw + _i * 8192), 16, 0, 0); } while (0)
; #define PG8_LDA(dst, b, h) do { _Pragma("unroll") for (int m = 0; m < 4; ++m) _Pragma("unroll") for (int k = 0; k < 2; ++k) dst[m][k] = *(const LAS bf16x8*)(lds + PG8_SA(b, h) + aoff + m * 2048 + k * 1024); } while (0)
; #define PG8_LDB(dst, b, h) do { _Pragma("unroll") for (int n = 0; n < 2; ++n) _Pragma("unroll") for (int k = 0; k < 2; ++k) dst[n][k] = *(const LAS bf16x8*)(lds + PG8_SB(b, h) + boff + n * 2048 + k * 1024); } while (0)
; #define PG8_WAIT_V(n) asm volatile("s_waitcnt vmcnt(" #n ")" ::: "memory")
; #define PG8_WAIT_L(n) asm volatile("s_waitcnt lgkmcnt(" #n ")" ::: "memory")
; #define PG8_BAR __builtin_amdgcn_s_barrier()
; #define PG8_SCHED __builtin_amdgcn_sched_barrier(0)
; template <class Epi, class Sched, bool SWAPD = false>
; __device__ __forceinline__ void gemm_phase(LAS unsigned char* lds, const Gemm g, const Sched& S, const Epi& E) {
;     ...
;             PG8_WAIT_V(8); PG8_WAIT_L(0); PG8_BAR; PG8_MMA(1, 0, At, B0); PG8_MMA(1, 1, At, B1); PG8_BAR; PG8_SCHED;
;             PG8_LDB(B0, 1, 0); PG8_LDB(B1, 1, 1); PG8_SCHED; PG8_LDA(At, 1, 0); PG8_STAGE(PG8_SA(0, 1), a2 + hstepA, voffA);
;             PG8_WAIT_V(8); PG8_WAIT_L(0); PG8_BAR; PG8_MMA(0, 0, At, B0); PG8_MMA(0, 1, At, B1); PG8_BAR; PG8_SCHED;
	s_setprio 1
	v_mfma_f32_16x16x32_bf16 v[60:63], v[128:131], v[188:191], v[60:63]
	v_mfma_f32_16x16x32_bf16 v[56:59], v[136:139], v[188:191], v[56:59]
	v_mfma_f32_16x16x32_bf16 v[44:47], v[128:131], v[208:211], v[44:47]
	v_mfma_f32_16x16x32_bf16 v[40:43], v[136:139], v[208:211], v[40:43]
	v_mfma_f32_16x16x32_bf16 v[36:39], v[128:131], v[216:219], v[36:39]
	v_mfma_f32_16x16x32_bf16 v[32:35], v[136:139], v[216:219], v[32:35]
	v_mfma_f32_16x16x32_bf16 v[20:23], v[128:131], v[224:227], v[20:23]
	v_mfma_f32_16x16x32_bf16 v[16:19], v[136:139], v[224:227], v[16:19]
	v_mfma_f32_16x16x32_bf16 v[60:63], v[132:135], v[192:195], v[60:63]
	v_mfma_f32_16x16x32_bf16 v[56:59], v[140:143], v[192:195], v[56:59]
	v_mfma_f32_16x16x32_bf16 v[44:47], v[132:135], v[212:215], v[44:47]
	v_mfma_f32_16x16x32_bf16 v[40:43], v[140:143], v[212:215], v[40:43]
	v_mfma_f32_16x16x32_bf16 v[36:39], v[132:135], v[220:223], v[36:39]
	v_mfma_f32_16x16x32_bf16 v[32:35], v[140:143], v[220:223], v[32:35]
	v_mfma_f32_16x16x32_bf16 v[20:23], v[132:135], v[228:231], v[20:23]
	v_mfma_f32_16x16x32_bf16 v[16:19], v[140:143], v[228:231], v[16:19]
	s_setprio 0
	s_setprio 1
	v_mfma_f32_16x16x32_bf16 v[52:55], v[144:147], v[188:191], v[52:55]
	v_mfma_f32_16x16x32_bf16 v[48:51], v[152:155], v[188:191], v[48:51]
	v_mfma_f32_16x16x32_bf16 v[28:31], v[144:147], v[208:211], v[28:31]
	v_mfma_f32_16x16x32_bf16 v[24:27], v[152:155], v[208:211], v[24:27]
	v_mfma_f32_16x16x32_bf16 v[12:15], v[144:147], v[216:219], v[12:15]
	v_mfma_f32_16x16x32_bf16 v[8:11], v[152:155], v[216:219], v[8:11]
	v_mfma_f32_16x16x32_bf16 v[4:7], v[144:147], v[224:227], v[4:7]
	v_mfma_f32_16x16x32_bf16 v[0:3], v[152:155], v[224:227], v[0:3]
	v_mfma_f32_16x16x32_bf16 v[52:55], v[148:151], v[192:195], v[52:55]
	v_mfma_f32_16x16x32_bf16 v[48:51], v[156:159], v[192:195], v[48:51]
	v_mfma_f32_16x16x32_bf16 v[28:31], v[148:151], v[212:215], v[28:31]
	v_mfma_f32_16x16x32_bf16 v[24:27], v[156:159], v[212:215], v[24:27]
	v_mfma_f32_16x16x32_bf16 v[12:15], v[148:151], v[220:223], v[12:15]
	v_mfma_f32_16x16x32_bf16 v[8:11], v[156:159], v[220:223], v[8:11]
	v_mfma_f32_16x16x32_bf16 v[4:7], v[148:151], v[228:231], v[4:7]
	v_mfma_f32_16x16x32_bf16 v[0:3], v[156:159], v[228:231], v[0:3]
	s_setprio 0
	s_barrier
	s_add_i32 s61, 0, 0x18000
	s_add_i32 s62, 0, 0x1c000
	v_add_u32_e32 v140, s61, v198
	v_add_u32_e32 v156, s62, v198
	ds_read_b128 v[128:131], v140
	ds_read_b128 v[132:135], v140 offset:1024
	ds_read_b128 v[136:139], v140 offset:2048
	ds_read_b128 v[140:143], v140 offset:3072
	ds_read_b128 v[144:147], v156
	ds_read_b128 v[148:151], v156 offset:1024
	ds_read_b128 v[152:155], v156 offset:2048
	ds_read_b128 v[156:159], v156 offset:3072
	s_add_u32 s46, s46, 0x40000
	s_addc_u32 s47, s47, 0
	s_mov_b32 m0, s33
	v_lshl_add_u64 v[236:237], s[46:47], 0, v[160:161]
	ds_read_b128 v[188:191], v202 offset:32768
	ds_read_b128 v[192:195], v202 offset:33792
	ds_read_b128 v[208:211], v202 offset:34816
	ds_read_b128 v[212:215], v202 offset:35840
	ds_read_b128 v[216:219], v202 offset:36864
	ds_read_b128 v[220:223], v202 offset:37888
	ds_read_b128 v[224:227], v202 offset:38912
	ds_read_b128 v[228:231], v202 offset:39936
	global_load_lds_dwordx4 v[236:237], off
	v_lshl_add_u64 v[236:237], s[46:47], 0, v[162:163]
	s_mov_b32 m0, s50
	s_nop 0
	global_load_lds_dwordx4 v[236:237], off
	s_waitcnt vmcnt(8)
	s_waitcnt lgkmcnt(0)
	s_barrier
	s_setprio 1
	v_mfma_f32_16x16x32_bf16 v[124:127], v[128:131], v[188:191], v[124:127]
	v_mfma_f32_16x16x32_bf16 v[120:123], v[136:139], v[188:191], v[120:123]
	v_mfma_f32_16x16x32_bf16 v[116:119], v[128:131], v[208:211], v[116:119]
	v_mfma_f32_16x16x32_bf16 v[112:115], v[136:139], v[208:211], v[112:115]
	v_mfma_f32_16x16x32_bf16 v[92:95], v[128:131], v[216:219], v[92:95]
	v_mfma_f32_16x16x32_bf16 v[88:91], v[136:139], v[216:219], v[88:91]
	v_mfma_f32_16x16x32_bf16 v[76:79], v[128:131], v[224:227], v[76:79]
	v_mfma_f32_16x16x32_bf16 v[72:75], v[136:139], v[224:227], v[72:75]
	v_mfma_f32_16x16x32_bf16 v[124:127], v[132:135], v[192:195], v[124:127]
	v_mfma_f32_16x16x32_bf16 v[120:123], v[140:143], v[192:195], v[120:123]
	v_mfma_f32_16x16x32_bf16 v[116:119], v[132:135], v[212:215], v[116:119]
	v_mfma_f32_16x16x32_bf16 v[112:115], v[140:143], v[212:215], v[112:115]
	v_mfma_f32_16x16x32_bf16 v[92:95], v[132:135], v[220:223], v[92:95]
	v_mfma_f32_16x16x32_bf16 v[88:91], v[140:143], v[220:223], v[88:91]
	v_mfma_f32_16x16x32_bf16 v[76:79], v[132:135], v[228:231], v[76:79]
	v_mfma_f32_16x16x32_bf16 v[72:75], v[140:143], v[228:231], v[72:75]
	s_setprio 0
	s_setprio 1
	v_mfma_f32_16x16x32_bf16 v[108:111], v[144:147], v[188:191], v[108:111]
	v_mfma_f32_16x16x32_bf16 v[104:107], v[152:155], v[188:191], v[104:107]
	v_mfma_f32_16x16x32_bf16 v[100:103], v[144:147], v[208:211], v[100:103]
	v_mfma_f32_16x16x32_bf16 v[96:99], v[152:155], v[208:211], v[96:99]
	v_mfma_f32_16x16x32_bf16 v[84:87], v[144:147], v[216:219], v[84:87]
	v_mfma_f32_16x16x32_bf16 v[80:83], v[152:155], v[216:219], v[80:83]
	v_mfma_f32_16x16x32_bf16 v[68:71], v[144:147], v[224:227], v[68:71]
	v_mfma_f32_16x16x32_bf16 v[64:67], v[152:155], v[224:227], v[64:67]
	v_mfma_f32_16x16x32_bf16 v[108:111], v[148:151], v[192:195], v[108:111]
	v_mfma_f32_16x16x32_bf16 v[104:107], v[156:159], v[192:195], v[104:107]
	v_mfma_f32_16x16x32_bf16 v[100:103], v[148:151], v[212:215], v[100:103]
	v_mfma_f32_16x16x32_bf16 v[96:99], v[156:159], v[212:215], v[96:99]
	v_mfma_f32_16x16x32_bf16 v[84:87], v[148:151], v[220:223], v[84:87]
	v_mfma_f32_16x16x32_bf16 v[80:83], v[156:159], v[220:223], v[80:83]
	v_mfma_f32_16x16x32_bf16 v[68:71], v[148:151], v[228:231], v[68:71]
	v_mfma_f32_16x16x32_bf16 v[64:67], v[156:159], v[228:231], v[64:67]
	s_setprio 0
	s_barrier
; #define PG8_STAGE(bufoff, gbase, voff) do { _Pragma("unroll") for (int _i = 0; _i < 2; ++_i) \
;         __builtin_amdgcn_global_load_lds((const unsigned*)((const char*)(gbase) + (voff)[_i]), (LAS unsigned*)(lds + (bufoff) + ldsw + _i * 8192), 16, 0, 0); } while (0)
; #define PG8_LDA(dst, b, h) do { _Pragma("unroll") for (int m = 0; m < 4; ++m) _Pragma("unroll") for (int k = 0; k < 2; ++k) dst[m][k] = *(const LAS bf16x8*)(lds + PG8_SA(b, h) + aoff + m * 2048 + k * 1024); } while (0)
; #define PG8_WAIT_V(n) asm volatile("s_waitcnt vmcnt(" #n ")" ::: "memory")
; #define PG8_WAIT_L(n) asm volatile("s_waitcnt lgkmcnt(" #n ")" ::: "memory")
; #define PG8_BAR __builtin_amdgcn_s_barrier()
; #define PG8_SCHED __builtin_amdgcn_sched_barrier(0)
; template <class Epi, class Sched, bool SWAPD = false>
; __device__ __forceinline__ void gemm_phase(LAS unsigned char* lds, const Gemm g, const Sched& S, const Epi& E) {
;     ...
;             PG8_LDA(At, 1, 1); PG8_STAGE(PG8_SB(1, 0), b3, voffB); PG8_STAGE(PG8_SB(1, 1), b3 + hstepB, voffB); PG8_STAGE(PG8_SA(1, 0), a3, voffA);
;             PG8_WAIT_V(8); PG8_WAIT_L(0); PG8_BAR; PG8_MMA(1, 0, At, B0); PG8_MMA(1, 1, At, B1); PG8_BAR; PG8_SCHED;
;         }
;         if (wr == 0) PG8_BAR;
	s_add_i32 s46, s61, s21
	v_lshl_add_u64 v[196:197], v[196:197], 0, s[10:11]
	s_mov_b32 m0, s46
	ds_read_b128 v[188:191], v202 offset:49152
	ds_read_b128 v[192:195], v202 offset:50176
	ds_read_b128 v[208:211], v202 offset:51200
	ds_read_b128 v[212:215], v202 offset:52224
	ds_read_b128 v[216:219], v202 offset:53248
	ds_read_b128 v[220:223], v202 offset:54272
	ds_read_b128 v[224:227], v202 offset:55296
	ds_read_b128 v[228:231], v202 offset:56320
	global_load_lds_dwordx4 v[196:197], off
	s_add_i32 m0, s46, 0x2000
	s_add_u32 s44, s44, 0x40080
	v_lshl_add_u64 v[196:197], v[204:205], 0, s[10:11]
	s_addc_u32 s45, s45, 0
	s_add_i32 s46, s62, s21
	global_load_lds_dwordx4 v[196:197], off
	v_lshl_add_u64 v[196:197], s[44:45], 0, v[160:161]
	s_mov_b32 m0, s46
	s_nop 0
	global_load_lds_dwordx4 v[196:197], off
	v_lshl_add_u64 v[196:197], s[44:45], 0, v[162:163]
	s_add_i32 m0, s46, 0x2000
	s_nop 0
	global_load_lds_dwordx4 v[196:197], off
	v_lshl_add_u64 v[196:197], v[232:233], 0, s[10:11]
	s_mov_b32 m0, s54
	s_nop 0
	global_load_lds_dwordx4 v[196:197], off
	v_lshl_add_u64 v[196:197], v[234:235], 0, s[10:11]
	s_mov_b32 m0, s55
	s_nop 0
	global_load_lds_dwordx4 v[196:197], off
	s_waitcnt vmcnt(8)
	s_waitcnt lgkmcnt(0)
	s_barrier
	s_setprio 1
	v_mfma_f32_16x16x32_bf16 v[60:63], v[128:131], v[188:191], v[60:63]
	v_mfma_f32_16x16x32_bf16 v[56:59], v[136:139], v[188:191], v[56:59]
	v_mfma_f32_16x16x32_bf16 v[44:47], v[128:131], v[208:211], v[44:47]
	v_mfma_f32_16x16x32_bf16 v[40:43], v[136:139], v[208:211], v[40:43]
	v_mfma_f32_16x16x32_bf16 v[36:39], v[128:131], v[216:219], v[36:39]
	v_mfma_f32_16x16x32_bf16 v[32:35], v[136:139], v[216:219], v[32:35]
	v_mfma_f32_16x16x32_bf16 v[20:23], v[128:131], v[224:227], v[20:23]
	v_mfma_f32_16x16x32_bf16 v[16:19], v[136:139], v[224:227], v[16:19]
	v_mfma_f32_16x16x32_bf16 v[60:63], v[132:135], v[192:195], v[60:63]
	v_mfma_f32_16x16x32_bf16 v[56:59], v[140:143], v[192:195], v[56:59]
	v_mfma_f32_16x16x32_bf16 v[44:47], v[132:135], v[212:215], v[44:47]
	v_mfma_f32_16x16x32_bf16 v[40:43], v[140:143], v[212:215], v[40:43]
	v_mfma_f32_16x16x32_bf16 v[36:39], v[132:135], v[220:223], v[36:39]
	v_mfma_f32_16x16x32_bf16 v[32:35], v[140:143], v[220:223], v[32:35]
	v_mfma_f32_16x16x32_bf16 v[20:23], v[132:135], v[228:231], v[20:23]
	v_mfma_f32_16x16x32_bf16 v[16:19], v[140:143], v[228:231], v[16:19]
	s_setprio 0
	s_setprio 1
	v_mfma_f32_16x16x32_bf16 v[52:55], v[144:147], v[188:191], v[52:55]
	v_mfma_f32_16x16x32_bf16 v[48:51], v[152:155], v[188:191], v[48:51]
	v_mfma_f32_16x16x32_bf16 v[28:31], v[144:147], v[208:211], v[28:31]
	v_mfma_f32_16x16x32_bf16 v[24:27], v[152:155], v[208:211], v[24:27]
	v_mfma_f32_16x16x32_bf16 v[12:15], v[144:147], v[216:219], v[12:15]
	v_mfma_f32_16x16x32_bf16 v[8:11], v[152:155], v[216:219], v[8:11]
	v_mfma_f32_16x16x32_bf16 v[4:7], v[144:147], v[224:227], v[4:7]
	v_mfma_f32_16x16x32_bf16 v[0:3], v[152:155], v[224:227], v[0:3]
	v_mfma_f32_16x16x32_bf16 v[52:55], v[148:151], v[192:195], v[52:55]
	v_mfma_f32_16x16x32_bf16 v[48:51], v[156:159], v[192:195], v[48:51]
	v_mfma_f32_16x16x32_bf16 v[28:31], v[148:151], v[212:215], v[28:31]
	v_mfma_f32_16x16x32_bf16 v[24:27], v[156:159], v[212:215], v[24:27]
	v_mfma_f32_16x16x32_bf16 v[12:15], v[148:151], v[220:223], v[12:15]
	v_mfma_f32_16x16x32_bf16 v[8:11], v[156:159], v[220:223], v[8:11]
	v_mfma_f32_16x16x32_bf16 v[4:7], v[148:151], v[228:231], v[4:7]
	v_mfma_f32_16x16x32_bf16 v[0:3], v[156:159], v[228:231], v[0:3]
	s_setprio 0
	s_barrier
	s_add_i32 s60, s60, 2
	s_add_u32 s42, s42, 0x100
	s_addc_u32 s43, s43, 0
	s_add_u32 s58, s58, 0x100
	s_addc_u32 s59, s59, 0
	s_cmp_gt_u32 s60, 13
	s_cbranch_scc0 .LBB0_918
	s_and_b64 vcc, exec, s[12:13]
	s_cbranch_vccz .LBB0_921
	s_barrier

; #define PG8_STAGE(bufoff, gbase, voff) do { _Pragma("unroll") for (int _i = 0; _i < 2; ++_i) \
;         __builtin_amdgcn_global_load_lds((const unsigned*)((const char*)(gbase) + (voff)[_i]), (LAS unsigned*)(lds + (bufoff) + ldsw + _i * 8192), 16, 0, 0); } while (0)
; #define PG8_LDA(dst, b, h) do { _Pragma("unroll") for (int m = 0; m < 4; ++m) _Pragma("unroll") for (int k = 0; k < 2; ++k) dst[m][k] = *(const LAS bf16x8*)(lds + PG8_SA(b, h) + aoff + m * 2048 + k * 1024); } while (0)
; #define PG8_LDB(dst, b, h) do { _Pragma("unroll") for (int n = 0; n < 2; ++n) _Pragma("unroll") for (int k = 0; k < 2; ++k) dst[n][k] = *(const LAS bf16x8*)(lds + PG8_SB(b, h) + boff + n * 2048 + k * 1024); } while (0)
; #define PG8_WAIT_V(n) asm volatile("s_waitcnt vmcnt(" #n ")" ::: "memory")
; #define PG8_WAIT_L(n) asm volatile("s_waitcnt lgkmcnt(" #n ")" ::: "memory")
; #define PG8_BAR __builtin_amdgcn_s_barrier()
; #define PG8_SCHED __builtin_amdgcn_sched_barrier(0)
; template <class Epi, class Sched, bool SWAPD = false>
; __device__ __forceinline__ void gemm_phase(LAS unsigned char* lds, const Gemm g, const Sched& S, const Epi& E) {
;     ...
;         const bool has_next = S.next(ui + 1, nxt);
;         const char* nA = has_next ? (const char*)g.A + nxt.aoff : cA; const char* nB = has_next ? (const char*)g.Bt + nxt.boff : cB;
;         const int nt = cur.nt ? cur.nt : ntK;
;         for (int t = 0; t < nt; t += 2) {
;             const bool last = (t == nt - 2);
;             const char* a1 = cA + (size_t)(t + 1) * kstepA;
;             const char* a2 = last ? nA : cA + (size_t)(t + 2) * kstepA; const char* b2 = last ? nB : cB + (size_t)(t + 2) * kstep;
;             const char* a3 = a2 + kstepA; const char* b3 = b2 + kstep;
;             PG8_LDB(B0, 0, 0); PG8_LDB(B1, 0, 1); PG8_SCHED; PG8_LDA(At, 0, 0); PG8_STAGE(PG8_SA(1, 1), a1 + hstepA, voffA);
;             PG8_WAIT_V(8); PG8_WAIT_L(0); PG8_BAR; PG8_MMA(0, 0, At, B0); PG8_MMA(0, 1, At, B1); PG8_BAR; PG8_SCHED;
;             PG8_LDA(At, 0, 1); PG8_STAGE(PG8_SB(0, 0), b2, voffB); PG8_STAGE(PG8_SB(0, 1), b2 + hstepB, voffB); PG8_STAGE(PG8_SA(0, 0), a2, voffA);
;             PG8_WAIT_V(8); PG8_WAIT_L(0); PG8_BAR; PG8_MMA(1, 0, At, B0); PG8_MMA(1, 1, At, B1); PG8_BAR; PG8_SCHED;
.LBB0_1044:
	ds_read_b128 v[148:151], v145
	ds_read_b128 v[152:155], v145 offset:1024
	ds_read_b128 v[156:159], v145 offset:2048
	ds_read_b128 v[160:163], v145 offset:3072
	ds_read_b128 v[164:167], v146
	ds_read_b128 v[168:171], v146 offset:1024
	ds_read_b128 v[172:175], v146 offset:2048
	ds_read_b128 v[176:179], v146 offset:3072
	s_add_u32 s44, s42, 0xfffc0080
	s_addc_u32 s45, s43, -1
	s_cmp_eq_u32 s63, 12
	s_cselect_b32 s47, s25, s45
	s_cselect_b32 s46, s27, s44
	s_cselect_b32 s45, s59, s62
	s_cselect_b32 s44, s60, s61
	v_lshl_add_u64 v[140:141], s[42:43], 0, v[132:133]
	s_add_i32 m0, s33, 0xc000
	ds_read_b128 v[180:183], v147
	ds_read_b128 v[184:187], v147 offset:1024
	ds_read_b128 v[188:191], v147 offset:2048
	ds_read_b128 v[192:195], v147 offset:3072
	ds_read_b128 v[196:199], v147 offset:4096
	ds_read_b128 v[200:203], v147 offset:5120
	ds_read_b128 v[208:211], v147 offset:6144
	ds_read_b128 v[212:215], v147 offset:7168
	global_load_lds_dwordx4 v[140:141], off
	v_lshl_add_u64 v[140:141], s[42:43], 0, v[134:135]
	s_add_i32 m0, s33, 0xe000
	s_nop 0
	global_load_lds_dwordx4 v[140:141], off
	s_waitcnt vmcnt(8)
	s_waitcnt lgkmcnt(0)
	s_barrier
	s_setprio 1
	v_mfma_f32_16x16x32_bf16 v[124:127], v[148:151], v[180:183], v[124:127]
	v_mfma_f32_16x16x32_bf16 v[116:119], v[156:159], v[180:183], v[116:119]
	v_mfma_f32_16x16x32_bf16 v[108:111], v[148:151], v[188:191], v[108:111]
	v_mfma_f32_16x16x32_bf16 v[100:103], v[156:159], v[188:191], v[100:103]
	v_mfma_f32_16x16x32_bf16 v[92:95], v[148:151], v[196:199], v[92:95]
	v_mfma_f32_16x16x32_bf16 v[84:87], v[156:159], v[196:199], v[84:87]
	v_mfma_f32_16x16x32_bf16 v[76:79], v[148:151], v[208:211], v[76:79]
	v_mfma_f32_16x16x32_bf16 v[68:71], v[156:159], v[208:211], v[68:71]
	v_mfma_f32_16x16x32_bf16 v[124:127], v[152:155], v[184:187], v[124:127]
	v_mfma_f32_16x16x32_bf16 v[116:119], v[160:163], v[184:187], v[116:119]
	v_mfma_f32_16x16x32_bf16 v[108:111], v[152:155], v[192:195], v[108:111]
	v_mfma_f32_16x16x32_bf16 v[100:103], v[160:163], v[192:195], v[100:103]
	v_mfma_f32_16x16x32_bf16 v[92:95], v[152:155], v[200:203], v[92:95]
	v_mfma_f32_16x16x32_bf16 v[84:87], v[160:163], v[200:203], v[84:87]
	v_mfma_f32_16x16x32_bf16 v[76:79], v[152:155], v[212:215], v[76:79]
	v_mfma_f32_16x16x32_bf16 v[68:71], v[160:163], v[212:215], v[68:71]
	s_setprio 0
	s_setprio 1
	v_mfma_f32_16x16x32_bf16 v[120:123], v[164:167], v[180:183], v[120:123]
	v_mfma_f32_16x16x32_bf16 v[112:115], v[172:175], v[180:183], v[112:115]
	v_mfma_f32_16x16x32_bf16 v[104:107], v[164:167], v[188:191], v[104:107]
	v_mfma_f32_16x16x32_bf16 v[96:99], v[172:175], v[188:191], v[96:99]
	v_mfma_f32_16x16x32_bf16 v[88:91], v[164:167], v[196:199], v[88:91]
	v_mfma_f32_16x16x32_bf16 v[80:83], v[172:175], v[196:199], v[80:83]
	v_mfma_f32_16x16x32_bf16 v[72:75], v[164:167], v[208:211], v[72:75]
	v_mfma_f32_16x16x32_bf16 v[64:67], v[172:175], v[208:211], v[64:67]
	v_mfma_f32_16x16x32_bf16 v[120:123], v[168:171], v[184:187], v[120:123]
	v_mfma_f32_16x16x32_bf16 v[112:115], v[176:179], v[184:187], v[112:115]
	v_mfma_f32_16x16x32_bf16 v[104:107], v[168:171], v[192:195], v[104:107]
	v_mfma_f32_16x16x32_bf16 v[96:99], v[176:179], v[192:195], v[96:99]
	v_mfma_f32_16x16x32_bf16 v[88:91], v[168:171], v[200:203], v[88:91]
	v_mfma_f32_16x16x32_bf16 v[80:83], v[176:179], v[200:203], v[80:83]
	v_mfma_f32_16x16x32_bf16 v[72:75], v[168:171], v[212:215], v[72:75]
	v_mfma_f32_16x16x32_bf16 v[64:67], v[176:179], v[212:215], v[64:67]
	s_setprio 0
	s_barrier
	s_add_i32 s64, s55, s30
	v_lshl_add_u64 v[140:141], s[44:45], 0, v[130:131]
	s_mov_b32 m0, s64
	ds_read_b128 v[180:183], v147 offset:16384
	ds_read_b128 v[184:187], v147 offset:17408
	ds_read_b128 v[188:191], v147 offset:18432
	ds_read_b128 v[192:195], v147 offset:19456
	ds_read_b128 v[196:199], v147 offset:20480
	ds_read_b128 v[200:203], v147 offset:21504
	ds_read_b128 v[208:211], v147 offset:22528
	ds_read_b128 v[212:215], v147 offset:23552
	global_load_lds_dwordx4 v[140:141], off
	s_add_i32 m0, s64, 0x2000
	s_add_u32 s64, s44, 0x40000
	v_lshl_add_u64 v[204:205], s[44:45], 0, v[128:129]
	s_addc_u32 s65, s45, 0
	s_add_i32 s66, s56, s30
	global_load_lds_dwordx4 v[204:205], off
	v_lshl_add_u64 v[216:217], s[64:65], 0, v[130:131]
	s_mov_b32 m0, s66
	v_lshl_add_u64 v[218:219], s[46:47], 0, v[128:129]
	global_load_lds_dwordx4 v[216:217], off
	v_lshl_add_u64 v[216:217], s[64:65], 0, v[128:129]
	s_add_i32 m0, s66, 0x2000
	s_nop 0
	global_load_lds_dwordx4 v[216:217], off
	v_lshl_add_u64 v[216:217], s[46:47], 0, v[130:131]
	s_mov_b32 m0, s33
	s_nop 0
	global_load_lds_dwordx4 v[216:217], off
	s_mov_b32 m0, s41
	s_nop 0
	global_load_lds_dwordx4 v[218:219], off
	s_waitcnt vmcnt(8)
	s_waitcnt lgkmcnt(0)
	s_barrier
; #define PG8_STAGE(bufoff, gbase, voff) do { _Pragma("unroll") for (int _i = 0; _i < 2; ++_i) \
;         __builtin_amdgcn_global_load_lds((const unsigned*)((const char*)(gbase) + (voff)[_i]), (LAS unsigned*)(lds + (bufoff) + ldsw + _i * 8192), 16, 0, 0); } while (0)
; #define PG8_LDA(dst, b, h) do { _Pragma("unroll") for (int m = 0; m < 4; ++m) _Pragma("unroll") for (int k = 0; k < 2; ++k) dst[m][k] = *(const LAS bf16x8*)(lds + PG8_SA(b, h) + aoff + m * 2048 + k * 1024); } while (0)
; #define PG8_LDB(dst, b, h) do { _Pragma("unroll") for (int n = 0; n < 2; ++n) _Pragma("unroll") for (int k = 0; k < 2; ++k) dst[n][k] = *(const LAS bf16x8*)(lds + PG8_SB(b, h) + boff + n * 2048 + k * 1024); } while (0)
; #define PG8_WAIT_V(n) asm volatile("s_waitcnt vmcnt(" #n ")" ::: "memory")
; #define PG8_WAIT_L(n) asm volatile("s_waitcnt lgkmcnt(" #n ")" ::: "memory")
; #define PG8_BAR __builtin_amdgcn_s_barrier()
; #define PG8_SCHED __builtin_amdgcn_sched_barrier(0)
; template <class Epi, class Sched, bool SWAPD = false>
; __device__ __forceinline__ void gemm_phase(LAS unsigned char* lds, const Gemm g, const Sched& S, const Epi& E) {
;     ...
;             PG8_WAIT_V(8); PG8_WAIT_L(0); PG8_BAR; PG8_MMA(1, 0, At, B0); PG8_MMA(1, 1, At, B1); PG8_BAR; PG8_SCHED;
;             PG8_LDB(B0, 1, 0); PG8_LDB(B1, 1, 1); PG8_SCHED; PG8_LDA(At, 1, 0); PG8_STAGE(PG8_SA(0, 1), a2 + hstepA, voffA);
;             PG8_WAIT_V(8); PG8_WAIT_L(0); PG8_BAR; PG8_MMA(0, 0, At, B0); PG8_MMA(0, 1, At, B1); PG8_BAR; PG8_SCHED;
	s_setprio 1
	v_mfma_f32_16x16x32_bf16 v[60:63], v[148:151], v[180:183], v[60:63]
	v_mfma_f32_16x16x32_bf16 v[52:55], v[156:159], v[180:183], v[52:55]
	v_mfma_f32_16x16x32_bf16 v[44:47], v[148:151], v[188:191], v[44:47]
	v_mfma_f32_16x16x32_bf16 v[36:39], v[156:159], v[188:191], v[36:39]
	v_mfma_f32_16x16x32_bf16 v[28:31], v[148:151], v[196:199], v[28:31]
	v_mfma_f32_16x16x32_bf16 v[20:23], v[156:159], v[196:199], v[20:23]
	v_mfma_f32_16x16x32_bf16 v[12:15], v[148:151], v[208:211], v[12:15]
	v_mfma_f32_16x16x32_bf16 v[4:7], v[156:159], v[208:211], v[4:7]
	v_mfma_f32_16x16x32_bf16 v[60:63], v[152:155], v[184:187], v[60:63]
	v_mfma_f32_16x16x32_bf16 v[52:55], v[160:163], v[184:187], v[52:55]
	v_mfma_f32_16x16x32_bf16 v[44:47], v[152:155], v[192:195], v[44:47]
	v_mfma_f32_16x16x32_bf16 v[36:39], v[160:163], v[192:195], v[36:39]
	v_mfma_f32_16x16x32_bf16 v[28:31], v[152:155], v[200:203], v[28:31]
	v_mfma_f32_16x16x32_bf16 v[20:23], v[160:163], v[200:203], v[20:23]
	v_mfma_f32_16x16x32_bf16 v[12:15], v[152:155], v[212:215], v[12:15]
	v_mfma_f32_16x16x32_bf16 v[4:7], v[160:163], v[212:215], v[4:7]
	s_setprio 0
	s_setprio 1
	v_mfma_f32_16x16x32_bf16 v[56:59], v[164:167], v[180:183], v[56:59]
	v_mfma_f32_16x16x32_bf16 v[48:51], v[172:175], v[180:183], v[48:51]
	v_mfma_f32_16x16x32_bf16 v[40:43], v[164:167], v[188:191], v[40:43]
	v_mfma_f32_16x16x32_bf16 v[32:35], v[172:175], v[188:191], v[32:35]
	v_mfma_f32_16x16x32_bf16 v[24:27], v[164:167], v[196:199], v[24:27]
	v_mfma_f32_16x16x32_bf16 v[16:19], v[172:175], v[196:199], v[16:19]
	v_mfma_f32_16x16x32_bf16 v[8:11], v[164:167], v[208:211], v[8:11]
	v_mfma_f32_16x16x32_bf16 v[0:3], v[172:175], v[208:211], v[0:3]
	v_mfma_f32_16x16x32_bf16 v[56:59], v[168:171], v[184:187], v[56:59]
	v_mfma_f32_16x16x32_bf16 v[48:51], v[176:179], v[184:187], v[48:51]
	v_mfma_f32_16x16x32_bf16 v[40:43], v[168:171], v[192:195], v[40:43]
	v_mfma_f32_16x16x32_bf16 v[32:35], v[176:179], v[192:195], v[32:35]
	v_mfma_f32_16x16x32_bf16 v[24:27], v[168:171], v[200:203], v[24:27]
	v_mfma_f32_16x16x32_bf16 v[16:19], v[176:179], v[200:203], v[16:19]
	v_mfma_f32_16x16x32_bf16 v[8:11], v[168:171], v[212:215], v[8:11]
	v_mfma_f32_16x16x32_bf16 v[0:3], v[176:179], v[212:215], v[0:3]
	s_setprio 0
	s_barrier
	s_add_i32 s64, 0, 0x18000
	s_add_i32 s65, 0, 0x1c000
	v_add_u32_e32 v160, s64, v143
	v_add_u32_e32 v176, s65, v143
	ds_read_b128 v[148:151], v160
	ds_read_b128 v[152:155], v160 offset:1024
	ds_read_b128 v[156:159], v160 offset:2048
	ds_read_b128 v[160:163], v160 offset:3072
	ds_read_b128 v[164:167], v176
	ds_read_b128 v[168:171], v176 offset:1024
	ds_read_b128 v[172:175], v176 offset:2048
	ds_read_b128 v[176:179], v176 offset:3072
	s_add_u32 s46, s46, 0x40000
	s_addc_u32 s47, s47, 0
	s_mov_b32 m0, s50
	v_lshl_add_u64 v[220:221], s[46:47], 0, v[130:131]
	ds_read_b128 v[180:183], v147 offset:32768
	ds_read_b128 v[184:187], v147 offset:33792
	ds_read_b128 v[188:191], v147 offset:34816
	ds_read_b128 v[192:195], v147 offset:35840
	ds_read_b128 v[196:199], v147 offset:36864
	ds_read_b128 v[200:203], v147 offset:37888
	ds_read_b128 v[208:211], v147 offset:38912
	ds_read_b128 v[212:215], v147 offset:39936
	global_load_lds_dwordx4 v[220:221], off
	v_lshl_add_u64 v[220:221], s[46:47], 0, v[128:129]
	s_mov_b32 m0, s51
	s_nop 0
	global_load_lds_dwordx4 v[220:221], off
	s_waitcnt vmcnt(8)
	s_waitcnt lgkmcnt(0)
	s_barrier
	s_setprio 1
	v_mfma_f32_16x16x32_bf16 v[124:127], v[148:151], v[180:183], v[124:127]
	v_mfma_f32_16x16x32_bf16 v[116:119], v[156:159], v[180:183], v[116:119]
	v_mfma_f32_16x16x32_bf16 v[108:111], v[148:151], v[188:191], v[108:111]
	v_mfma_f32_16x16x32_bf16 v[100:103], v[156:159], v[188:191], v[100:103]
	v_mfma_f32_16x16x32_bf16 v[92:95], v[148:151], v[196:199], v[92:95]
	v_mfma_f32_16x16x32_bf16 v[84:87], v[156:159], v[196:199], v[84:87]
	v_mfma_f32_16x16x32_bf16 v[76:79], v[148:151], v[208:211], v[76:79]
	v_mfma_f32_16x16x32_bf16 v[68:71], v[156:159], v[208:211], v[68:71]
	v_mfma_f32_16x16x32_bf16 v[124:127], v[152:155], v[184:187], v[124:127]
	v_mfma_f32_16x16x32_bf16 v[116:119], v[160:163], v[184:187], v[116:119]
	v_mfma_f32_16x16x32_bf16 v[108:111], v[152:155], v[192:195], v[108:111]
	v_mfma_f32_16x16x32_bf16 v[100:103], v[160:163], v[192:195], v[100:103]
	v_mfma_f32_16x16x32_bf16 v[92:95], v[152:155], v[200:203], v[92:95]
	v_mfma_f32_16x16x32_bf16 v[84:87], v[160:163], v[200:203], v[84:87]
	v_mfma_f32_16x16x32_bf16 v[76:79], v[152:155], v[212:215], v[76:79]
	v_mfma_f32_16x16x32_bf16 v[68:71], v[160:163], v[212:215], v[68:71]
	s_setprio 0
	s_setprio 1
	v_mfma_f32_16x16x32_bf16 v[120:123], v[164:167], v[180:183], v[120:123]
	v_mfma_f32_16x16x32_bf16 v[112:115], v[172:175], v[180:183], v[112:115]
	v_mfma_f32_16x16x32_bf16 v[104:107], v[164:167], v[188:191], v[104:107]
	v_mfma_f32_16x16x32_bf16 v[96:99], v[172:175], v[188:191], v[96:99]
	v_mfma_f32_16x16x32_bf16 v[88:91], v[164:167], v[196:199], v[88:91]
	v_mfma_f32_16x16x32_bf16 v[80:83], v[172:175], v[196:199], v[80:83]
	v_mfma_f32_16x16x32_bf16 v[72:75], v[164:167], v[208:211], v[72:75]
	v_mfma_f32_16x16x32_bf16 v[64:67], v[172:175], v[208:211], v[64:67]
	v_mfma_f32_16x16x32_bf16 v[120:123], v[168:171], v[184:187], v[120:123]
	v_mfma_f32_16x16x32_bf16 v[112:115], v[176:179], v[184:187], v[112:115]
	v_mfma_f32_16x16x32_bf16 v[104:107], v[168:171], v[192:195], v[104:107]
	v_mfma_f32_16x16x32_bf16 v[96:99], v[176:179], v[192:195], v[96:99]
	v_mfma_f32_16x16x32_bf16 v[88:91], v[168:171], v[200:203], v[88:91]
	v_mfma_f32_16x16x32_bf16 v[80:83], v[176:179], v[200:203], v[80:83]
	v_mfma_f32_16x16x32_bf16 v[72:75], v[168:171], v[212:215], v[72:75]
	v_mfma_f32_16x16x32_bf16 v[64:67], v[176:179], v[212:215], v[64:67]
	s_setprio 0
	s_barrier
; #define PG8_STAGE(bufoff, gbase, voff) do { _Pragma("unroll") for (int _i = 0; _i < 2; ++_i) \
;         __builtin_amdgcn_global_load_lds((const unsigned*)((const char*)(gbase) + (voff)[_i]), (LAS unsigned*)(lds + (bufoff) + ldsw + _i * 8192), 16, 0, 0); } while (0)
; #define PG8_LDA(dst, b, h) do { _Pragma("unroll") for (int m = 0; m < 4; ++m) _Pragma("unroll") for (int k = 0; k < 2; ++k) dst[m][k] = *(const LAS bf16x8*)(lds + PG8_SA(b, h) + aoff + m * 2048 + k * 1024); } while (0)
; #define PG8_WAIT_V(n) asm volatile("s_waitcnt vmcnt(" #n ")" ::: "memory")
; #define PG8_WAIT_L(n) asm volatile("s_waitcnt lgkmcnt(" #n ")" ::: "memory")
; #define PG8_BAR __builtin_amdgcn_s_barrier()
; #define PG8_SCHED __builtin_amdgcn_sched_barrier(0)
; template <class Epi, class Sched, bool SWAPD = false>
; __device__ __forceinline__ void gemm_phase(LAS unsigned char* lds, const Gemm g, const Sched& S, const Epi& E) {
;     ...
;             PG8_LDA(At, 1, 1); PG8_STAGE(PG8_SB(1, 0), b3, voffB); PG8_STAGE(PG8_SB(1, 1), b3 + hstepB, voffB); PG8_STAGE(PG8_SA(1, 0), a3, voffA);
;             PG8_WAIT_V(8); PG8_WAIT_L(0); PG8_BAR; PG8_MMA(1, 0, At, B0); PG8_MMA(1, 1, At, B1); PG8_BAR; PG8_SCHED;
;         }
;         if (wr == 0) PG8_BAR;
	s_add_i32 s46, s64, s30
	v_lshl_add_u64 v[140:141], v[140:141], 0, s[8:9]
	s_mov_b32 m0, s46
	ds_read_b128 v[180:183], v147 offset:49152
	ds_read_b128 v[184:187], v147 offset:50176
	ds_read_b128 v[188:191], v147 offset:51200
	ds_read_b128 v[192:195], v147 offset:52224
	ds_read_b128 v[196:199], v147 offset:53248
	ds_read_b128 v[200:203], v147 offset:54272
	ds_read_b128 v[208:211], v147 offset:55296
	ds_read_b128 v[212:215], v147 offset:56320
	global_load_lds_dwordx4 v[140:141], off
	s_add_i32 m0, s46, 0x2000
	s_add_u32 s44, s44, 0x40080
	v_lshl_add_u64 v[140:141], v[204:205], 0, s[8:9]
	s_addc_u32 s45, s45, 0
	s_add_i32 s46, s65, s30
	global_load_lds_dwordx4 v[140:141], off
	v_lshl_add_u64 v[140:141], s[44:45], 0, v[130:131]
	s_mov_b32 m0, s46
	s_nop 0
	global_load_lds_dwordx4 v[140:141], off
	v_lshl_add_u64 v[140:141], s[44:45], 0, v[128:129]
	s_add_i32 m0, s46, 0x2000
	s_nop 0
	global_load_lds_dwordx4 v[140:141], off
	v_lshl_add_u64 v[140:141], v[216:217], 0, s[8:9]
	s_mov_b32 m0, s53
	s_nop 0
	global_load_lds_dwordx4 v[140:141], off
	v_lshl_add_u64 v[140:141], v[218:219], 0, s[8:9]
	s_mov_b32 m0, s54
	s_nop 0
	global_load_lds_dwordx4 v[140:141], off
	s_waitcnt vmcnt(8)
	s_waitcnt lgkmcnt(0)
	s_barrier
	s_setprio 1
	v_mfma_f32_16x16x32_bf16 v[60:63], v[148:151], v[180:183], v[60:63]
	v_mfma_f32_16x16x32_bf16 v[52:55], v[156:159], v[180:183], v[52:55]
	v_mfma_f32_16x16x32_bf16 v[44:47], v[148:151], v[188:191], v[44:47]
	v_mfma_f32_16x16x32_bf16 v[36:39], v[156:159], v[188:191], v[36:39]
	v_mfma_f32_16x16x32_bf16 v[28:31], v[148:151], v[196:199], v[28:31]
	v_mfma_f32_16x16x32_bf16 v[20:23], v[156:159], v[196:199], v[20:23]
	v_mfma_f32_16x16x32_bf16 v[12:15], v[148:151], v[208:211], v[12:15]
	v_mfma_f32_16x16x32_bf16 v[4:7], v[156:159], v[208:211], v[4:7]
	v_mfma_f32_16x16x32_bf16 v[60:63], v[152:155], v[184:187], v[60:63]
	v_mfma_f32_16x16x32_bf16 v[52:55], v[160:163], v[184:187], v[52:55]
	v_mfma_f32_16x16x32_bf16 v[44:47], v[152:155], v[192:195], v[44:47]
	v_mfma_f32_16x16x32_bf16 v[36:39], v[160:163], v[192:195], v[36:39]
	v_mfma_f32_16x16x32_bf16 v[28:31], v[152:155], v[200:203], v[28:31]
	v_mfma_f32_16x16x32_bf16 v[20:23], v[160:163], v[200:203], v[20:23]
	v_mfma_f32_16x16x32_bf16 v[12:15], v[152:155], v[212:215], v[12:15]
	v_mfma_f32_16x16x32_bf16 v[4:7], v[160:163], v[212:215], v[4:7]
	s_setprio 0
	s_setprio 1
	v_mfma_f32_16x16x32_bf16 v[56:59], v[164:167], v[180:183], v[56:59]
	v_mfma_f32_16x16x32_bf16 v[48:51], v[172:175], v[180:183], v[48:51]
	v_mfma_f32_16x16x32_bf16 v[40:43], v[164:167], v[188:191], v[40:43]
	v_mfma_f32_16x16x32_bf16 v[32:35], v[172:175], v[188:191], v[32:35]
	v_mfma_f32_16x16x32_bf16 v[24:27], v[164:167], v[196:199], v[24:27]
	v_mfma_f32_16x16x32_bf16 v[16:19], v[172:175], v[196:199], v[16:19]
	v_mfma_f32_16x16x32_bf16 v[8:11], v[164:167], v[208:211], v[8:11]
	v_mfma_f32_16x16x32_bf16 v[0:3], v[172:175], v[208:211], v[0:3]
	v_mfma_f32_16x16x32_bf16 v[56:59], v[168:171], v[184:187], v[56:59]
	v_mfma_f32_16x16x32_bf16 v[48:51], v[176:179], v[184:187], v[48:51]
	v_mfma_f32_16x16x32_bf16 v[40:43], v[168:171], v[192:195], v[40:43]
	v_mfma_f32_16x16x32_bf16 v[32:35], v[176:179], v[192:195], v[32:35]
	v_mfma_f32_16x16x32_bf16 v[24:27], v[168:171], v[200:203], v[24:27]
	v_mfma_f32_16x16x32_bf16 v[16:19], v[176:179], v[200:203], v[16:19]
	v_mfma_f32_16x16x32_bf16 v[8:11], v[168:171], v[212:215], v[8:11]
	v_mfma_f32_16x16x32_bf16 v[0:3], v[176:179], v[212:215], v[0:3]
	s_setprio 0
	s_barrier
	s_add_i32 s63, s63, 2
	s_add_u32 s42, s42, 0x100
	s_addc_u32 s43, s43, 0
	s_add_u32 s61, s61, 0x100
	s_addc_u32 s62, s62, 0
	s_cmp_gt_u32 s63, 13
	s_cbranch_scc0 .LBB0_1044
	s_and_b64 vcc, exec, s[12:13]
	s_cbranch_vccz .LBB0_1047
	s_barrier

; #define PG8_STAGE(bufoff, gbase, voff) do { _Pragma("unroll") for (int _i = 0; _i < 2; ++_i) \
;         __builtin_amdgcn_global_load_lds((const unsigned*)((const char*)(gbase) + (voff)[_i]), (LAS unsigned*)(lds + (bufoff) + ldsw + _i * 8192), 16, 0, 0); } while (0)
; #define PG8_LDA(dst, b, h) do { _Pragma("unroll") for (int m = 0; m < 4; ++m) _Pragma("unroll") for (int k = 0; k < 2; ++k) dst[m][k] = *(const LAS bf16x8*)(lds + PG8_SA(b, h) + aoff + m * 2048 + k * 1024); } while (0)
; #define PG8_LDB(dst, b, h) do { _Pragma("unroll") for (int n = 0; n < 2; ++n) _Pragma("unroll") for (int k = 0; k < 2; ++k) dst[n][k] = *(const LAS bf16x8*)(lds + PG8_SB(b, h) + boff + n * 2048 + k * 1024); } while (0)
; #define PG8_WAIT_V(n) asm volatile("s_waitcnt vmcnt(" #n ")" ::: "memory")
; #define PG8_WAIT_L(n) asm volatile("s_waitcnt lgkmcnt(" #n ")" ::: "memory")
; #define PG8_BAR __builtin_amdgcn_s_barrier()
; #define PG8_SCHED __builtin_amdgcn_sched_barrier(0)
; template <class Epi, class Sched, bool SWAPD = false>
; __device__ __forceinline__ void gemm_phase(LAS unsigned char* lds, const Gemm g, const Sched& S, const Epi& E) {
;     ...
;             const bool last = (t == nt - 2);
;             const char* a1 = cA + (size_t)(t + 1) * kstepA;
;             const char* a2 = last ? nA : cA + (size_t)(t + 2) * kstepA; const char* b2 = last ? nB : cB + (size_t)(t + 2) * kstep;
;             const char* a3 = a2 + kstepA; const char* b3 = b2 + kstep;
;             PG8_LDB(B0, 0, 0); PG8_LDB(B1, 0, 1); PG8_SCHED; PG8_LDA(At, 0, 0); PG8_STAGE(PG8_SA(1, 1), a1 + hstepA, voffA);
;             PG8_WAIT_V(8); PG8_WAIT_L(0); PG8_BAR; PG8_MMA(0, 0, At, B0); PG8_MMA(0, 1, At, B1); PG8_BAR; PG8_SCHED;
;             PG8_LDA(At, 0, 1); PG8_STAGE(PG8_SB(0, 0), b2, voffB); PG8_STAGE(PG8_SB(0, 1), b2 + hstepB, voffB); PG8_STAGE(PG8_SA(0, 0), a2, voffA);
;             PG8_WAIT_V(8); PG8_WAIT_L(0); PG8_BAR; PG8_MMA(1, 0, At, B0); PG8_MMA(1, 1, At, B1); PG8_BAR; PG8_SCHED;
.LBB0_1121:
	ds_read_b128 v[128:131], v210
	ds_read_b128 v[132:135], v210 offset:1024
	ds_read_b128 v[136:139], v210 offset:2048
	ds_read_b128 v[140:143], v210 offset:3072
	ds_read_b128 v[144:147], v211
	ds_read_b128 v[148:151], v211 offset:1024
	ds_read_b128 v[152:155], v211 offset:2048
	ds_read_b128 v[156:159], v211 offset:3072
	s_add_u32 s36, s34, 0x100
	s_addc_u32 s37, s35, 0
	s_cmp_eq_u32 s64, 40
	s_cselect_b32 s41, s58, s37
	s_cselect_b32 s40, s59, s36
	s_cselect_b32 s39, s60, s63
	s_cselect_b32 s38, s61, s62
	v_lshl_add_u64 v[204:205], s[34:35], 0, v[180:181]
	s_add_i32 m0, s33, 0xc000
	ds_read_b128 v[188:191], v212
	ds_read_b128 v[192:195], v212 offset:1024
	ds_read_b128 v[196:199], v212 offset:2048
	ds_read_b128 v[200:203], v212 offset:3072
	ds_read_b128 v[214:217], v212 offset:4096
	ds_read_b128 v[218:221], v212 offset:5120
	ds_read_b128 v[222:225], v212 offset:6144
	ds_read_b128 v[226:229], v212 offset:7168
	global_load_lds_dwordx4 v[204:205], off
	v_lshl_add_u64 v[204:205], s[34:35], 0, v[182:183]
	s_add_i32 m0, s33, 0xe000
	s_nop 0
	global_load_lds_dwordx4 v[204:205], off
	s_waitcnt vmcnt(8)
	s_waitcnt lgkmcnt(0)
	s_barrier
	s_setprio 1
	v_mfma_f32_16x16x32_bf16 v[124:127], v[128:131], v[188:191], v[124:127]
	v_mfma_f32_16x16x32_bf16 v[120:123], v[136:139], v[188:191], v[120:123]
	v_mfma_f32_16x16x32_bf16 v[116:119], v[128:131], v[196:199], v[116:119]
	v_mfma_f32_16x16x32_bf16 v[112:115], v[136:139], v[196:199], v[112:115]
	v_mfma_f32_16x16x32_bf16 v[92:95], v[128:131], v[214:217], v[92:95]
	v_mfma_f32_16x16x32_bf16 v[88:91], v[136:139], v[214:217], v[88:91]
	v_mfma_f32_16x16x32_bf16 v[76:79], v[128:131], v[222:225], v[76:79]
	v_mfma_f32_16x16x32_bf16 v[72:75], v[136:139], v[222:225], v[72:75]
	v_mfma_f32_16x16x32_bf16 v[124:127], v[132:135], v[192:195], v[124:127]
	v_mfma_f32_16x16x32_bf16 v[120:123], v[140:143], v[192:195], v[120:123]
	v_mfma_f32_16x16x32_bf16 v[116:119], v[132:135], v[200:203], v[116:119]
	v_mfma_f32_16x16x32_bf16 v[112:115], v[140:143], v[200:203], v[112:115]
	v_mfma_f32_16x16x32_bf16 v[92:95], v[132:135], v[218:221], v[92:95]
	v_mfma_f32_16x16x32_bf16 v[88:91], v[140:143], v[218:221], v[88:91]
	v_mfma_f32_16x16x32_bf16 v[76:79], v[132:135], v[226:229], v[76:79]
	v_mfma_f32_16x16x32_bf16 v[72:75], v[140:143], v[226:229], v[72:75]
	s_setprio 0
	s_setprio 1
	v_mfma_f32_16x16x32_bf16 v[108:111], v[144:147], v[188:191], v[108:111]
	v_mfma_f32_16x16x32_bf16 v[104:107], v[152:155], v[188:191], v[104:107]
	v_mfma_f32_16x16x32_bf16 v[100:103], v[144:147], v[196:199], v[100:103]
	v_mfma_f32_16x16x32_bf16 v[96:99], v[152:155], v[196:199], v[96:99]
	v_mfma_f32_16x16x32_bf16 v[84:87], v[144:147], v[214:217], v[84:87]
	v_mfma_f32_16x16x32_bf16 v[80:83], v[152:155], v[214:217], v[80:83]
	v_mfma_f32_16x16x32_bf16 v[68:71], v[144:147], v[222:225], v[68:71]
	v_mfma_f32_16x16x32_bf16 v[64:67], v[152:155], v[222:225], v[64:67]
	v_mfma_f32_16x16x32_bf16 v[108:111], v[148:151], v[192:195], v[108:111]
	v_mfma_f32_16x16x32_bf16 v[104:107], v[156:159], v[192:195], v[104:107]
	v_mfma_f32_16x16x32_bf16 v[100:103], v[148:151], v[200:203], v[100:103]
	v_mfma_f32_16x16x32_bf16 v[96:99], v[156:159], v[200:203], v[96:99]
	v_mfma_f32_16x16x32_bf16 v[84:87], v[148:151], v[218:221], v[84:87]
	v_mfma_f32_16x16x32_bf16 v[80:83], v[156:159], v[218:221], v[80:83]
	v_mfma_f32_16x16x32_bf16 v[68:71], v[148:151], v[226:229], v[68:71]
	v_mfma_f32_16x16x32_bf16 v[64:67], v[156:159], v[226:229], v[64:67]
	s_setprio 0
	s_barrier
	s_add_i32 s34, s52, s31
	v_lshl_add_u64 v[204:205], s[38:39], 0, v[160:161]
	s_mov_b32 m0, s34
	ds_read_b128 v[188:191], v212 offset:16384
	ds_read_b128 v[192:195], v212 offset:17408
	ds_read_b128 v[196:199], v212 offset:18432
	ds_read_b128 v[200:203], v212 offset:19456
	ds_read_b128 v[214:217], v212 offset:20480
	ds_read_b128 v[218:221], v212 offset:21504
	ds_read_b128 v[222:225], v212 offset:22528
	ds_read_b128 v[226:229], v212 offset:23552
	global_load_lds_dwordx4 v[204:205], off
	s_add_i32 m0, s34, 0x2000
	s_add_u32 s34, s38, 0xb0000
	v_lshl_add_u64 v[230:231], s[38:39], 0, v[162:163]
	s_addc_u32 s35, s39, 0
	s_add_i32 s65, s53, s31
	global_load_lds_dwordx4 v[230:231], off
	v_lshl_add_u64 v[232:233], s[34:35], 0, v[160:161]
	s_mov_b32 m0, s65
	v_lshl_add_u64 v[234:235], s[40:41], 0, v[162:163]
	global_load_lds_dwordx4 v[232:233], off
	v_lshl_add_u64 v[232:233], s[34:35], 0, v[162:163]
	s_add_i32 m0, s65, 0x2000
	s_nop 0
	global_load_lds_dwordx4 v[232:233], off
	v_lshl_add_u64 v[232:233], s[40:41], 0, v[160:161]
	s_mov_b32 m0, s33
	s_nop 0
	global_load_lds_dwordx4 v[232:233], off
	s_mov_b32 m0, s42
	s_nop 0
	global_load_lds_dwordx4 v[234:235], off
	s_waitcnt vmcnt(8)
	s_waitcnt lgkmcnt(0)
	s_barrier
; #define PG8_STAGE(bufoff, gbase, voff) do { _Pragma("unroll") for (int _i = 0; _i < 2; ++_i) \
;         __builtin_amdgcn_global_load_lds((const unsigned*)((const char*)(gbase) + (voff)[_i]), (LAS unsigned*)(lds + (bufoff) + ldsw + _i * 8192), 16, 0, 0); } while (0)
; #define PG8_LDA(dst, b, h) do { _Pragma("unroll") for (int m = 0; m < 4; ++m) _Pragma("unroll") for (int k = 0; k < 2; ++k) dst[m][k] = *(const LAS bf16x8*)(lds + PG8_SA(b, h) + aoff + m * 2048 + k * 1024); } while (0)
; #define PG8_LDB(dst, b, h) do { _Pragma("unroll") for (int n = 0; n < 2; ++n) _Pragma("unroll") for (int k = 0; k < 2; ++k) dst[n][k] = *(const LAS bf16x8*)(lds + PG8_SB(b, h) + boff + n * 2048 + k * 1024); } while (0)
; #define PG8_WAIT_V(n) asm volatile("s_waitcnt vmcnt(" #n ")" ::: "memory")
; #define PG8_WAIT_L(n) asm volatile("s_waitcnt lgkmcnt(" #n ")" ::: "memory")
; #define PG8_BAR __builtin_amdgcn_s_barrier()
; #define PG8_SCHED __builtin_amdgcn_sched_barrier(0)
; template <class Epi, class Sched, bool SWAPD = false>
; __device__ __forceinline__ void gemm_phase(LAS unsigned char* lds, const Gemm g, const Sched& S, const Epi& E) {
;     ...
;             PG8_WAIT_V(8); PG8_WAIT_L(0); PG8_BAR; PG8_MMA(1, 0, At, B0); PG8_MMA(1, 1, At, B1); PG8_BAR; PG8_SCHED;
;             PG8_LDB(B0, 1, 0); PG8_LDB(B1, 1, 1); PG8_SCHED; PG8_LDA(At, 1, 0); PG8_STAGE(PG8_SA(0, 1), a2 + hstepA, voffA);
;             PG8_WAIT_V(8); PG8_WAIT_L(0); PG8_BAR; PG8_MMA(0, 0, At, B0); PG8_MMA(0, 1, At, B1); PG8_BAR; PG8_SCHED;
	s_setprio 1
	v_mfma_f32_16x16x32_bf16 v[60:63], v[128:131], v[188:191], v[60:63]
	v_mfma_f32_16x16x32_bf16 v[56:59], v[136:139], v[188:191], v[56:59]
	v_mfma_f32_16x16x32_bf16 v[44:47], v[128:131], v[196:199], v[44:47]
	v_mfma_f32_16x16x32_bf16 v[40:43], v[136:139], v[196:199], v[40:43]
	v_mfma_f32_16x16x32_bf16 v[36:39], v[128:131], v[214:217], v[36:39]
	v_mfma_f32_16x16x32_bf16 v[32:35], v[136:139], v[214:217], v[32:35]
	v_mfma_f32_16x16x32_bf16 v[20:23], v[128:131], v[222:225], v[20:23]
	v_mfma_f32_16x16x32_bf16 v[16:19], v[136:139], v[222:225], v[16:19]
	v_mfma_f32_16x16x32_bf16 v[60:63], v[132:135], v[192:195], v[60:63]
	v_mfma_f32_16x16x32_bf16 v[56:59], v[140:143], v[192:195], v[56:59]
	v_mfma_f32_16x16x32_bf16 v[44:47], v[132:135], v[200:203], v[44:47]
	v_mfma_f32_16x16x32_bf16 v[40:43], v[140:143], v[200:203], v[40:43]
	v_mfma_f32_16x16x32_bf16 v[36:39], v[132:135], v[218:221], v[36:39]
	v_mfma_f32_16x16x32_bf16 v[32:35], v[140:143], v[218:221], v[32:35]
	v_mfma_f32_16x16x32_bf16 v[20:23], v[132:135], v[226:229], v[20:23]
	v_mfma_f32_16x16x32_bf16 v[16:19], v[140:143], v[226:229], v[16:19]
	s_setprio 0
	s_setprio 1
	v_mfma_f32_16x16x32_bf16 v[52:55], v[144:147], v[188:191], v[52:55]
	v_mfma_f32_16x16x32_bf16 v[48:51], v[152:155], v[188:191], v[48:51]
	v_mfma_f32_16x16x32_bf16 v[28:31], v[144:147], v[196:199], v[28:31]
	v_mfma_f32_16x16x32_bf16 v[24:27], v[152:155], v[196:199], v[24:27]
	v_mfma_f32_16x16x32_bf16 v[12:15], v[144:147], v[214:217], v[12:15]
	v_mfma_f32_16x16x32_bf16 v[8:11], v[152:155], v[214:217], v[8:11]
	v_mfma_f32_16x16x32_bf16 v[4:7], v[144:147], v[222:225], v[4:7]
	v_mfma_f32_16x16x32_bf16 v[0:3], v[152:155], v[222:225], v[0:3]
	v_mfma_f32_16x16x32_bf16 v[52:55], v[148:151], v[192:195], v[52:55]
	v_mfma_f32_16x16x32_bf16 v[48:51], v[156:159], v[192:195], v[48:51]
	v_mfma_f32_16x16x32_bf16 v[28:31], v[148:151], v[200:203], v[28:31]
	v_mfma_f32_16x16x32_bf16 v[24:27], v[156:159], v[200:203], v[24:27]
	v_mfma_f32_16x16x32_bf16 v[12:15], v[148:151], v[218:221], v[12:15]
	v_mfma_f32_16x16x32_bf16 v[8:11], v[156:159], v[218:221], v[8:11]
	v_mfma_f32_16x16x32_bf16 v[4:7], v[148:151], v[226:229], v[4:7]
	v_mfma_f32_16x16x32_bf16 v[0:3], v[156:159], v[226:229], v[0:3]
	s_setprio 0
	s_barrier
	s_add_i32 s65, 0, 0x18000
	s_add_i32 s66, 0, 0x1c000
	v_add_u32_e32 v140, s65, v208
	v_add_u32_e32 v156, s66, v208
	ds_read_b128 v[128:131], v140
	ds_read_b128 v[132:135], v140 offset:1024
	ds_read_b128 v[136:139], v140 offset:2048
	ds_read_b128 v[140:143], v140 offset:3072
	ds_read_b128 v[144:147], v156
	ds_read_b128 v[148:151], v156 offset:1024
	ds_read_b128 v[152:155], v156 offset:2048
	ds_read_b128 v[156:159], v156 offset:3072
	s_add_u32 s34, s40, 0xb0000
	s_addc_u32 s35, s41, 0
	s_mov_b32 m0, s43
	v_lshl_add_u64 v[236:237], s[34:35], 0, v[160:161]
	ds_read_b128 v[188:191], v212 offset:32768
	ds_read_b128 v[192:195], v212 offset:33792
	ds_read_b128 v[196:199], v212 offset:34816
	ds_read_b128 v[200:203], v212 offset:35840
	ds_read_b128 v[214:217], v212 offset:36864
	ds_read_b128 v[218:221], v212 offset:37888
	ds_read_b128 v[222:225], v212 offset:38912
	ds_read_b128 v[226:229], v212 offset:39936
	global_load_lds_dwordx4 v[236:237], off
	v_lshl_add_u64 v[236:237], s[34:35], 0, v[162:163]
	s_mov_b32 m0, s44
	s_nop 0
	global_load_lds_dwordx4 v[236:237], off
	s_waitcnt vmcnt(8)
	s_waitcnt lgkmcnt(0)
	s_barrier
	s_setprio 1
	v_mfma_f32_16x16x32_bf16 v[124:127], v[128:131], v[188:191], v[124:127]
	v_mfma_f32_16x16x32_bf16 v[120:123], v[136:139], v[188:191], v[120:123]
	v_mfma_f32_16x16x32_bf16 v[116:119], v[128:131], v[196:199], v[116:119]
	v_mfma_f32_16x16x32_bf16 v[112:115], v[136:139], v[196:199], v[112:115]
	v_mfma_f32_16x16x32_bf16 v[92:95], v[128:131], v[214:217], v[92:95]
	v_mfma_f32_16x16x32_bf16 v[88:91], v[136:139], v[214:217], v[88:91]
	v_mfma_f32_16x16x32_bf16 v[76:79], v[128:131], v[222:225], v[76:79]
	v_mfma_f32_16x16x32_bf16 v[72:75], v[136:139], v[222:225], v[72:75]
	v_mfma_f32_16x16x32_bf16 v[124:127], v[132:135], v[192:195], v[124:127]
	v_mfma_f32_16x16x32_bf16 v[120:123], v[140:143], v[192:195], v[120:123]
	v_mfma_f32_16x16x32_bf16 v[116:119], v[132:135], v[200:203], v[116:119]
	v_mfma_f32_16x16x32_bf16 v[112:115], v[140:143], v[200:203], v[112:115]
	v_mfma_f32_16x16x32_bf16 v[92:95], v[132:135], v[218:221], v[92:95]
	v_mfma_f32_16x16x32_bf16 v[88:91], v[140:143], v[218:221], v[88:91]
	v_mfma_f32_16x16x32_bf16 v[76:79], v[132:135], v[226:229], v[76:79]
	v_mfma_f32_16x16x32_bf16 v[72:75], v[140:143], v[226:229], v[72:75]
	s_setprio 0
	s_setprio 1
	v_mfma_f32_16x16x32_bf16 v[108:111], v[144:147], v[188:191], v[108:111]
	v_mfma_f32_16x16x32_bf16 v[104:107], v[152:155], v[188:191], v[104:107]
	v_mfma_f32_16x16x32_bf16 v[100:103], v[144:147], v[196:199], v[100:103]
	v_mfma_f32_16x16x32_bf16 v[96:99], v[152:155], v[196:199], v[96:99]
	v_mfma_f32_16x16x32_bf16 v[84:87], v[144:147], v[214:217], v[84:87]
	v_mfma_f32_16x16x32_bf16 v[80:83], v[152:155], v[214:217], v[80:83]
	v_mfma_f32_16x16x32_bf16 v[68:71], v[144:147], v[222:225], v[68:71]
	v_mfma_f32_16x16x32_bf16 v[64:67], v[152:155], v[222:225], v[64:67]
	v_mfma_f32_16x16x32_bf16 v[108:111], v[148:151], v[192:195], v[108:111]
	v_mfma_f32_16x16x32_bf16 v[104:107], v[156:159], v[192:195], v[104:107]
	v_mfma_f32_16x16x32_bf16 v[100:103], v[148:151], v[200:203], v[100:103]
	v_mfma_f32_16x16x32_bf16 v[96:99], v[156:159], v[200:203], v[96:99]
	v_mfma_f32_16x16x32_bf16 v[84:87], v[148:151], v[218:221], v[84:87]
	v_mfma_f32_16x16x32_bf16 v[80:83], v[156:159], v[218:221], v[80:83]
	v_mfma_f32_16x16x32_bf16 v[68:71], v[148:151], v[226:229], v[68:71]
	v_mfma_f32_16x16x32_bf16 v[64:67], v[156:159], v[226:229], v[64:67]
	s_setprio 0
	s_barrier
; #define PG8_STAGE(bufoff, gbase, voff) do { _Pragma("unroll") for (int _i = 0; _i < 2; ++_i) \
;         __builtin_amdgcn_global_load_lds((const unsigned*)((const char*)(gbase) + (voff)[_i]), (LAS unsigned*)(lds + (bufoff) + ldsw + _i * 8192), 16, 0, 0); } while (0)
; #define PG8_LDA(dst, b, h) do { _Pragma("unroll") for (int m = 0; m < 4; ++m) _Pragma("unroll") for (int k = 0; k < 2; ++k) dst[m][k] = *(const LAS bf16x8*)(lds + PG8_SA(b, h) + aoff + m * 2048 + k * 1024); } while (0)
; #define PG8_WAIT_V(n) asm volatile("s_waitcnt vmcnt(" #n ")" ::: "memory")
; #define PG8_WAIT_L(n) asm volatile("s_waitcnt lgkmcnt(" #n ")" ::: "memory")
; #define PG8_BAR __builtin_amdgcn_s_barrier()
; #define PG8_SCHED __builtin_amdgcn_sched_barrier(0)
; template <class Epi, class Sched, bool SWAPD = false>
; __device__ __forceinline__ void gemm_phase(LAS unsigned char* lds, const Gemm g, const Sched& S, const Epi& E) {
;     ...
;             PG8_LDA(At, 1, 1); PG8_STAGE(PG8_SB(1, 0), b3, voffB); PG8_STAGE(PG8_SB(1, 1), b3 + hstepB, voffB); PG8_STAGE(PG8_SA(1, 0), a3, voffA);
;             PG8_WAIT_V(8); PG8_WAIT_L(0); PG8_BAR; PG8_MMA(1, 0, At, B0); PG8_MMA(1, 1, At, B1); PG8_BAR; PG8_SCHED;
;         }
;         if (wr == 0) PG8_BAR;
	s_add_i32 s34, s65, s31
	v_lshl_add_u64 v[204:205], v[204:205], 0, s[8:9]
	s_mov_b32 m0, s34
	ds_read_b128 v[188:191], v212 offset:49152
	ds_read_b128 v[192:195], v212 offset:50176
	ds_read_b128 v[196:199], v212 offset:51200
	ds_read_b128 v[200:203], v212 offset:52224
	ds_read_b128 v[214:217], v212 offset:53248
	ds_read_b128 v[218:221], v212 offset:54272
	ds_read_b128 v[222:225], v212 offset:55296
	ds_read_b128 v[226:229], v212 offset:56320
	global_load_lds_dwordx4 v[204:205], off
	s_add_i32 m0, s34, 0x2000
	s_add_u32 s34, s38, 0xb0080
	v_lshl_add_u64 v[204:205], v[230:231], 0, s[8:9]
	s_addc_u32 s35, s39, 0
	s_add_i32 s38, s66, s31
	global_load_lds_dwordx4 v[204:205], off
	v_lshl_add_u64 v[204:205], s[34:35], 0, v[160:161]
	s_mov_b32 m0, s38
	s_nop 0
	global_load_lds_dwordx4 v[204:205], off
	v_lshl_add_u64 v[204:205], s[34:35], 0, v[162:163]
	s_add_i32 m0, s38, 0x2000
	s_nop 0
	global_load_lds_dwordx4 v[204:205], off
	v_lshl_add_u64 v[204:205], v[232:233], 0, s[8:9]
	s_mov_b32 m0, s50
	s_nop 0
	global_load_lds_dwordx4 v[204:205], off
	v_lshl_add_u64 v[204:205], v[234:235], 0, s[8:9]
	s_mov_b32 m0, s51
	s_nop 0
	global_load_lds_dwordx4 v[204:205], off
	s_waitcnt vmcnt(8)
	s_waitcnt lgkmcnt(0)
	s_barrier
	s_setprio 1
	v_mfma_f32_16x16x32_bf16 v[60:63], v[128:131], v[188:191], v[60:63]
	v_mfma_f32_16x16x32_bf16 v[56:59], v[136:139], v[188:191], v[56:59]
	v_mfma_f32_16x16x32_bf16 v[44:47], v[128:131], v[196:199], v[44:47]
	v_mfma_f32_16x16x32_bf16 v[40:43], v[136:139], v[196:199], v[40:43]
	v_mfma_f32_16x16x32_bf16 v[36:39], v[128:131], v[214:217], v[36:39]
	v_mfma_f32_16x16x32_bf16 v[32:35], v[136:139], v[214:217], v[32:35]
	v_mfma_f32_16x16x32_bf16 v[20:23], v[128:131], v[222:225], v[20:23]
	v_mfma_f32_16x16x32_bf16 v[16:19], v[136:139], v[222:225], v[16:19]
	v_mfma_f32_16x16x32_bf16 v[60:63], v[132:135], v[192:195], v[60:63]
	v_mfma_f32_16x16x32_bf16 v[56:59], v[140:143], v[192:195], v[56:59]
	v_mfma_f32_16x16x32_bf16 v[44:47], v[132:135], v[200:203], v[44:47]
	v_mfma_f32_16x16x32_bf16 v[40:43], v[140:143], v[200:203], v[40:43]
	v_mfma_f32_16x16x32_bf16 v[36:39], v[132:135], v[218:221], v[36:39]
	v_mfma_f32_16x16x32_bf16 v[32:35], v[140:143], v[218:221], v[32:35]
	v_mfma_f32_16x16x32_bf16 v[20:23], v[132:135], v[226:229], v[20:23]
	v_mfma_f32_16x16x32_bf16 v[16:19], v[140:143], v[226:229], v[16:19]
	s_setprio 0
	s_setprio 1
	v_mfma_f32_16x16x32_bf16 v[52:55], v[144:147], v[188:191], v[52:55]
	v_mfma_f32_16x16x32_bf16 v[48:51], v[152:155], v[188:191], v[48:51]
	v_mfma_f32_16x16x32_bf16 v[28:31], v[144:147], v[196:199], v[28:31]
	v_mfma_f32_16x16x32_bf16 v[24:27], v[152:155], v[196:199], v[24:27]
	v_mfma_f32_16x16x32_bf16 v[12:15], v[144:147], v[214:217], v[12:15]
	v_mfma_f32_16x16x32_bf16 v[8:11], v[152:155], v[214:217], v[8:11]
	v_mfma_f32_16x16x32_bf16 v[4:7], v[144:147], v[222:225], v[4:7]
	v_mfma_f32_16x16x32_bf16 v[0:3], v[152:155], v[222:225], v[0:3]
	v_mfma_f32_16x16x32_bf16 v[52:55], v[148:151], v[192:195], v[52:55]
	v_mfma_f32_16x16x32_bf16 v[48:51], v[156:159], v[192:195], v[48:51]
	v_mfma_f32_16x16x32_bf16 v[28:31], v[148:151], v[200:203], v[28:31]
	v_mfma_f32_16x16x32_bf16 v[24:27], v[156:159], v[200:203], v[24:27]
	v_mfma_f32_16x16x32_bf16 v[12:15], v[148:151], v[218:221], v[12:15]
	v_mfma_f32_16x16x32_bf16 v[8:11], v[156:159], v[218:221], v[8:11]
	v_mfma_f32_16x16x32_bf16 v[4:7], v[148:151], v[226:229], v[4:7]
	v_mfma_f32_16x16x32_bf16 v[0:3], v[156:159], v[226:229], v[0:3]
	s_setprio 0
	s_barrier
	s_add_i32 s64, s64, 2
	s_add_u32 s62, s62, 0x100
	s_addc_u32 s63, s63, 0
	s_cmp_gt_u32 s64, 41
	s_mov_b64 s[34:35], s[36:37]
	s_cbranch_scc0 .LBB0_1121
	s_and_b64 vcc, exec, s[12:13]
	s_cbranch_vccz .LBB0_1124
	s_barrier

; #define PG8_STAGE(bufoff, gbase, voff) do { _Pragma("unroll") for (int _i = 0; _i < 2; ++_i) \
;         __builtin_amdgcn_global_load_lds((const unsigned*)((const char*)(gbase) + (voff)[_i]), (LAS unsigned*)(lds + (bufoff) + ldsw + _i * 8192), 16, 0, 0); } while (0)
; #define PG8_LDA(dst, b, h) do { _Pragma("unroll") for (int m = 0; m < 4; ++m) _Pragma("unroll") for (int k = 0; k < 2; ++k) dst[m][k] = *(const LAS bf16x8*)(lds + PG8_SA(b, h) + aoff + m * 2048 + k * 1024); } while (0)
; #define PG8_LDB(dst, b, h) do { _Pragma("unroll") for (int n = 0; n < 2; ++n) _Pragma("unroll") for (int k = 0; k < 2; ++k) dst[n][k] = *(const LAS bf16x8*)(lds + PG8_SB(b, h) + boff + n * 2048 + k * 1024); } while (0)
; #define PG8_WAIT_V(n) asm volatile("s_waitcnt vmcnt(" #n ")" ::: "memory")
; #define PG8_WAIT_L(n) asm volatile("s_waitcnt lgkmcnt(" #n ")" ::: "memory")
; #define PG8_BAR __builtin_amdgcn_s_barrier()
; #define PG8_SCHED __builtin_amdgcn_sched_barrier(0)
; template <class Epi, class Sched, bool SWAPD = false>
; __device__ __forceinline__ void gemm_phase(LAS unsigned char* lds, const Gemm g, const Sched& S, const Epi& E) {
;     ...
;             const bool last = (t == nt - 2);
;             const char* a1 = cA + (size_t)(t + 1) * kstepA;
;             const char* a2 = last ? nA : cA + (size_t)(t + 2) * kstepA; const char* b2 = last ? nB : cB + (size_t)(t + 2) * kstep;
;             const char* a3 = a2 + kstepA; const char* b3 = b2 + kstep;
;             PG8_LDB(B0, 0, 0); PG8_LDB(B1, 0, 1); PG8_SCHED; PG8_LDA(At, 0, 0); PG8_STAGE(PG8_SA(1, 1), a1 + hstepA, voffA);
;             PG8_WAIT_V(8); PG8_WAIT_L(0); PG8_BAR; PG8_MMA(0, 0, At, B0); PG8_MMA(0, 1, At, B1); PG8_BAR; PG8_SCHED;
;             PG8_LDA(At, 0, 1); PG8_STAGE(PG8_SB(0, 0), b2, voffB); PG8_STAGE(PG8_SB(0, 1), b2 + hstepB, voffB); PG8_STAGE(PG8_SA(0, 0), a2, voffA);
;             PG8_WAIT_V(8); PG8_WAIT_L(0); PG8_BAR; PG8_MMA(1, 0, At, B0); PG8_MMA(1, 1, At, B1); PG8_BAR; PG8_SCHED;
.LBB0_1531:
	ds_read_b128 v[142:145], v151
	ds_read_b128 v[154:157], v151 offset:1024
	ds_read_b128 v[158:161], v151 offset:2048
	ds_read_b128 v[162:165], v151 offset:3072
	ds_read_b128 v[166:169], v152
	ds_read_b128 v[170:173], v152 offset:1024
	ds_read_b128 v[174:177], v152 offset:2048
	ds_read_b128 v[178:181], v152 offset:3072
	s_add_u32 s42, s40, 0xfffe0080
	s_addc_u32 s43, s41, -1
	s_cmp_eq_u32 s61, 4
	s_cselect_b32 s45, s9, s43
	s_cselect_b32 s44, s25, s42
	s_cselect_b32 s43, s27, s60
	s_cselect_b32 s42, s58, s59
	v_lshl_add_u64 v[216:217], s[40:41], 0, v[134:135]
	s_add_i32 m0, s33, 0xc000
	ds_read_b128 v[182:185], v153
	ds_read_b128 v[186:189], v153 offset:1024
	ds_read_b128 v[190:193], v153 offset:2048
	ds_read_b128 v[194:197], v153 offset:3072
	ds_read_b128 v[198:201], v153 offset:4096
	ds_read_b128 v[202:205], v153 offset:5120
	ds_read_b128 v[208:211], v153 offset:6144
	ds_read_b128 v[212:215], v153 offset:7168
	global_load_lds_dwordx4 v[216:217], off
	v_lshl_add_u64 v[216:217], s[40:41], 0, v[136:137]
	s_add_i32 m0, s33, 0xe000
	s_nop 0
	global_load_lds_dwordx4 v[216:217], off
	s_waitcnt vmcnt(8)
	s_waitcnt lgkmcnt(0)
	s_barrier
	s_setprio 1
	v_mfma_f32_16x16x32_bf16 v[124:127], v[182:185], v[142:145], v[124:127]
	v_mfma_f32_16x16x32_bf16 v[120:123], v[182:185], v[158:161], v[120:123]
	v_mfma_f32_16x16x32_bf16 v[108:111], v[190:193], v[142:145], v[108:111]
	v_mfma_f32_16x16x32_bf16 v[104:107], v[190:193], v[158:161], v[104:107]
	v_mfma_f32_16x16x32_bf16 v[96:99], v[198:201], v[142:145], v[96:99]
	v_mfma_f32_16x16x32_bf16 v[88:91], v[198:201], v[158:161], v[88:91]
	v_mfma_f32_16x16x32_bf16 v[80:83], v[208:211], v[142:145], v[80:83]
	v_mfma_f32_16x16x32_bf16 v[72:75], v[208:211], v[158:161], v[72:75]
	v_mfma_f32_16x16x32_bf16 v[124:127], v[186:189], v[154:157], v[124:127]
	v_mfma_f32_16x16x32_bf16 v[120:123], v[186:189], v[162:165], v[120:123]
	v_mfma_f32_16x16x32_bf16 v[108:111], v[194:197], v[154:157], v[108:111]
	v_mfma_f32_16x16x32_bf16 v[104:107], v[194:197], v[162:165], v[104:107]
	v_mfma_f32_16x16x32_bf16 v[96:99], v[202:205], v[154:157], v[96:99]
	v_mfma_f32_16x16x32_bf16 v[88:91], v[202:205], v[162:165], v[88:91]
	v_mfma_f32_16x16x32_bf16 v[80:83], v[212:215], v[154:157], v[80:83]
	v_mfma_f32_16x16x32_bf16 v[72:75], v[212:215], v[162:165], v[72:75]
	s_setprio 0
	s_setprio 1
	v_mfma_f32_16x16x32_bf16 v[116:119], v[182:185], v[166:169], v[116:119]
	v_mfma_f32_16x16x32_bf16 v[112:115], v[182:185], v[174:177], v[112:115]
	v_mfma_f32_16x16x32_bf16 v[100:103], v[190:193], v[166:169], v[100:103]
	v_mfma_f32_16x16x32_bf16 v[92:95], v[190:193], v[174:177], v[92:95]
	v_mfma_f32_16x16x32_bf16 v[84:87], v[198:201], v[166:169], v[84:87]
	v_mfma_f32_16x16x32_bf16 v[76:79], v[198:201], v[174:177], v[76:79]
	v_mfma_f32_16x16x32_bf16 v[68:71], v[208:211], v[166:169], v[68:71]
	v_mfma_f32_16x16x32_bf16 v[64:67], v[208:211], v[174:177], v[64:67]
	v_mfma_f32_16x16x32_bf16 v[116:119], v[186:189], v[170:173], v[116:119]
	v_mfma_f32_16x16x32_bf16 v[112:115], v[186:189], v[178:181], v[112:115]
	v_mfma_f32_16x16x32_bf16 v[100:103], v[194:197], v[170:173], v[100:103]
	v_mfma_f32_16x16x32_bf16 v[92:95], v[194:197], v[178:181], v[92:95]
	v_mfma_f32_16x16x32_bf16 v[84:87], v[202:205], v[170:173], v[84:87]
	v_mfma_f32_16x16x32_bf16 v[76:79], v[202:205], v[178:181], v[76:79]
	v_mfma_f32_16x16x32_bf16 v[68:71], v[212:215], v[170:173], v[68:71]
	v_mfma_f32_16x16x32_bf16 v[64:67], v[212:215], v[178:181], v[64:67]
	s_setprio 0
	s_barrier
	s_add_i32 s62, s55, s21
	v_lshl_add_u64 v[216:217], s[42:43], 0, v[128:129]
	s_mov_b32 m0, s62
	ds_read_b128 v[182:185], v153 offset:16384
	ds_read_b128 v[186:189], v153 offset:17408
	ds_read_b128 v[190:193], v153 offset:18432
	ds_read_b128 v[194:197], v153 offset:19456
	ds_read_b128 v[198:201], v153 offset:20480
	ds_read_b128 v[202:205], v153 offset:21504
	ds_read_b128 v[208:211], v153 offset:22528
	ds_read_b128 v[212:215], v153 offset:23552
	global_load_lds_dwordx4 v[216:217], off
	s_add_i32 m0, s62, 0x2000
	s_add_u32 s62, s42, 0x20000
	v_lshl_add_u64 v[218:219], s[42:43], 0, v[130:131]
	s_addc_u32 s63, s43, 0
	s_add_i32 s64, s56, s21
	global_load_lds_dwordx4 v[218:219], off
	v_lshl_add_u64 v[220:221], s[62:63], 0, v[128:129]
	s_mov_b32 m0, s64
	v_lshl_add_u64 v[222:223], s[44:45], 0, v[130:131]
	global_load_lds_dwordx4 v[220:221], off
	v_lshl_add_u64 v[220:221], s[62:63], 0, v[130:131]
	s_add_i32 m0, s64, 0x2000
	s_nop 0
	global_load_lds_dwordx4 v[220:221], off
	v_lshl_add_u64 v[220:221], s[44:45], 0, v[128:129]
	s_mov_b32 m0, s33
	s_nop 0
	global_load_lds_dwordx4 v[220:221], off
	s_mov_b32 m0, s46
	s_nop 0
	global_load_lds_dwordx4 v[222:223], off
	s_waitcnt vmcnt(8)
	s_waitcnt lgkmcnt(0)
	s_barrier
; #define PG8_STAGE(bufoff, gbase, voff) do { _Pragma("unroll") for (int _i = 0; _i < 2; ++_i) \
;         __builtin_amdgcn_global_load_lds((const unsigned*)((const char*)(gbase) + (voff)[_i]), (LAS unsigned*)(lds + (bufoff) + ldsw + _i * 8192), 16, 0, 0); } while (0)
; #define PG8_LDA(dst, b, h) do { _Pragma("unroll") for (int m = 0; m < 4; ++m) _Pragma("unroll") for (int k = 0; k < 2; ++k) dst[m][k] = *(const LAS bf16x8*)(lds + PG8_SA(b, h) + aoff + m * 2048 + k * 1024); } while (0)
; #define PG8_LDB(dst, b, h) do { _Pragma("unroll") for (int n = 0; n < 2; ++n) _Pragma("unroll") for (int k = 0; k < 2; ++k) dst[n][k] = *(const LAS bf16x8*)(lds + PG8_SB(b, h) + boff + n * 2048 + k * 1024); } while (0)
; #define PG8_WAIT_V(n) asm volatile("s_waitcnt vmcnt(" #n ")" ::: "memory")
; #define PG8_WAIT_L(n) asm volatile("s_waitcnt lgkmcnt(" #n ")" ::: "memory")
; #define PG8_BAR __builtin_amdgcn_s_barrier()
; #define PG8_SCHED __builtin_amdgcn_sched_barrier(0)
; template <class Epi, class Sched, bool SWAPD = false>
; __device__ __forceinline__ void gemm_phase(LAS unsigned char* lds, const Gemm g, const Sched& S, const Epi& E) {
;     ...
;             PG8_WAIT_V(8); PG8_WAIT_L(0); PG8_BAR; PG8_MMA(1, 0, At, B0); PG8_MMA(1, 1, At, B1); PG8_BAR; PG8_SCHED;
;             PG8_LDB(B0, 1, 0); PG8_LDB(B1, 1, 1); PG8_SCHED; PG8_LDA(At, 1, 0); PG8_STAGE(PG8_SA(0, 1), a2 + hstepA, voffA);
;             PG8_WAIT_V(8); PG8_WAIT_L(0); PG8_BAR; PG8_MMA(0, 0, At, B0); PG8_MMA(0, 1, At, B1); PG8_BAR; PG8_SCHED;
	s_setprio 1
	v_mfma_f32_16x16x32_bf16 v[60:63], v[182:185], v[142:145], v[60:63]
	v_mfma_f32_16x16x32_bf16 v[56:59], v[182:185], v[158:161], v[56:59]
	v_mfma_f32_16x16x32_bf16 v[48:51], v[190:193], v[142:145], v[48:51]
	v_mfma_f32_16x16x32_bf16 v[40:43], v[190:193], v[158:161], v[40:43]
	v_mfma_f32_16x16x32_bf16 v[32:35], v[198:201], v[142:145], v[32:35]
	v_mfma_f32_16x16x32_bf16 v[24:27], v[198:201], v[158:161], v[24:27]
	v_mfma_f32_16x16x32_bf16 v[16:19], v[208:211], v[142:145], v[16:19]
	v_mfma_f32_16x16x32_bf16 v[8:11], v[208:211], v[158:161], v[8:11]
	v_mfma_f32_16x16x32_bf16 v[60:63], v[186:189], v[154:157], v[60:63]
	v_mfma_f32_16x16x32_bf16 v[56:59], v[186:189], v[162:165], v[56:59]
	v_mfma_f32_16x16x32_bf16 v[48:51], v[194:197], v[154:157], v[48:51]
	v_mfma_f32_16x16x32_bf16 v[40:43], v[194:197], v[162:165], v[40:43]
	v_mfma_f32_16x16x32_bf16 v[32:35], v[202:205], v[154:157], v[32:35]
	v_mfma_f32_16x16x32_bf16 v[24:27], v[202:205], v[162:165], v[24:27]
	v_mfma_f32_16x16x32_bf16 v[16:19], v[212:215], v[154:157], v[16:19]
	v_mfma_f32_16x16x32_bf16 v[8:11], v[212:215], v[162:165], v[8:11]
	s_setprio 0
	s_setprio 1
	v_mfma_f32_16x16x32_bf16 v[52:55], v[182:185], v[166:169], v[52:55]
	v_mfma_f32_16x16x32_bf16 v[44:47], v[182:185], v[174:177], v[44:47]
	v_mfma_f32_16x16x32_bf16 v[36:39], v[190:193], v[166:169], v[36:39]
	v_mfma_f32_16x16x32_bf16 v[28:31], v[190:193], v[174:177], v[28:31]
	v_mfma_f32_16x16x32_bf16 v[20:23], v[198:201], v[166:169], v[20:23]
	v_mfma_f32_16x16x32_bf16 v[12:15], v[198:201], v[174:177], v[12:15]
	v_mfma_f32_16x16x32_bf16 v[4:7], v[208:211], v[166:169], v[4:7]
	v_mfma_f32_16x16x32_bf16 v[0:3], v[208:211], v[174:177], v[0:3]
	v_mfma_f32_16x16x32_bf16 v[52:55], v[186:189], v[170:173], v[52:55]
	v_mfma_f32_16x16x32_bf16 v[44:47], v[186:189], v[178:181], v[44:47]
	v_mfma_f32_16x16x32_bf16 v[36:39], v[194:197], v[170:173], v[36:39]
	v_mfma_f32_16x16x32_bf16 v[28:31], v[194:197], v[178:181], v[28:31]
	v_mfma_f32_16x16x32_bf16 v[20:23], v[202:205], v[170:173], v[20:23]
	v_mfma_f32_16x16x32_bf16 v[12:15], v[202:205], v[178:181], v[12:15]
	v_mfma_f32_16x16x32_bf16 v[4:7], v[212:215], v[170:173], v[4:7]
	v_mfma_f32_16x16x32_bf16 v[0:3], v[212:215], v[178:181], v[0:3]
	s_setprio 0
	s_barrier
	s_add_i32 s62, 0, 0x18000
	s_add_i32 s63, 0, 0x1c000
	v_add_u32_e32 v162, s62, v146
	v_add_u32_e32 v178, s63, v146
	ds_read_b128 v[142:145], v162
	ds_read_b128 v[154:157], v162 offset:1024
	ds_read_b128 v[158:161], v162 offset:2048
	ds_read_b128 v[162:165], v162 offset:3072
	ds_read_b128 v[166:169], v178
	ds_read_b128 v[170:173], v178 offset:1024
	ds_read_b128 v[174:177], v178 offset:2048
	ds_read_b128 v[178:181], v178 offset:3072
	s_add_u32 s44, s44, 0x20000
	s_addc_u32 s45, s45, 0
	s_mov_b32 m0, s47
	v_lshl_add_u64 v[224:225], s[44:45], 0, v[128:129]
	ds_read_b128 v[182:185], v153 offset:32768
	ds_read_b128 v[186:189], v153 offset:33792
	ds_read_b128 v[190:193], v153 offset:34816
	ds_read_b128 v[194:197], v153 offset:35840
	ds_read_b128 v[198:201], v153 offset:36864
	ds_read_b128 v[202:205], v153 offset:37888
	ds_read_b128 v[208:211], v153 offset:38912
	ds_read_b128 v[212:215], v153 offset:39936
	global_load_lds_dwordx4 v[224:225], off
	v_lshl_add_u64 v[224:225], s[44:45], 0, v[130:131]
	s_mov_b32 m0, s50
	s_nop 0
	global_load_lds_dwordx4 v[224:225], off
	s_waitcnt vmcnt(8)
	s_waitcnt lgkmcnt(0)
	s_barrier
	s_setprio 1
	v_mfma_f32_16x16x32_bf16 v[124:127], v[182:185], v[142:145], v[124:127]
	v_mfma_f32_16x16x32_bf16 v[120:123], v[182:185], v[158:161], v[120:123]
	v_mfma_f32_16x16x32_bf16 v[108:111], v[190:193], v[142:145], v[108:111]
	v_mfma_f32_16x16x32_bf16 v[104:107], v[190:193], v[158:161], v[104:107]
	v_mfma_f32_16x16x32_bf16 v[96:99], v[198:201], v[142:145], v[96:99]
	v_mfma_f32_16x16x32_bf16 v[88:91], v[198:201], v[158:161], v[88:91]
	v_mfma_f32_16x16x32_bf16 v[80:83], v[208:211], v[142:145], v[80:83]
	v_mfma_f32_16x16x32_bf16 v[72:75], v[208:211], v[158:161], v[72:75]
	v_mfma_f32_16x16x32_bf16 v[124:127], v[186:189], v[154:157], v[124:127]
	v_mfma_f32_16x16x32_bf16 v[120:123], v[186:189], v[162:165], v[120:123]
	v_mfma_f32_16x16x32_bf16 v[108:111], v[194:197], v[154:157], v[108:111]
	v_mfma_f32_16x16x32_bf16 v[104:107], v[194:197], v[162:165], v[104:107]
	v_mfma_f32_16x16x32_bf16 v[96:99], v[202:205], v[154:157], v[96:99]
	v_mfma_f32_16x16x32_bf16 v[88:91], v[202:205], v[162:165], v[88:91]
	v_mfma_f32_16x16x32_bf16 v[80:83], v[212:215], v[154:157], v[80:83]
	v_mfma_f32_16x16x32_bf16 v[72:75], v[212:215], v[162:165], v[72:75]
	s_setprio 0
	s_setprio 1
	v_mfma_f32_16x16x32_bf16 v[116:119], v[182:185], v[166:169], v[116:119]
	v_mfma_f32_16x16x32_bf16 v[112:115], v[182:185], v[174:177], v[112:115]
	v_mfma_f32_16x16x32_bf16 v[100:103], v[190:193], v[166:169], v[100:103]
	v_mfma_f32_16x16x32_bf16 v[92:95], v[190:193], v[174:177], v[92:95]
	v_mfma_f32_16x16x32_bf16 v[84:87], v[198:201], v[166:169], v[84:87]
	v_mfma_f32_16x16x32_bf16 v[76:79], v[198:201], v[174:177], v[76:79]
	v_mfma_f32_16x16x32_bf16 v[68:71], v[208:211], v[166:169], v[68:71]
	v_mfma_f32_16x16x32_bf16 v[64:67], v[208:211], v[174:177], v[64:67]
	v_mfma_f32_16x16x32_bf16 v[116:119], v[186:189], v[170:173], v[116:119]
	v_mfma_f32_16x16x32_bf16 v[112:115], v[186:189], v[178:181], v[112:115]
	v_mfma_f32_16x16x32_bf16 v[100:103], v[194:197], v[170:173], v[100:103]
	v_mfma_f32_16x16x32_bf16 v[92:95], v[194:197], v[178:181], v[92:95]
	v_mfma_f32_16x16x32_bf16 v[84:87], v[202:205], v[170:173], v[84:87]
	v_mfma_f32_16x16x32_bf16 v[76:79], v[202:205], v[178:181], v[76:79]
	v_mfma_f32_16x16x32_bf16 v[68:71], v[212:215], v[170:173], v[68:71]
	v_mfma_f32_16x16x32_bf16 v[64:67], v[212:215], v[178:181], v[64:67]
	s_setprio 0
	s_barrier
; #define PG8_STAGE(bufoff, gbase, voff) do { _Pragma("unroll") for (int _i = 0; _i < 2; ++_i) \
;         __builtin_amdgcn_global_load_lds((const unsigned*)((const char*)(gbase) + (voff)[_i]), (LAS unsigned*)(lds + (bufoff) + ldsw + _i * 8192), 16, 0, 0); } while (0)
; #define PG8_LDA(dst, b, h) do { _Pragma("unroll") for (int m = 0; m < 4; ++m) _Pragma("unroll") for (int k = 0; k < 2; ++k) dst[m][k] = *(const LAS bf16x8*)(lds + PG8_SA(b, h) + aoff + m * 2048 + k * 1024); } while (0)
; #define PG8_WAIT_V(n) asm volatile("s_waitcnt vmcnt(" #n ")" ::: "memory")
; #define PG8_WAIT_L(n) asm volatile("s_waitcnt lgkmcnt(" #n ")" ::: "memory")
; #define PG8_BAR __builtin_amdgcn_s_barrier()
; #define PG8_SCHED __builtin_amdgcn_sched_barrier(0)
; template <class Epi, class Sched, bool SWAPD = false>
; __device__ __forceinline__ void gemm_phase(LAS unsigned char* lds, const Gemm g, const Sched& S, const Epi& E) {
;     ...
;             PG8_LDA(At, 1, 1); PG8_STAGE(PG8_SB(1, 0), b3, voffB); PG8_STAGE(PG8_SB(1, 1), b3 + hstepB, voffB); PG8_STAGE(PG8_SA(1, 0), a3, voffA);
;             PG8_WAIT_V(8); PG8_WAIT_L(0); PG8_BAR; PG8_MMA(1, 0, At, B0); PG8_MMA(1, 1, At, B1); PG8_BAR; PG8_SCHED;
;         }
;         if (wr == 0) PG8_BAR;
	s_add_i32 s44, s62, s21
	v_lshl_add_u64 v[216:217], v[216:217], 0, s[12:13]
	s_mov_b32 m0, s44
	ds_read_b128 v[182:185], v153 offset:49152
	ds_read_b128 v[186:189], v153 offset:50176
	ds_read_b128 v[190:193], v153 offset:51200
	ds_read_b128 v[194:197], v153 offset:52224
	ds_read_b128 v[198:201], v153 offset:53248
	ds_read_b128 v[202:205], v153 offset:54272
	ds_read_b128 v[208:211], v153 offset:55296
	ds_read_b128 v[212:215], v153 offset:56320
	global_load_lds_dwordx4 v[216:217], off
	s_add_i32 m0, s44, 0x2000
	s_add_u32 s42, s42, 0x20080
	v_lshl_add_u64 v[216:217], v[218:219], 0, s[12:13]
	s_addc_u32 s43, s43, 0
	s_add_i32 s44, s63, s21
	global_load_lds_dwordx4 v[216:217], off
	v_lshl_add_u64 v[216:217], s[42:43], 0, v[128:129]
	s_mov_b32 m0, s44
	s_nop 0
	global_load_lds_dwordx4 v[216:217], off
	v_lshl_add_u64 v[216:217], s[42:43], 0, v[130:131]
	s_add_i32 m0, s44, 0x2000
	s_nop 0
	global_load_lds_dwordx4 v[216:217], off
	v_lshl_add_u64 v[216:217], v[220:221], 0, s[12:13]
	s_mov_b32 m0, s52
	s_nop 0
	global_load_lds_dwordx4 v[216:217], off
	v_lshl_add_u64 v[216:217], v[222:223], 0, s[12:13]
	s_mov_b32 m0, s53
	s_nop 0
	global_load_lds_dwordx4 v[216:217], off
	s_waitcnt vmcnt(8)
	s_waitcnt lgkmcnt(0)
	s_barrier
	s_setprio 1
	v_mfma_f32_16x16x32_bf16 v[60:63], v[182:185], v[142:145], v[60:63]
	v_mfma_f32_16x16x32_bf16 v[56:59], v[182:185], v[158:161], v[56:59]
	v_mfma_f32_16x16x32_bf16 v[48:51], v[190:193], v[142:145], v[48:51]
	v_mfma_f32_16x16x32_bf16 v[40:43], v[190:193], v[158:161], v[40:43]
	v_mfma_f32_16x16x32_bf16 v[32:35], v[198:201], v[142:145], v[32:35]
	v_mfma_f32_16x16x32_bf16 v[24:27], v[198:201], v[158:161], v[24:27]
	v_mfma_f32_16x16x32_bf16 v[16:19], v[208:211], v[142:145], v[16:19]
	v_mfma_f32_16x16x32_bf16 v[8:11], v[208:211], v[158:161], v[8:11]
	v_mfma_f32_16x16x32_bf16 v[60:63], v[186:189], v[154:157], v[60:63]
	v_mfma_f32_16x16x32_bf16 v[56:59], v[186:189], v[162:165], v[56:59]
	v_mfma_f32_16x16x32_bf16 v[48:51], v[194:197], v[154:157], v[48:51]
	v_mfma_f32_16x16x32_bf16 v[40:43], v[194:197], v[162:165], v[40:43]
	v_mfma_f32_16x16x32_bf16 v[32:35], v[202:205], v[154:157], v[32:35]
	v_mfma_f32_16x16x32_bf16 v[24:27], v[202:205], v[162:165], v[24:27]
	v_mfma_f32_16x16x32_bf16 v[16:19], v[212:215], v[154:157], v[16:19]
	v_mfma_f32_16x16x32_bf16 v[8:11], v[212:215], v[162:165], v[8:11]
	s_setprio 0
	s_setprio 1
	v_mfma_f32_16x16x32_bf16 v[52:55], v[182:185], v[166:169], v[52:55]
	v_mfma_f32_16x16x32_bf16 v[44:47], v[182:185], v[174:177], v[44:47]
	v_mfma_f32_16x16x32_bf16 v[36:39], v[190:193], v[166:169], v[36:39]
	v_mfma_f32_16x16x32_bf16 v[28:31], v[190:193], v[174:177], v[28:31]
	v_mfma_f32_16x16x32_bf16 v[20:23], v[198:201], v[166:169], v[20:23]
	v_mfma_f32_16x16x32_bf16 v[12:15], v[198:201], v[174:177], v[12:15]
	v_mfma_f32_16x16x32_bf16 v[4:7], v[208:211], v[166:169], v[4:7]
	v_mfma_f32_16x16x32_bf16 v[0:3], v[208:211], v[174:177], v[0:3]
	v_mfma_f32_16x16x32_bf16 v[52:55], v[186:189], v[170:173], v[52:55]
	v_mfma_f32_16x16x32_bf16 v[44:47], v[186:189], v[178:181], v[44:47]
	v_mfma_f32_16x16x32_bf16 v[36:39], v[194:197], v[170:173], v[36:39]
	v_mfma_f32_16x16x32_bf16 v[28:31], v[194:197], v[178:181], v[28:31]
	v_mfma_f32_16x16x32_bf16 v[20:23], v[202:205], v[170:173], v[20:23]
	v_mfma_f32_16x16x32_bf16 v[12:15], v[202:205], v[178:181], v[12:15]
	v_mfma_f32_16x16x32_bf16 v[4:7], v[212:215], v[170:173], v[4:7]
	v_mfma_f32_16x16x32_bf16 v[0:3], v[212:215], v[178:181], v[0:3]
	s_setprio 0
	s_barrier
	s_add_i32 s61, s61, 2
	s_add_u32 s40, s40, 0x100
	s_addc_u32 s41, s41, 0
	s_add_u32 s59, s59, 0x100
	s_addc_u32 s60, s60, 0
	s_cmp_gt_u32 s61, 5
	s_cbranch_scc0 .LBB0_1531
	s_and_b64 vcc, exec, s[22:23]
	s_cbranch_vccz .LBB0_1534
	s_barrier

; #define PG8_STAGE(bufoff, gbase, voff) do { _Pragma("unroll") for (int _i = 0; _i < 2; ++_i) \
;         __builtin_amdgcn_global_load_lds((const unsigned*)((const char*)(gbase) + (voff)[_i]), (LAS unsigned*)(lds + (bufoff) + ldsw + _i * 8192), 16, 0, 0); } while (0)
; #define PG8_LDA(dst, b, h) do { _Pragma("unroll") for (int m = 0; m < 4; ++m) _Pragma("unroll") for (int k = 0; k < 2; ++k) dst[m][k] = *(const LAS bf16x8*)(lds + PG8_SA(b, h) + aoff + m * 2048 + k * 1024); } while (0)
; #define PG8_LDB(dst, b, h) do { _Pragma("unroll") for (int n = 0; n < 2; ++n) _Pragma("unroll") for (int k = 0; k < 2; ++k) dst[n][k] = *(const LAS bf16x8*)(lds + PG8_SB(b, h) + boff + n * 2048 + k * 1024); } while (0)
; #define PG8_WAIT_V(n) asm volatile("s_waitcnt vmcnt(" #n ")" ::: "memory")
; #define PG8_WAIT_L(n) asm volatile("s_waitcnt lgkmcnt(" #n ")" ::: "memory")
; #define PG8_BAR __builtin_amdgcn_s_barrier()
; #define PG8_SCHED __builtin_amdgcn_sched_barrier(0)
; template <class Epi, class Sched, bool SWAPD = false>
; __device__ __forceinline__ void gemm_phase(LAS unsigned char* lds, const Gemm g, const Sched& S, const Epi& E) {
;     ...
;             const bool last = (t == nt - 2);
;             const char* a1 = cA + (size_t)(t + 1) * kstepA;
;             const char* a2 = last ? nA : cA + (size_t)(t + 2) * kstepA; const char* b2 = last ? nB : cB + (size_t)(t + 2) * kstep;
;             const char* a3 = a2 + kstepA; const char* b3 = b2 + kstep;
;             PG8_LDB(B0, 0, 0); PG8_LDB(B1, 0, 1); PG8_SCHED; PG8_LDA(At, 0, 0); PG8_STAGE(PG8_SA(1, 1), a1 + hstepA, voffA);
;             PG8_WAIT_V(8); PG8_WAIT_L(0); PG8_BAR; PG8_MMA(0, 0, At, B0); PG8_MMA(0, 1, At, B1); PG8_BAR; PG8_SCHED;
;             PG8_LDA(At, 0, 1); PG8_STAGE(PG8_SB(0, 0), b2, voffB); PG8_STAGE(PG8_SB(0, 1), b2 + hstepB, voffB); PG8_STAGE(PG8_SA(0, 0), a2, voffA);
;             PG8_WAIT_V(8); PG8_WAIT_L(0); PG8_BAR; PG8_MMA(1, 0, At, B0); PG8_MMA(1, 1, At, B1); PG8_BAR; PG8_SCHED;
.LBB0_1661:
	ds_read_b128 v[154:157], v150
	ds_read_b128 v[158:161], v150 offset:1024
	ds_read_b128 v[162:165], v150 offset:2048
	ds_read_b128 v[166:169], v150 offset:3072
	ds_read_b128 v[170:173], v151
	ds_read_b128 v[174:177], v151 offset:1024
	ds_read_b128 v[178:181], v151 offset:2048
	ds_read_b128 v[182:185], v151 offset:3072
	s_add_u32 s46, s44, 0x100
	s_addc_u32 s47, s45, 0
	s_add_u32 s50, s75, s44
	s_addc_u32 s51, s76, s45
	s_cmp_eq_u32 s77, 4
	s_cselect_b32 s52, s74, s50
	s_cselect_b32 s50, 0, s46
	s_cselect_b32 s53, s9, s51
	s_cselect_b32 s51, 0, s47
	s_add_u32 s50, s0, s50
	s_addc_u32 s51, s1, s51
	s_mov_b32 m0, s62
	v_lshl_add_u64 v[220:221], v[144:145], 0, s[44:45]
	ds_read_b128 v[186:189], v152
	ds_read_b128 v[190:193], v152 offset:1024
	ds_read_b128 v[194:197], v152 offset:2048
	ds_read_b128 v[198:201], v152 offset:3072
	ds_read_b128 v[202:205], v152 offset:4096
	ds_read_b128 v[208:211], v152 offset:5120
	ds_read_b128 v[212:215], v152 offset:6144
	ds_read_b128 v[216:219], v152 offset:7168
	global_load_lds_dwordx4 v[220:221], off
	v_lshl_add_u64 v[220:221], v[146:147], 0, s[44:45]
	s_mov_b32 m0, s63
	s_nop 0
	global_load_lds_dwordx4 v[220:221], off
	s_waitcnt vmcnt(8)
	s_waitcnt lgkmcnt(0)
	s_barrier
	s_setprio 1
	v_mfma_f32_16x16x32_bf16 v[124:127], v[154:157], v[186:189], v[124:127]
	v_mfma_f32_16x16x32_bf16 v[120:123], v[162:165], v[186:189], v[120:123]
	v_mfma_f32_16x16x32_bf16 v[112:115], v[154:157], v[194:197], v[112:115]
	v_mfma_f32_16x16x32_bf16 v[104:107], v[162:165], v[194:197], v[104:107]
	v_mfma_f32_16x16x32_bf16 v[96:99], v[154:157], v[202:205], v[96:99]
	v_mfma_f32_16x16x32_bf16 v[88:91], v[162:165], v[202:205], v[88:91]
	v_mfma_f32_16x16x32_bf16 v[80:83], v[154:157], v[212:215], v[80:83]
	v_mfma_f32_16x16x32_bf16 v[72:75], v[162:165], v[212:215], v[72:75]
	v_mfma_f32_16x16x32_bf16 v[124:127], v[158:161], v[190:193], v[124:127]
	v_mfma_f32_16x16x32_bf16 v[120:123], v[166:169], v[190:193], v[120:123]
	v_mfma_f32_16x16x32_bf16 v[112:115], v[158:161], v[198:201], v[112:115]
	v_mfma_f32_16x16x32_bf16 v[104:107], v[166:169], v[198:201], v[104:107]
	v_mfma_f32_16x16x32_bf16 v[96:99], v[158:161], v[208:211], v[96:99]
	v_mfma_f32_16x16x32_bf16 v[88:91], v[166:169], v[208:211], v[88:91]
	v_mfma_f32_16x16x32_bf16 v[80:83], v[158:161], v[216:219], v[80:83]
	v_mfma_f32_16x16x32_bf16 v[72:75], v[166:169], v[216:219], v[72:75]
	s_setprio 0
	s_setprio 1
	v_mfma_f32_16x16x32_bf16 v[116:119], v[170:173], v[186:189], v[116:119]
	v_mfma_f32_16x16x32_bf16 v[108:111], v[178:181], v[186:189], v[108:111]
	v_mfma_f32_16x16x32_bf16 v[100:103], v[170:173], v[194:197], v[100:103]
	v_mfma_f32_16x16x32_bf16 v[92:95], v[178:181], v[194:197], v[92:95]
	v_mfma_f32_16x16x32_bf16 v[84:87], v[170:173], v[202:205], v[84:87]
	v_mfma_f32_16x16x32_bf16 v[76:79], v[178:181], v[202:205], v[76:79]
	v_mfma_f32_16x16x32_bf16 v[68:71], v[170:173], v[212:215], v[68:71]
	v_mfma_f32_16x16x32_bf16 v[64:67], v[178:181], v[212:215], v[64:67]
	v_mfma_f32_16x16x32_bf16 v[116:119], v[174:177], v[190:193], v[116:119]
	v_mfma_f32_16x16x32_bf16 v[108:111], v[182:185], v[190:193], v[108:111]
	v_mfma_f32_16x16x32_bf16 v[100:103], v[174:177], v[198:201], v[100:103]
	v_mfma_f32_16x16x32_bf16 v[92:95], v[182:185], v[198:201], v[92:95]
	v_mfma_f32_16x16x32_bf16 v[84:87], v[174:177], v[208:211], v[84:87]
	v_mfma_f32_16x16x32_bf16 v[76:79], v[182:185], v[208:211], v[76:79]
	v_mfma_f32_16x16x32_bf16 v[68:71], v[174:177], v[216:219], v[68:71]
	v_mfma_f32_16x16x32_bf16 v[64:67], v[182:185], v[216:219], v[64:67]
	s_setprio 0
	s_barrier
	s_mov_b32 m0, s64
	v_lshl_add_u64 v[220:221], s[50:51], 0, v[132:133]
	s_add_u32 s44, s50, 0x20000
	ds_read_b128 v[186:189], v152 offset:16384
	ds_read_b128 v[190:193], v152 offset:17408
	ds_read_b128 v[194:197], v152 offset:18432
	ds_read_b128 v[198:201], v152 offset:19456
	ds_read_b128 v[202:205], v152 offset:20480
	ds_read_b128 v[208:211], v152 offset:21504
	ds_read_b128 v[212:215], v152 offset:22528
	ds_read_b128 v[216:219], v152 offset:23552
	global_load_lds_dwordx4 v[220:221], off
	v_lshl_add_u64 v[222:223], s[50:51], 0, v[128:129]
	s_mov_b32 m0, s65
	s_addc_u32 s45, s51, 0
	global_load_lds_dwordx4 v[222:223], off
	v_lshl_add_u64 v[224:225], s[44:45], 0, v[132:133]
	s_mov_b32 m0, s66
	v_lshl_add_u64 v[226:227], s[52:53], 0, v[130:131]
	global_load_lds_dwordx4 v[224:225], off
	v_lshl_add_u64 v[224:225], s[44:45], 0, v[128:129]
	s_mov_b32 m0, s67
	s_nop 0
	global_load_lds_dwordx4 v[224:225], off
	v_lshl_add_u64 v[224:225], s[52:53], 0, v[134:135]
	s_mov_b32 m0, s30
	s_nop 0
	global_load_lds_dwordx4 v[224:225], off
	s_mov_b32 m0, s31
	s_nop 0
	global_load_lds_dwordx4 v[226:227], off
	s_waitcnt vmcnt(8)
	s_waitcnt lgkmcnt(0)
	s_barrier
; #define PG8_STAGE(bufoff, gbase, voff) do { _Pragma("unroll") for (int _i = 0; _i < 2; ++_i) \
;         __builtin_amdgcn_global_load_lds((const unsigned*)((const char*)(gbase) + (voff)[_i]), (LAS unsigned*)(lds + (bufoff) + ldsw + _i * 8192), 16, 0, 0); } while (0)
; #define PG8_LDA(dst, b, h) do { _Pragma("unroll") for (int m = 0; m < 4; ++m) _Pragma("unroll") for (int k = 0; k < 2; ++k) dst[m][k] = *(const LAS bf16x8*)(lds + PG8_SA(b, h) + aoff + m * 2048 + k * 1024); } while (0)
; #define PG8_LDB(dst, b, h) do { _Pragma("unroll") for (int n = 0; n < 2; ++n) _Pragma("unroll") for (int k = 0; k < 2; ++k) dst[n][k] = *(const LAS bf16x8*)(lds + PG8_SB(b, h) + boff + n * 2048 + k * 1024); } while (0)
; #define PG8_WAIT_V(n) asm volatile("s_waitcnt vmcnt(" #n ")" ::: "memory")
; #define PG8_WAIT_L(n) asm volatile("s_waitcnt lgkmcnt(" #n ")" ::: "memory")
; #define PG8_BAR __builtin_amdgcn_s_barrier()
; #define PG8_SCHED __builtin_amdgcn_sched_barrier(0)
; template <class Epi, class Sched, bool SWAPD = false>
; __device__ __forceinline__ void gemm_phase(LAS unsigned char* lds, const Gemm g, const Sched& S, const Epi& E) {
;     ...
;             PG8_WAIT_V(8); PG8_WAIT_L(0); PG8_BAR; PG8_MMA(1, 0, At, B0); PG8_MMA(1, 1, At, B1); PG8_BAR; PG8_SCHED;
;             PG8_LDB(B0, 1, 0); PG8_LDB(B1, 1, 1); PG8_SCHED; PG8_LDA(At, 1, 0); PG8_STAGE(PG8_SA(0, 1), a2 + hstepA, voffA);
;             PG8_WAIT_V(8); PG8_WAIT_L(0); PG8_BAR; PG8_MMA(0, 0, At, B0); PG8_MMA(0, 1, At, B1); PG8_BAR; PG8_SCHED;
	s_setprio 1
	v_mfma_f32_16x16x32_bf16 v[60:63], v[154:157], v[186:189], v[60:63]
	v_mfma_f32_16x16x32_bf16 v[56:59], v[162:165], v[186:189], v[56:59]
	v_mfma_f32_16x16x32_bf16 v[48:51], v[154:157], v[194:197], v[48:51]
	v_mfma_f32_16x16x32_bf16 v[40:43], v[162:165], v[194:197], v[40:43]
	v_mfma_f32_16x16x32_bf16 v[32:35], v[154:157], v[202:205], v[32:35]
	v_mfma_f32_16x16x32_bf16 v[24:27], v[162:165], v[202:205], v[24:27]
	v_mfma_f32_16x16x32_bf16 v[16:19], v[154:157], v[212:215], v[16:19]
	v_mfma_f32_16x16x32_bf16 v[8:11], v[162:165], v[212:215], v[8:11]
	v_mfma_f32_16x16x32_bf16 v[60:63], v[158:161], v[190:193], v[60:63]
	v_mfma_f32_16x16x32_bf16 v[56:59], v[166:169], v[190:193], v[56:59]
	v_mfma_f32_16x16x32_bf16 v[48:51], v[158:161], v[198:201], v[48:51]
	v_mfma_f32_16x16x32_bf16 v[40:43], v[166:169], v[198:201], v[40:43]
	v_mfma_f32_16x16x32_bf16 v[32:35], v[158:161], v[208:211], v[32:35]
	v_mfma_f32_16x16x32_bf16 v[24:27], v[166:169], v[208:211], v[24:27]
	v_mfma_f32_16x16x32_bf16 v[16:19], v[158:161], v[216:219], v[16:19]
	v_mfma_f32_16x16x32_bf16 v[8:11], v[166:169], v[216:219], v[8:11]
	s_setprio 0
	s_setprio 1
	v_mfma_f32_16x16x32_bf16 v[52:55], v[170:173], v[186:189], v[52:55]
	v_mfma_f32_16x16x32_bf16 v[44:47], v[178:181], v[186:189], v[44:47]
	v_mfma_f32_16x16x32_bf16 v[36:39], v[170:173], v[194:197], v[36:39]
	v_mfma_f32_16x16x32_bf16 v[28:31], v[178:181], v[194:197], v[28:31]
	v_mfma_f32_16x16x32_bf16 v[20:23], v[170:173], v[202:205], v[20:23]
	v_mfma_f32_16x16x32_bf16 v[12:15], v[178:181], v[202:205], v[12:15]
	v_mfma_f32_16x16x32_bf16 v[4:7], v[170:173], v[212:215], v[4:7]
	v_mfma_f32_16x16x32_bf16 v[0:3], v[178:181], v[212:215], v[0:3]
	v_mfma_f32_16x16x32_bf16 v[52:55], v[174:177], v[190:193], v[52:55]
	v_mfma_f32_16x16x32_bf16 v[44:47], v[182:185], v[190:193], v[44:47]
	v_mfma_f32_16x16x32_bf16 v[36:39], v[174:177], v[198:201], v[36:39]
	v_mfma_f32_16x16x32_bf16 v[28:31], v[182:185], v[198:201], v[28:31]
	v_mfma_f32_16x16x32_bf16 v[20:23], v[174:177], v[208:211], v[20:23]
	v_mfma_f32_16x16x32_bf16 v[12:15], v[182:185], v[208:211], v[12:15]
	v_mfma_f32_16x16x32_bf16 v[4:7], v[174:177], v[216:219], v[4:7]
	v_mfma_f32_16x16x32_bf16 v[0:3], v[182:185], v[216:219], v[0:3]
	s_setprio 0
	s_barrier
	s_add_i32 s78, 0, 0x18000
	v_add_u32_e32 v136, s78, v149
	s_add_i32 s79, 0, 0x1c000
	ds_read_b128 v[154:157], v136
	ds_read_b128 v[158:161], v136 offset:1024
	ds_read_b128 v[162:165], v136 offset:2048
	ds_read_b128 v[166:169], v136 offset:3072
	v_add_u32_e32 v136, s79, v149
	ds_read_b128 v[170:173], v136
	ds_read_b128 v[174:177], v136 offset:1024
	ds_read_b128 v[178:181], v136 offset:2048
	ds_read_b128 v[182:185], v136 offset:3072
	s_add_u32 s44, s52, 0x80000
	s_addc_u32 s45, s53, 0
	s_mov_b32 m0, s33
	v_lshl_add_u64 v[228:229], s[44:45], 0, v[134:135]
	ds_read_b128 v[186:189], v152 offset:32768
	ds_read_b128 v[190:193], v152 offset:33792
	ds_read_b128 v[194:197], v152 offset:34816
	ds_read_b128 v[198:201], v152 offset:35840
	ds_read_b128 v[202:205], v152 offset:36864
	ds_read_b128 v[208:211], v152 offset:37888
	ds_read_b128 v[212:215], v152 offset:38912
	ds_read_b128 v[216:219], v152 offset:39936
	global_load_lds_dwordx4 v[228:229], off
	v_lshl_add_u64 v[228:229], s[44:45], 0, v[130:131]
	s_mov_b32 m0, s54
	s_nop 0
	global_load_lds_dwordx4 v[228:229], off
	s_waitcnt vmcnt(8)
	s_waitcnt lgkmcnt(0)
	s_barrier
	s_setprio 1
	v_mfma_f32_16x16x32_bf16 v[124:127], v[154:157], v[186:189], v[124:127]
	v_mfma_f32_16x16x32_bf16 v[120:123], v[162:165], v[186:189], v[120:123]
	v_mfma_f32_16x16x32_bf16 v[112:115], v[154:157], v[194:197], v[112:115]
	v_mfma_f32_16x16x32_bf16 v[104:107], v[162:165], v[194:197], v[104:107]
	v_mfma_f32_16x16x32_bf16 v[96:99], v[154:157], v[202:205], v[96:99]
	v_mfma_f32_16x16x32_bf16 v[88:91], v[162:165], v[202:205], v[88:91]
	v_mfma_f32_16x16x32_bf16 v[80:83], v[154:157], v[212:215], v[80:83]
	v_mfma_f32_16x16x32_bf16 v[72:75], v[162:165], v[212:215], v[72:75]
	v_mfma_f32_16x16x32_bf16 v[124:127], v[158:161], v[190:193], v[124:127]
	v_mfma_f32_16x16x32_bf16 v[120:123], v[166:169], v[190:193], v[120:123]
	v_mfma_f32_16x16x32_bf16 v[112:115], v[158:161], v[198:201], v[112:115]
	v_mfma_f32_16x16x32_bf16 v[104:107], v[166:169], v[198:201], v[104:107]
	v_mfma_f32_16x16x32_bf16 v[96:99], v[158:161], v[208:211], v[96:99]
	v_mfma_f32_16x16x32_bf16 v[88:91], v[166:169], v[208:211], v[88:91]
	v_mfma_f32_16x16x32_bf16 v[80:83], v[158:161], v[216:219], v[80:83]
	v_mfma_f32_16x16x32_bf16 v[72:75], v[166:169], v[216:219], v[72:75]
	s_setprio 0
	s_setprio 1
	v_mfma_f32_16x16x32_bf16 v[116:119], v[170:173], v[186:189], v[116:119]
	v_mfma_f32_16x16x32_bf16 v[108:111], v[178:181], v[186:189], v[108:111]
	v_mfma_f32_16x16x32_bf16 v[100:103], v[170:173], v[194:197], v[100:103]
	v_mfma_f32_16x16x32_bf16 v[92:95], v[178:181], v[194:197], v[92:95]
	v_mfma_f32_16x16x32_bf16 v[84:87], v[170:173], v[202:205], v[84:87]
	v_mfma_f32_16x16x32_bf16 v[76:79], v[178:181], v[202:205], v[76:79]
	v_mfma_f32_16x16x32_bf16 v[68:71], v[170:173], v[212:215], v[68:71]
	v_mfma_f32_16x16x32_bf16 v[64:67], v[178:181], v[212:215], v[64:67]
	v_mfma_f32_16x16x32_bf16 v[116:119], v[174:177], v[190:193], v[116:119]
	v_mfma_f32_16x16x32_bf16 v[108:111], v[182:185], v[190:193], v[108:111]
	v_mfma_f32_16x16x32_bf16 v[100:103], v[174:177], v[198:201], v[100:103]
	v_mfma_f32_16x16x32_bf16 v[92:95], v[182:185], v[198:201], v[92:95]
	v_mfma_f32_16x16x32_bf16 v[84:87], v[174:177], v[208:211], v[84:87]
	v_mfma_f32_16x16x32_bf16 v[76:79], v[182:185], v[208:211], v[76:79]
	v_mfma_f32_16x16x32_bf16 v[68:71], v[174:177], v[216:219], v[68:71]
	v_mfma_f32_16x16x32_bf16 v[64:67], v[182:185], v[216:219], v[64:67]
	s_setprio 0
	s_barrier
; #define PG8_STAGE(bufoff, gbase, voff) do { _Pragma("unroll") for (int _i = 0; _i < 2; ++_i) \
;         __builtin_amdgcn_global_load_lds((const unsigned*)((const char*)(gbase) + (voff)[_i]), (LAS unsigned*)(lds + (bufoff) + ldsw + _i * 8192), 16, 0, 0); } while (0)
; #define PG8_LDA(dst, b, h) do { _Pragma("unroll") for (int m = 0; m < 4; ++m) _Pragma("unroll") for (int k = 0; k < 2; ++k) dst[m][k] = *(const LAS bf16x8*)(lds + PG8_SA(b, h) + aoff + m * 2048 + k * 1024); } while (0)
; #define PG8_WAIT_V(n) asm volatile("s_waitcnt vmcnt(" #n ")" ::: "memory")
; #define PG8_WAIT_L(n) asm volatile("s_waitcnt lgkmcnt(" #n ")" ::: "memory")
; #define PG8_BAR __builtin_amdgcn_s_barrier()
; #define PG8_SCHED __builtin_amdgcn_sched_barrier(0)
; template <class Epi, class Sched, bool SWAPD = false>
; __device__ __forceinline__ void gemm_phase(LAS unsigned char* lds, const Gemm g, const Sched& S, const Epi& E) {
;     ...
;             PG8_LDA(At, 1, 1); PG8_STAGE(PG8_SB(1, 0), b3, voffB); PG8_STAGE(PG8_SB(1, 1), b3 + hstepB, voffB); PG8_STAGE(PG8_SA(1, 0), a3, voffA);
;             PG8_WAIT_V(8); PG8_WAIT_L(0); PG8_BAR; PG8_MMA(1, 0, At, B0); PG8_MMA(1, 1, At, B1); PG8_BAR; PG8_SCHED;
;         }
;         if (wr == 0) PG8_BAR;
	s_add_i32 s44, s78, s21
	v_lshl_add_u64 v[220:221], v[220:221], 0, s[24:25]
	s_mov_b32 m0, s44
	ds_read_b128 v[186:189], v152 offset:49152
	ds_read_b128 v[190:193], v152 offset:50176
	ds_read_b128 v[194:197], v152 offset:51200
	ds_read_b128 v[198:201], v152 offset:52224
	ds_read_b128 v[202:205], v152 offset:53248
	ds_read_b128 v[208:211], v152 offset:54272
	ds_read_b128 v[212:215], v152 offset:55296
	ds_read_b128 v[216:219], v152 offset:56320
	global_load_lds_dwordx4 v[220:221], off
	s_add_i32 m0, s44, 0x2000
	s_add_u32 s44, s50, 0x20080
	v_lshl_add_u64 v[220:221], v[222:223], 0, s[24:25]
	s_addc_u32 s45, s51, 0
	s_add_i32 s50, s79, s21
	global_load_lds_dwordx4 v[220:221], off
	v_lshl_add_u64 v[220:221], s[44:45], 0, v[132:133]
	s_mov_b32 m0, s50
	s_nop 0
	global_load_lds_dwordx4 v[220:221], off
	v_lshl_add_u64 v[220:221], s[44:45], 0, v[128:129]
	s_add_i32 m0, s50, 0x2000
	s_nop 0
	global_load_lds_dwordx4 v[220:221], off
	v_lshl_add_u64 v[220:221], v[224:225], 0, s[24:25]
	s_mov_b32 m0, s56
	s_nop 0
	global_load_lds_dwordx4 v[220:221], off
	v_lshl_add_u64 v[220:221], v[226:227], 0, s[24:25]
	s_mov_b32 m0, s57
	s_nop 0
	global_load_lds_dwordx4 v[220:221], off
	s_waitcnt vmcnt(8)
	s_waitcnt lgkmcnt(0)
	s_barrier
	s_setprio 1
	v_mfma_f32_16x16x32_bf16 v[60:63], v[154:157], v[186:189], v[60:63]
	v_mfma_f32_16x16x32_bf16 v[56:59], v[162:165], v[186:189], v[56:59]
	v_mfma_f32_16x16x32_bf16 v[48:51], v[154:157], v[194:197], v[48:51]
	v_mfma_f32_16x16x32_bf16 v[40:43], v[162:165], v[194:197], v[40:43]
	v_mfma_f32_16x16x32_bf16 v[32:35], v[154:157], v[202:205], v[32:35]
	v_mfma_f32_16x16x32_bf16 v[24:27], v[162:165], v[202:205], v[24:27]
	v_mfma_f32_16x16x32_bf16 v[16:19], v[154:157], v[212:215], v[16:19]
	v_mfma_f32_16x16x32_bf16 v[8:11], v[162:165], v[212:215], v[8:11]
	v_mfma_f32_16x16x32_bf16 v[60:63], v[158:161], v[190:193], v[60:63]
	v_mfma_f32_16x16x32_bf16 v[56:59], v[166:169], v[190:193], v[56:59]
	v_mfma_f32_16x16x32_bf16 v[48:51], v[158:161], v[198:201], v[48:51]
	v_mfma_f32_16x16x32_bf16 v[40:43], v[166:169], v[198:201], v[40:43]
	v_mfma_f32_16x16x32_bf16 v[32:35], v[158:161], v[208:211], v[32:35]
	v_mfma_f32_16x16x32_bf16 v[24:27], v[166:169], v[208:211], v[24:27]
	v_mfma_f32_16x16x32_bf16 v[16:19], v[158:161], v[216:219], v[16:19]
	v_mfma_f32_16x16x32_bf16 v[8:11], v[166:169], v[216:219], v[8:11]
	s_setprio 0
	s_setprio 1
	v_mfma_f32_16x16x32_bf16 v[52:55], v[170:173], v[186:189], v[52:55]
	v_mfma_f32_16x16x32_bf16 v[44:47], v[178:181], v[186:189], v[44:47]
	v_mfma_f32_16x16x32_bf16 v[36:39], v[170:173], v[194:197], v[36:39]
	v_mfma_f32_16x16x32_bf16 v[28:31], v[178:181], v[194:197], v[28:31]
	v_mfma_f32_16x16x32_bf16 v[20:23], v[170:173], v[202:205], v[20:23]
	v_mfma_f32_16x16x32_bf16 v[12:15], v[178:181], v[202:205], v[12:15]
	v_mfma_f32_16x16x32_bf16 v[4:7], v[170:173], v[212:215], v[4:7]
	v_mfma_f32_16x16x32_bf16 v[0:3], v[178:181], v[212:215], v[0:3]
	v_mfma_f32_16x16x32_bf16 v[52:55], v[174:177], v[190:193], v[52:55]
	v_mfma_f32_16x16x32_bf16 v[44:47], v[182:185], v[190:193], v[44:47]
	v_mfma_f32_16x16x32_bf16 v[36:39], v[174:177], v[198:201], v[36:39]
	v_mfma_f32_16x16x32_bf16 v[28:31], v[182:185], v[198:201], v[28:31]
	v_mfma_f32_16x16x32_bf16 v[20:23], v[174:177], v[208:211], v[20:23]
	v_mfma_f32_16x16x32_bf16 v[12:15], v[182:185], v[208:211], v[12:15]
	v_mfma_f32_16x16x32_bf16 v[4:7], v[174:177], v[216:219], v[4:7]
	v_mfma_f32_16x16x32_bf16 v[0:3], v[182:185], v[216:219], v[0:3]
	s_setprio 0
	s_barrier
	s_add_i32 s77, s77, 2
	s_cmp_gt_u32 s77, 5
	s_mov_b64 s[44:45], s[46:47]
	s_cbranch_scc0 .LBB0_1661
	s_and_b64 vcc, exec, s[26:27]
	s_cbranch_vccz .LBB0_1664
	s_barrier

; #define PG8_STAGE(bufoff, gbase, voff) do { _Pragma("unroll") for (int _i = 0; _i < 2; ++_i) \
;         __builtin_amdgcn_global_load_lds((const unsigned*)((const char*)(gbase) + (voff)[_i]), (LAS unsigned*)(lds + (bufoff) + ldsw + _i * 8192), 16, 0, 0); } while (0)
; #define PG8_LDA(dst, b, h) do { _Pragma("unroll") for (int m = 0; m < 4; ++m) _Pragma("unroll") for (int k = 0; k < 2; ++k) dst[m][k] = *(const LAS bf16x8*)(lds + PG8_SA(b, h) + aoff + m * 2048 + k * 1024); } while (0)
; #define PG8_LDB(dst, b, h) do { _Pragma("unroll") for (int n = 0; n < 2; ++n) _Pragma("unroll") for (int k = 0; k < 2; ++k) dst[n][k] = *(const LAS bf16x8*)(lds + PG8_SB(b, h) + boff + n * 2048 + k * 1024); } while (0)
; #define PG8_WAIT_V(n) asm volatile("s_waitcnt vmcnt(" #n ")" ::: "memory")
; #define PG8_WAIT_L(n) asm volatile("s_waitcnt lgkmcnt(" #n ")" ::: "memory")
; #define PG8_BAR __builtin_amdgcn_s_barrier()
; #define PG8_SCHED __builtin_amdgcn_sched_barrier(0)
; template <class Epi, class Sched, bool SWAPD = false>
; __device__ __forceinline__ void gemm_phase(LAS unsigned char* lds, const Gemm g, const Sched& S, const Epi& E) {
;     ...
;             const bool last = (t == nt - 2);
;             const char* a1 = cA + (size_t)(t + 1) * kstepA;
;             const char* a2 = last ? nA : cA + (size_t)(t + 2) * kstepA; const char* b2 = last ? nB : cB + (size_t)(t + 2) * kstep;
;             const char* a3 = a2 + kstepA; const char* b3 = b2 + kstep;
;             PG8_LDB(B0, 0, 0); PG8_LDB(B1, 0, 1); PG8_SCHED; PG8_LDA(At, 0, 0); PG8_STAGE(PG8_SA(1, 1), a1 + hstepA, voffA);
;             PG8_WAIT_V(8); PG8_WAIT_L(0); PG8_BAR; PG8_MMA(0, 0, At, B0); PG8_MMA(0, 1, At, B1); PG8_BAR; PG8_SCHED;
;             PG8_LDA(At, 0, 1); PG8_STAGE(PG8_SB(0, 0), b2, voffB); PG8_STAGE(PG8_SB(0, 1), b2 + hstepB, voffB); PG8_STAGE(PG8_SA(0, 0), a2, voffA);
;             PG8_WAIT_V(8); PG8_WAIT_L(0); PG8_BAR; PG8_MMA(1, 0, At, B0); PG8_MMA(1, 1, At, B1); PG8_BAR; PG8_SCHED;
.LBB0_1737:
	ds_read_b128 v[104:107], v176
	ds_read_b128 v[108:111], v176 offset:1024
	ds_read_b128 v[124:127], v176 offset:2048
	ds_read_b128 v[128:131], v176 offset:3072
	ds_read_b128 v[180:183], v177
	ds_read_b128 v[184:187], v177 offset:1024
	ds_read_b128 v[188:191], v177 offset:2048
	ds_read_b128 v[192:195], v177 offset:3072
	s_add_u32 s42, s40, 0xfffc0080
	s_addc_u32 s43, s41, -1
	s_cmp_eq_u32 s60, 12
	s_cselect_b32 s45, s23, s43
	s_cselect_b32 s44, s25, s42
	s_cselect_b32 s43, s56, s59
	s_cselect_b32 s42, s57, s58
	v_lshl_add_u64 v[172:173], s[40:41], 0, v[164:165]
	s_add_i32 m0, s30, 0xc000
	ds_read_b128 v[196:199], v178
	ds_read_b128 v[200:203], v178 offset:1024
	ds_read_b128 v[208:211], v178 offset:2048
	ds_read_b128 v[212:215], v178 offset:3072
	ds_read_b128 v[216:219], v178 offset:4096
	ds_read_b128 v[220:223], v178 offset:5120
	ds_read_b128 v[224:227], v178 offset:6144
	ds_read_b128 v[228:231], v178 offset:7168
	global_load_lds_dwordx4 v[172:173], off
	v_lshl_add_u64 v[172:173], s[40:41], 0, v[166:167]
	s_add_i32 m0, s30, 0xe000
	s_nop 0
	global_load_lds_dwordx4 v[172:173], off
	s_waitcnt vmcnt(8)
	s_waitcnt lgkmcnt(0)
	s_barrier
	s_setprio 1
	v_mfma_f32_16x16x32_bf16 v[140:143], v[104:107], v[196:199], v[140:143]
	v_mfma_f32_16x16x32_bf16 v[136:139], v[124:127], v[196:199], v[136:139]
	v_mfma_f32_16x16x32_bf16 v[116:119], v[104:107], v[208:211], v[116:119]
	v_mfma_f32_16x16x32_bf16 v[112:115], v[124:127], v[208:211], v[112:115]
	v_mfma_f32_16x16x32_bf16 v[92:95], v[104:107], v[216:219], v[92:95]
	v_mfma_f32_16x16x32_bf16 v[88:91], v[124:127], v[216:219], v[88:91]
	v_mfma_f32_16x16x32_bf16 v[76:79], v[104:107], v[224:227], v[76:79]
	v_mfma_f32_16x16x32_bf16 v[72:75], v[124:127], v[224:227], v[72:75]
	v_mfma_f32_16x16x32_bf16 v[140:143], v[108:111], v[200:203], v[140:143]
	v_mfma_f32_16x16x32_bf16 v[136:139], v[128:131], v[200:203], v[136:139]
	v_mfma_f32_16x16x32_bf16 v[116:119], v[108:111], v[212:215], v[116:119]
	v_mfma_f32_16x16x32_bf16 v[112:115], v[128:131], v[212:215], v[112:115]
	v_mfma_f32_16x16x32_bf16 v[92:95], v[108:111], v[220:223], v[92:95]
	v_mfma_f32_16x16x32_bf16 v[88:91], v[128:131], v[220:223], v[88:91]
	v_mfma_f32_16x16x32_bf16 v[76:79], v[108:111], v[228:231], v[76:79]
	v_mfma_f32_16x16x32_bf16 v[72:75], v[128:131], v[228:231], v[72:75]
	s_setprio 0
	s_setprio 1
	v_mfma_f32_16x16x32_bf16 v[132:135], v[180:183], v[196:199], v[132:135]
	v_mfma_f32_16x16x32_bf16 v[120:123], v[188:191], v[196:199], v[120:123]
	v_mfma_f32_16x16x32_bf16 v[100:103], v[180:183], v[208:211], v[100:103]
	v_mfma_f32_16x16x32_bf16 v[96:99], v[188:191], v[208:211], v[96:99]
	v_mfma_f32_16x16x32_bf16 v[84:87], v[180:183], v[216:219], v[84:87]
	v_mfma_f32_16x16x32_bf16 v[80:83], v[188:191], v[216:219], v[80:83]
	v_mfma_f32_16x16x32_bf16 v[68:71], v[180:183], v[224:227], v[68:71]
	v_mfma_f32_16x16x32_bf16 v[64:67], v[188:191], v[224:227], v[64:67]
	v_mfma_f32_16x16x32_bf16 v[132:135], v[184:187], v[200:203], v[132:135]
	v_mfma_f32_16x16x32_bf16 v[120:123], v[192:195], v[200:203], v[120:123]
	v_mfma_f32_16x16x32_bf16 v[100:103], v[184:187], v[212:215], v[100:103]
	v_mfma_f32_16x16x32_bf16 v[96:99], v[192:195], v[212:215], v[96:99]
	v_mfma_f32_16x16x32_bf16 v[84:87], v[184:187], v[220:223], v[84:87]
	v_mfma_f32_16x16x32_bf16 v[80:83], v[192:195], v[220:223], v[80:83]
	v_mfma_f32_16x16x32_bf16 v[68:71], v[184:187], v[228:231], v[68:71]
	v_mfma_f32_16x16x32_bf16 v[64:67], v[192:195], v[228:231], v[64:67]
	s_setprio 0
	s_barrier
	s_add_i32 s61, s54, s21
	v_lshl_add_u64 v[172:173], s[42:43], 0, v[144:145]
	s_mov_b32 m0, s61
	ds_read_b128 v[196:199], v178 offset:16384
	ds_read_b128 v[200:203], v178 offset:17408
	ds_read_b128 v[208:211], v178 offset:18432
	ds_read_b128 v[212:215], v178 offset:19456
	ds_read_b128 v[216:219], v178 offset:20480
	ds_read_b128 v[220:223], v178 offset:21504
	ds_read_b128 v[224:227], v178 offset:22528
	ds_read_b128 v[228:231], v178 offset:23552
	global_load_lds_dwordx4 v[172:173], off
	s_add_i32 m0, s61, 0x2000
	s_add_u32 s62, s42, 0x40000
	v_lshl_add_u64 v[204:205], s[42:43], 0, v[146:147]
	s_addc_u32 s63, s43, 0
	s_add_i32 s61, s55, s21
	global_load_lds_dwordx4 v[204:205], off
	v_lshl_add_u64 v[232:233], s[62:63], 0, v[144:145]
	s_mov_b32 m0, s61
	v_lshl_add_u64 v[234:235], s[44:45], 0, v[146:147]
	global_load_lds_dwordx4 v[232:233], off
	v_lshl_add_u64 v[232:233], s[62:63], 0, v[146:147]
	s_add_i32 m0, s61, 0x2000
	s_nop 0
	global_load_lds_dwordx4 v[232:233], off
	v_lshl_add_u64 v[232:233], s[44:45], 0, v[144:145]
	s_mov_b32 m0, s30
	s_nop 0
	global_load_lds_dwordx4 v[232:233], off
	s_mov_b32 m0, s31
	s_nop 0
	global_load_lds_dwordx4 v[234:235], off
	s_waitcnt vmcnt(8)
	s_waitcnt lgkmcnt(0)
	s_barrier
; #define PG8_STAGE(bufoff, gbase, voff) do { _Pragma("unroll") for (int _i = 0; _i < 2; ++_i) \
;         __builtin_amdgcn_global_load_lds((const unsigned*)((const char*)(gbase) + (voff)[_i]), (LAS unsigned*)(lds + (bufoff) + ldsw + _i * 8192), 16, 0, 0); } while (0)
; #define PG8_LDA(dst, b, h) do { _Pragma("unroll") for (int m = 0; m < 4; ++m) _Pragma("unroll") for (int k = 0; k < 2; ++k) dst[m][k] = *(const LAS bf16x8*)(lds + PG8_SA(b, h) + aoff + m * 2048 + k * 1024); } while (0)
; #define PG8_LDB(dst, b, h) do { _Pragma("unroll") for (int n = 0; n < 2; ++n) _Pragma("unroll") for (int k = 0; k < 2; ++k) dst[n][k] = *(const LAS bf16x8*)(lds + PG8_SB(b, h) + boff + n * 2048 + k * 1024); } while (0)
; #define PG8_WAIT_V(n) asm volatile("s_waitcnt vmcnt(" #n ")" ::: "memory")
; #define PG8_WAIT_L(n) asm volatile("s_waitcnt lgkmcnt(" #n ")" ::: "memory")
; #define PG8_BAR __builtin_amdgcn_s_barrier()
; #define PG8_SCHED __builtin_amdgcn_sched_barrier(0)
; template <class Epi, class Sched, bool SWAPD = false>
; __device__ __forceinline__ void gemm_phase(LAS unsigned char* lds, const Gemm g, const Sched& S, const Epi& E) {
;     ...
;             PG8_WAIT_V(8); PG8_WAIT_L(0); PG8_BAR; PG8_MMA(1, 0, At, B0); PG8_MMA(1, 1, At, B1); PG8_BAR; PG8_SCHED;
;             PG8_LDB(B0, 1, 0); PG8_LDB(B1, 1, 1); PG8_SCHED; PG8_LDA(At, 1, 0); PG8_STAGE(PG8_SA(0, 1), a2 + hstepA, voffA);
;             PG8_WAIT_V(8); PG8_WAIT_L(0); PG8_BAR; PG8_MMA(0, 0, At, B0); PG8_MMA(0, 1, At, B1); PG8_BAR; PG8_SCHED;
	s_setprio 1
	v_mfma_f32_16x16x32_bf16 v[60:63], v[104:107], v[196:199], v[60:63]
	v_mfma_f32_16x16x32_bf16 v[56:59], v[124:127], v[196:199], v[56:59]
	v_mfma_f32_16x16x32_bf16 v[44:47], v[104:107], v[208:211], v[44:47]
	v_mfma_f32_16x16x32_bf16 v[40:43], v[124:127], v[208:211], v[40:43]
	v_mfma_f32_16x16x32_bf16 v[28:31], v[104:107], v[216:219], v[28:31]
	v_mfma_f32_16x16x32_bf16 v[24:27], v[124:127], v[216:219], v[24:27]
	v_mfma_f32_16x16x32_bf16 v[12:15], v[104:107], v[224:227], v[12:15]
	v_mfma_f32_16x16x32_bf16 v[8:11], v[124:127], v[224:227], v[8:11]
	v_mfma_f32_16x16x32_bf16 v[60:63], v[108:111], v[200:203], v[60:63]
	v_mfma_f32_16x16x32_bf16 v[56:59], v[128:131], v[200:203], v[56:59]
	v_mfma_f32_16x16x32_bf16 v[44:47], v[108:111], v[212:215], v[44:47]
	v_mfma_f32_16x16x32_bf16 v[40:43], v[128:131], v[212:215], v[40:43]
	v_mfma_f32_16x16x32_bf16 v[28:31], v[108:111], v[220:223], v[28:31]
	v_mfma_f32_16x16x32_bf16 v[24:27], v[128:131], v[220:223], v[24:27]
	v_mfma_f32_16x16x32_bf16 v[12:15], v[108:111], v[228:231], v[12:15]
	v_mfma_f32_16x16x32_bf16 v[8:11], v[128:131], v[228:231], v[8:11]
	s_setprio 0
	s_setprio 1
	v_mfma_f32_16x16x32_bf16 v[52:55], v[180:183], v[196:199], v[52:55]
	v_mfma_f32_16x16x32_bf16 v[48:51], v[188:191], v[196:199], v[48:51]
	v_mfma_f32_16x16x32_bf16 v[36:39], v[180:183], v[208:211], v[36:39]
	v_mfma_f32_16x16x32_bf16 v[32:35], v[188:191], v[208:211], v[32:35]
	v_mfma_f32_16x16x32_bf16 v[20:23], v[180:183], v[216:219], v[20:23]
	v_mfma_f32_16x16x32_bf16 v[16:19], v[188:191], v[216:219], v[16:19]
	v_mfma_f32_16x16x32_bf16 v[4:7], v[180:183], v[224:227], v[4:7]
	v_mfma_f32_16x16x32_bf16 v[0:3], v[188:191], v[224:227], v[0:3]
	v_mfma_f32_16x16x32_bf16 v[52:55], v[184:187], v[200:203], v[52:55]
	v_mfma_f32_16x16x32_bf16 v[48:51], v[192:195], v[200:203], v[48:51]
	v_mfma_f32_16x16x32_bf16 v[36:39], v[184:187], v[212:215], v[36:39]
	v_mfma_f32_16x16x32_bf16 v[32:35], v[192:195], v[212:215], v[32:35]
	v_mfma_f32_16x16x32_bf16 v[20:23], v[184:187], v[220:223], v[20:23]
	v_mfma_f32_16x16x32_bf16 v[16:19], v[192:195], v[220:223], v[16:19]
	v_mfma_f32_16x16x32_bf16 v[4:7], v[184:187], v[228:231], v[4:7]
	v_mfma_f32_16x16x32_bf16 v[0:3], v[192:195], v[228:231], v[0:3]
	s_setprio 0
	s_barrier
	s_add_i32 s61, 0, 0x18000
	s_add_i32 s62, 0, 0x1c000
	v_add_u32_e32 v128, s61, v174
	v_add_u32_e32 v179, s62, v174
	ds_read_b128 v[104:107], v128
	ds_read_b128 v[108:111], v128 offset:1024
	ds_read_b128 v[124:127], v128 offset:2048
	ds_read_b128 v[128:131], v128 offset:3072
	ds_read_b128 v[180:183], v179
	ds_read_b128 v[184:187], v179 offset:1024
	ds_read_b128 v[188:191], v179 offset:2048
	ds_read_b128 v[192:195], v179 offset:3072
	s_add_u32 s44, s44, 0x40000
	s_addc_u32 s45, s45, 0
	s_mov_b32 m0, s33
	v_lshl_add_u64 v[236:237], s[44:45], 0, v[144:145]
	ds_read_b128 v[196:199], v178 offset:32768
	ds_read_b128 v[200:203], v178 offset:33792
	ds_read_b128 v[208:211], v178 offset:34816
	ds_read_b128 v[212:215], v178 offset:35840
	ds_read_b128 v[216:219], v178 offset:36864
	ds_read_b128 v[220:223], v178 offset:37888
	ds_read_b128 v[224:227], v178 offset:38912
	ds_read_b128 v[228:231], v178 offset:39936
	global_load_lds_dwordx4 v[236:237], off
	v_lshl_add_u64 v[236:237], s[44:45], 0, v[146:147]
	s_mov_b32 m0, s46
	s_nop 0
	global_load_lds_dwordx4 v[236:237], off
	s_waitcnt vmcnt(8)
	s_waitcnt lgkmcnt(0)
	s_barrier
	s_setprio 1
	v_mfma_f32_16x16x32_bf16 v[140:143], v[104:107], v[196:199], v[140:143]
	v_mfma_f32_16x16x32_bf16 v[136:139], v[124:127], v[196:199], v[136:139]
	v_mfma_f32_16x16x32_bf16 v[116:119], v[104:107], v[208:211], v[116:119]
	v_mfma_f32_16x16x32_bf16 v[112:115], v[124:127], v[208:211], v[112:115]
	v_mfma_f32_16x16x32_bf16 v[92:95], v[104:107], v[216:219], v[92:95]
	v_mfma_f32_16x16x32_bf16 v[88:91], v[124:127], v[216:219], v[88:91]
	v_mfma_f32_16x16x32_bf16 v[76:79], v[104:107], v[224:227], v[76:79]
	v_mfma_f32_16x16x32_bf16 v[72:75], v[124:127], v[224:227], v[72:75]
	v_mfma_f32_16x16x32_bf16 v[140:143], v[108:111], v[200:203], v[140:143]
	v_mfma_f32_16x16x32_bf16 v[136:139], v[128:131], v[200:203], v[136:139]
	v_mfma_f32_16x16x32_bf16 v[116:119], v[108:111], v[212:215], v[116:119]
	v_mfma_f32_16x16x32_bf16 v[112:115], v[128:131], v[212:215], v[112:115]
	v_mfma_f32_16x16x32_bf16 v[92:95], v[108:111], v[220:223], v[92:95]
	v_mfma_f32_16x16x32_bf16 v[88:91], v[128:131], v[220:223], v[88:91]
	v_mfma_f32_16x16x32_bf16 v[76:79], v[108:111], v[228:231], v[76:79]
	v_mfma_f32_16x16x32_bf16 v[72:75], v[128:131], v[228:231], v[72:75]
	s_setprio 0
	s_setprio 1
	v_mfma_f32_16x16x32_bf16 v[132:135], v[180:183], v[196:199], v[132:135]
	v_mfma_f32_16x16x32_bf16 v[120:123], v[188:191], v[196:199], v[120:123]
	v_mfma_f32_16x16x32_bf16 v[100:103], v[180:183], v[208:211], v[100:103]
	v_mfma_f32_16x16x32_bf16 v[96:99], v[188:191], v[208:211], v[96:99]
	v_mfma_f32_16x16x32_bf16 v[84:87], v[180:183], v[216:219], v[84:87]
	v_mfma_f32_16x16x32_bf16 v[80:83], v[188:191], v[216:219], v[80:83]
	v_mfma_f32_16x16x32_bf16 v[68:71], v[180:183], v[224:227], v[68:71]
	v_mfma_f32_16x16x32_bf16 v[64:67], v[188:191], v[224:227], v[64:67]
	v_mfma_f32_16x16x32_bf16 v[132:135], v[184:187], v[200:203], v[132:135]
	v_mfma_f32_16x16x32_bf16 v[120:123], v[192:195], v[200:203], v[120:123]
	v_mfma_f32_16x16x32_bf16 v[100:103], v[184:187], v[212:215], v[100:103]
	v_mfma_f32_16x16x32_bf16 v[96:99], v[192:195], v[212:215], v[96:99]
	v_mfma_f32_16x16x32_bf16 v[84:87], v[184:187], v[220:223], v[84:87]
	v_mfma_f32_16x16x32_bf16 v[80:83], v[192:195], v[220:223], v[80:83]
	v_mfma_f32_16x16x32_bf16 v[68:71], v[184:187], v[228:231], v[68:71]
	v_mfma_f32_16x16x32_bf16 v[64:67], v[192:195], v[228:231], v[64:67]
	s_setprio 0
	s_barrier
; #define PG8_STAGE(bufoff, gbase, voff) do { _Pragma("unroll") for (int _i = 0; _i < 2; ++_i) \
;         __builtin_amdgcn_global_load_lds((const unsigned*)((const char*)(gbase) + (voff)[_i]), (LAS unsigned*)(lds + (bufoff) + ldsw + _i * 8192), 16, 0, 0); } while (0)
; #define PG8_LDA(dst, b, h) do { _Pragma("unroll") for (int m = 0; m < 4; ++m) _Pragma("unroll") for (int k = 0; k < 2; ++k) dst[m][k] = *(const LAS bf16x8*)(lds + PG8_SA(b, h) + aoff + m * 2048 + k * 1024); } while (0)
; #define PG8_WAIT_V(n) asm volatile("s_waitcnt vmcnt(" #n ")" ::: "memory")
; #define PG8_WAIT_L(n) asm volatile("s_waitcnt lgkmcnt(" #n ")" ::: "memory")
; #define PG8_BAR __builtin_amdgcn_s_barrier()
; #define PG8_SCHED __builtin_amdgcn_sched_barrier(0)
; template <class Epi, class Sched, bool SWAPD = false>
; __device__ __forceinline__ void gemm_phase(LAS unsigned char* lds, const Gemm g, const Sched& S, const Epi& E) {
;     ...
;             PG8_LDA(At, 1, 1); PG8_STAGE(PG8_SB(1, 0), b3, voffB); PG8_STAGE(PG8_SB(1, 1), b3 + hstepB, voffB); PG8_STAGE(PG8_SA(1, 0), a3, voffA);
;             PG8_WAIT_V(8); PG8_WAIT_L(0); PG8_BAR; PG8_MMA(1, 0, At, B0); PG8_MMA(1, 1, At, B1); PG8_BAR; PG8_SCHED;
;         }
;         if (wr == 0) PG8_BAR;
	s_add_i32 s44, s61, s21
	v_lshl_add_u64 v[172:173], v[172:173], 0, s[8:9]
	s_mov_b32 m0, s44
	ds_read_b128 v[196:199], v178 offset:49152
	ds_read_b128 v[200:203], v178 offset:50176
	ds_read_b128 v[208:211], v178 offset:51200
	ds_read_b128 v[212:215], v178 offset:52224
	ds_read_b128 v[216:219], v178 offset:53248
	ds_read_b128 v[220:223], v178 offset:54272
	ds_read_b128 v[224:227], v178 offset:55296
	ds_read_b128 v[228:231], v178 offset:56320
	global_load_lds_dwordx4 v[172:173], off
	s_add_i32 m0, s44, 0x2000
	s_add_u32 s42, s42, 0x40080
	v_lshl_add_u64 v[172:173], v[204:205], 0, s[8:9]
	s_addc_u32 s43, s43, 0
	s_add_i32 s44, s62, s21
	global_load_lds_dwordx4 v[172:173], off
	v_lshl_add_u64 v[172:173], s[42:43], 0, v[144:145]
	s_mov_b32 m0, s44
	s_nop 0
	global_load_lds_dwordx4 v[172:173], off
	v_lshl_add_u64 v[172:173], s[42:43], 0, v[146:147]
	s_add_i32 m0, s44, 0x2000
	s_nop 0
	global_load_lds_dwordx4 v[172:173], off
	v_lshl_add_u64 v[172:173], v[232:233], 0, s[8:9]
	s_mov_b32 m0, s52
	s_nop 0
	global_load_lds_dwordx4 v[172:173], off
	v_lshl_add_u64 v[172:173], v[234:235], 0, s[8:9]
	s_mov_b32 m0, s53
	s_nop 0
	global_load_lds_dwordx4 v[172:173], off
	s_waitcnt vmcnt(8)
	s_waitcnt lgkmcnt(0)
	s_barrier
	s_setprio 1
	v_mfma_f32_16x16x32_bf16 v[60:63], v[104:107], v[196:199], v[60:63]
	v_mfma_f32_16x16x32_bf16 v[56:59], v[124:127], v[196:199], v[56:59]
	v_mfma_f32_16x16x32_bf16 v[44:47], v[104:107], v[208:211], v[44:47]
	v_mfma_f32_16x16x32_bf16 v[40:43], v[124:127], v[208:211], v[40:43]
	v_mfma_f32_16x16x32_bf16 v[28:31], v[104:107], v[216:219], v[28:31]
	v_mfma_f32_16x16x32_bf16 v[24:27], v[124:127], v[216:219], v[24:27]
	v_mfma_f32_16x16x32_bf16 v[12:15], v[104:107], v[224:227], v[12:15]
	v_mfma_f32_16x16x32_bf16 v[8:11], v[124:127], v[224:227], v[8:11]
	v_mfma_f32_16x16x32_bf16 v[60:63], v[108:111], v[200:203], v[60:63]
	v_mfma_f32_16x16x32_bf16 v[56:59], v[128:131], v[200:203], v[56:59]
	v_mfma_f32_16x16x32_bf16 v[44:47], v[108:111], v[212:215], v[44:47]
	v_mfma_f32_16x16x32_bf16 v[40:43], v[128:131], v[212:215], v[40:43]
	v_mfma_f32_16x16x32_bf16 v[28:31], v[108:111], v[220:223], v[28:31]
	v_mfma_f32_16x16x32_bf16 v[24:27], v[128:131], v[220:223], v[24:27]
	v_mfma_f32_16x16x32_bf16 v[12:15], v[108:111], v[228:231], v[12:15]
	v_mfma_f32_16x16x32_bf16 v[8:11], v[128:131], v[228:231], v[8:11]
	s_setprio 0
	s_setprio 1
	v_mfma_f32_16x16x32_bf16 v[52:55], v[180:183], v[196:199], v[52:55]
	v_mfma_f32_16x16x32_bf16 v[48:51], v[188:191], v[196:199], v[48:51]
	v_mfma_f32_16x16x32_bf16 v[36:39], v[180:183], v[208:211], v[36:39]
	v_mfma_f32_16x16x32_bf16 v[32:35], v[188:191], v[208:211], v[32:35]
	v_mfma_f32_16x16x32_bf16 v[20:23], v[180:183], v[216:219], v[20:23]
	v_mfma_f32_16x16x32_bf16 v[16:19], v[188:191], v[216:219], v[16:19]
	v_mfma_f32_16x16x32_bf16 v[4:7], v[180:183], v[224:227], v[4:7]
	v_mfma_f32_16x16x32_bf16 v[0:3], v[188:191], v[224:227], v[0:3]
	v_mfma_f32_16x16x32_bf16 v[52:55], v[184:187], v[200:203], v[52:55]
	v_mfma_f32_16x16x32_bf16 v[48:51], v[192:195], v[200:203], v[48:51]
	v_mfma_f32_16x16x32_bf16 v[36:39], v[184:187], v[212:215], v[36:39]
	v_mfma_f32_16x16x32_bf16 v[32:35], v[192:195], v[212:215], v[32:35]
	v_mfma_f32_16x16x32_bf16 v[20:23], v[184:187], v[220:223], v[20:23]
	v_mfma_f32_16x16x32_bf16 v[16:19], v[192:195], v[220:223], v[16:19]
	v_mfma_f32_16x16x32_bf16 v[4:7], v[184:187], v[228:231], v[4:7]
	v_mfma_f32_16x16x32_bf16 v[0:3], v[192:195], v[228:231], v[0:3]
	s_setprio 0
	s_barrier
	s_add_i32 s60, s60, 2
	s_add_u32 s40, s40, 0x100
	s_addc_u32 s41, s41, 0
	s_add_u32 s58, s58, 0x100
	s_addc_u32 s59, s59, 0
	s_cmp_gt_u32 s60, 13
	s_cbranch_scc0 .LBB0_1737
	s_and_b64 vcc, exec, s[12:13]
	s_cbranch_vccz .LBB0_1740
	s_barrier

; #define PG8_STAGE(bufoff, gbase, voff) do { _Pragma("unroll") for (int _i = 0; _i < 2; ++_i) \
;         __builtin_amdgcn_global_load_lds((const unsigned*)((const char*)(gbase) + (voff)[_i]), (LAS unsigned*)(lds + (bufoff) + ldsw + _i * 8192), 16, 0, 0); } while (0)
; #define PG8_LDA(dst, b, h) do { _Pragma("unroll") for (int m = 0; m < 4; ++m) _Pragma("unroll") for (int k = 0; k < 2; ++k) dst[m][k] = *(const LAS bf16x8*)(lds + PG8_SA(b, h) + aoff + m * 2048 + k * 1024); } while (0)
; #define PG8_LDB(dst, b, h) do { _Pragma("unroll") for (int n = 0; n < 2; ++n) _Pragma("unroll") for (int k = 0; k < 2; ++k) dst[n][k] = *(const LAS bf16x8*)(lds + PG8_SB(b, h) + boff + n * 2048 + k * 1024); } while (0)
; #define PG8_WAIT_V(n) asm volatile("s_waitcnt vmcnt(" #n ")" ::: "memory")
; #define PG8_WAIT_L(n) asm volatile("s_waitcnt lgkmcnt(" #n ")" ::: "memory")
; #define PG8_BAR __builtin_amdgcn_s_barrier()
; #define PG8_SCHED __builtin_amdgcn_sched_barrier(0)
; template <class Epi, class Sched, bool SWAPD = false>
; __device__ __forceinline__ void gemm_phase(LAS unsigned char* lds, const Gemm g, const Sched& S, const Epi& E) {
;     ...
;             const bool last = (t == nt - 2);
;             const char* a1 = cA + (size_t)(t + 1) * kstepA;
;             const char* a2 = last ? nA : cA + (size_t)(t + 2) * kstepA; const char* b2 = last ? nB : cB + (size_t)(t + 2) * kstep;
;             const char* a3 = a2 + kstepA; const char* b3 = b2 + kstep;
;             PG8_LDB(B0, 0, 0); PG8_LDB(B1, 0, 1); PG8_SCHED; PG8_LDA(At, 0, 0); PG8_STAGE(PG8_SA(1, 1), a1 + hstepA, voffA);
;             PG8_WAIT_V(8); PG8_WAIT_L(0); PG8_BAR; PG8_MMA(0, 0, At, B0); PG8_MMA(0, 1, At, B1); PG8_BAR; PG8_SCHED;
;             PG8_LDA(At, 0, 1); PG8_STAGE(PG8_SB(0, 0), b2, voffB); PG8_STAGE(PG8_SB(0, 1), b2 + hstepB, voffB); PG8_STAGE(PG8_SA(0, 0), a2, voffA);
;             PG8_WAIT_V(8); PG8_WAIT_L(0); PG8_BAR; PG8_MMA(1, 0, At, B0); PG8_MMA(1, 1, At, B1); PG8_BAR; PG8_SCHED;
.LBB0_1863:
	ds_read_b128 v[148:151], v145
	ds_read_b128 v[152:155], v145 offset:1024
	ds_read_b128 v[156:159], v145 offset:2048
	ds_read_b128 v[160:163], v145 offset:3072
	ds_read_b128 v[164:167], v146
	ds_read_b128 v[168:171], v146 offset:1024
	ds_read_b128 v[172:175], v146 offset:2048
	ds_read_b128 v[176:179], v146 offset:3072
	s_add_u32 s38, s36, 0xfffc0080
	s_addc_u32 s39, s37, -1
	s_cmp_eq_u32 s58, 12
	s_cselect_b32 s41, s21, s39
	s_cselect_b32 s40, s23, s38
	s_cselect_b32 s39, s54, s57
	s_cselect_b32 s38, s55, s56
	v_lshl_add_u64 v[140:141], s[36:37], 0, v[132:133]
	s_add_i32 m0, s35, 0xc000
	ds_read_b128 v[180:183], v147
	ds_read_b128 v[184:187], v147 offset:1024
	ds_read_b128 v[188:191], v147 offset:2048
	ds_read_b128 v[192:195], v147 offset:3072
	ds_read_b128 v[196:199], v147 offset:4096
	ds_read_b128 v[200:203], v147 offset:5120
	ds_read_b128 v[208:211], v147 offset:6144
	ds_read_b128 v[212:215], v147 offset:7168
	global_load_lds_dwordx4 v[140:141], off
	v_lshl_add_u64 v[140:141], s[36:37], 0, v[134:135]
	s_add_i32 m0, s35, 0xe000
	s_nop 0
	global_load_lds_dwordx4 v[140:141], off
	s_waitcnt vmcnt(8)
	s_waitcnt lgkmcnt(0)
	s_barrier
	s_setprio 1
	v_mfma_f32_16x16x32_bf16 v[124:127], v[148:151], v[180:183], v[124:127]
	v_mfma_f32_16x16x32_bf16 v[116:119], v[156:159], v[180:183], v[116:119]
	v_mfma_f32_16x16x32_bf16 v[108:111], v[148:151], v[188:191], v[108:111]
	v_mfma_f32_16x16x32_bf16 v[100:103], v[156:159], v[188:191], v[100:103]
	v_mfma_f32_16x16x32_bf16 v[92:95], v[148:151], v[196:199], v[92:95]
	v_mfma_f32_16x16x32_bf16 v[84:87], v[156:159], v[196:199], v[84:87]
	v_mfma_f32_16x16x32_bf16 v[76:79], v[148:151], v[208:211], v[76:79]
	v_mfma_f32_16x16x32_bf16 v[68:71], v[156:159], v[208:211], v[68:71]
	v_mfma_f32_16x16x32_bf16 v[124:127], v[152:155], v[184:187], v[124:127]
	v_mfma_f32_16x16x32_bf16 v[116:119], v[160:163], v[184:187], v[116:119]
	v_mfma_f32_16x16x32_bf16 v[108:111], v[152:155], v[192:195], v[108:111]
	v_mfma_f32_16x16x32_bf16 v[100:103], v[160:163], v[192:195], v[100:103]
	v_mfma_f32_16x16x32_bf16 v[92:95], v[152:155], v[200:203], v[92:95]
	v_mfma_f32_16x16x32_bf16 v[84:87], v[160:163], v[200:203], v[84:87]
	v_mfma_f32_16x16x32_bf16 v[76:79], v[152:155], v[212:215], v[76:79]
	v_mfma_f32_16x16x32_bf16 v[68:71], v[160:163], v[212:215], v[68:71]
	s_setprio 0
	s_setprio 1
	v_mfma_f32_16x16x32_bf16 v[120:123], v[164:167], v[180:183], v[120:123]
	v_mfma_f32_16x16x32_bf16 v[112:115], v[172:175], v[180:183], v[112:115]
	v_mfma_f32_16x16x32_bf16 v[104:107], v[164:167], v[188:191], v[104:107]
	v_mfma_f32_16x16x32_bf16 v[96:99], v[172:175], v[188:191], v[96:99]
	v_mfma_f32_16x16x32_bf16 v[88:91], v[164:167], v[196:199], v[88:91]
	v_mfma_f32_16x16x32_bf16 v[80:83], v[172:175], v[196:199], v[80:83]
	v_mfma_f32_16x16x32_bf16 v[72:75], v[164:167], v[208:211], v[72:75]
	v_mfma_f32_16x16x32_bf16 v[64:67], v[172:175], v[208:211], v[64:67]
	v_mfma_f32_16x16x32_bf16 v[120:123], v[168:171], v[184:187], v[120:123]
	v_mfma_f32_16x16x32_bf16 v[112:115], v[176:179], v[184:187], v[112:115]
	v_mfma_f32_16x16x32_bf16 v[104:107], v[168:171], v[192:195], v[104:107]
	v_mfma_f32_16x16x32_bf16 v[96:99], v[176:179], v[192:195], v[96:99]
	v_mfma_f32_16x16x32_bf16 v[88:91], v[168:171], v[200:203], v[88:91]
	v_mfma_f32_16x16x32_bf16 v[80:83], v[176:179], v[200:203], v[80:83]
	v_mfma_f32_16x16x32_bf16 v[72:75], v[168:171], v[212:215], v[72:75]
	v_mfma_f32_16x16x32_bf16 v[64:67], v[176:179], v[212:215], v[64:67]
	s_setprio 0
	s_barrier
	s_add_i32 s59, s50, s42
	v_lshl_add_u64 v[140:141], s[38:39], 0, v[130:131]
	s_mov_b32 m0, s59
	ds_read_b128 v[180:183], v147 offset:16384
	ds_read_b128 v[184:187], v147 offset:17408
	ds_read_b128 v[188:191], v147 offset:18432
	ds_read_b128 v[192:195], v147 offset:19456
	ds_read_b128 v[196:199], v147 offset:20480
	ds_read_b128 v[200:203], v147 offset:21504
	ds_read_b128 v[208:211], v147 offset:22528
	ds_read_b128 v[212:215], v147 offset:23552
	global_load_lds_dwordx4 v[140:141], off
	s_add_i32 m0, s59, 0x2000
	s_add_u32 s60, s38, 0x40000
	v_lshl_add_u64 v[204:205], s[38:39], 0, v[128:129]
	s_addc_u32 s61, s39, 0
	s_add_i32 s59, s51, s42
	global_load_lds_dwordx4 v[204:205], off
	v_lshl_add_u64 v[216:217], s[60:61], 0, v[130:131]
	s_mov_b32 m0, s59
	v_lshl_add_u64 v[218:219], s[40:41], 0, v[128:129]
	global_load_lds_dwordx4 v[216:217], off
	v_lshl_add_u64 v[216:217], s[60:61], 0, v[128:129]
	s_add_i32 m0, s59, 0x2000
	s_nop 0
	global_load_lds_dwordx4 v[216:217], off
	v_lshl_add_u64 v[216:217], s[40:41], 0, v[130:131]
	s_mov_b32 m0, s35
	s_nop 0
	global_load_lds_dwordx4 v[216:217], off
	s_mov_b32 m0, s44
	s_nop 0
	global_load_lds_dwordx4 v[218:219], off
	s_waitcnt vmcnt(8)
	s_waitcnt lgkmcnt(0)
	s_barrier
; #define PG8_STAGE(bufoff, gbase, voff) do { _Pragma("unroll") for (int _i = 0; _i < 2; ++_i) \
;         __builtin_amdgcn_global_load_lds((const unsigned*)((const char*)(gbase) + (voff)[_i]), (LAS unsigned*)(lds + (bufoff) + ldsw + _i * 8192), 16, 0, 0); } while (0)
; #define PG8_LDA(dst, b, h) do { _Pragma("unroll") for (int m = 0; m < 4; ++m) _Pragma("unroll") for (int k = 0; k < 2; ++k) dst[m][k] = *(const LAS bf16x8*)(lds + PG8_SA(b, h) + aoff + m * 2048 + k * 1024); } while (0)
; #define PG8_LDB(dst, b, h) do { _Pragma("unroll") for (int n = 0; n < 2; ++n) _Pragma("unroll") for (int k = 0; k < 2; ++k) dst[n][k] = *(const LAS bf16x8*)(lds + PG8_SB(b, h) + boff + n * 2048 + k * 1024); } while (0)
; #define PG8_WAIT_V(n) asm volatile("s_waitcnt vmcnt(" #n ")" ::: "memory")
; #define PG8_WAIT_L(n) asm volatile("s_waitcnt lgkmcnt(" #n ")" ::: "memory")
; #define PG8_BAR __builtin_amdgcn_s_barrier()
; #define PG8_SCHED __builtin_amdgcn_sched_barrier(0)
; template <class Epi, class Sched, bool SWAPD = false>
; __device__ __forceinline__ void gemm_phase(LAS unsigned char* lds, const Gemm g, const Sched& S, const Epi& E) {
;     ...
;             PG8_WAIT_V(8); PG8_WAIT_L(0); PG8_BAR; PG8_MMA(1, 0, At, B0); PG8_MMA(1, 1, At, B1); PG8_BAR; PG8_SCHED;
;             PG8_LDB(B0, 1, 0); PG8_LDB(B1, 1, 1); PG8_SCHED; PG8_LDA(At, 1, 0); PG8_STAGE(PG8_SA(0, 1), a2 + hstepA, voffA);
;             PG8_WAIT_V(8); PG8_WAIT_L(0); PG8_BAR; PG8_MMA(0, 0, At, B0); PG8_MMA(0, 1, At, B1); PG8_BAR; PG8_SCHED;
	s_setprio 1
	v_mfma_f32_16x16x32_bf16 v[60:63], v[148:151], v[180:183], v[60:63]
	v_mfma_f32_16x16x32_bf16 v[52:55], v[156:159], v[180:183], v[52:55]
	v_mfma_f32_16x16x32_bf16 v[44:47], v[148:151], v[188:191], v[44:47]
	v_mfma_f32_16x16x32_bf16 v[36:39], v[156:159], v[188:191], v[36:39]
	v_mfma_f32_16x16x32_bf16 v[28:31], v[148:151], v[196:199], v[28:31]
	v_mfma_f32_16x16x32_bf16 v[20:23], v[156:159], v[196:199], v[20:23]
	v_mfma_f32_16x16x32_bf16 v[12:15], v[148:151], v[208:211], v[12:15]
	v_mfma_f32_16x16x32_bf16 v[4:7], v[156:159], v[208:211], v[4:7]
	v_mfma_f32_16x16x32_bf16 v[60:63], v[152:155], v[184:187], v[60:63]
	v_mfma_f32_16x16x32_bf16 v[52:55], v[160:163], v[184:187], v[52:55]
	v_mfma_f32_16x16x32_bf16 v[44:47], v[152:155], v[192:195], v[44:47]
	v_mfma_f32_16x16x32_bf16 v[36:39], v[160:163], v[192:195], v[36:39]
	v_mfma_f32_16x16x32_bf16 v[28:31], v[152:155], v[200:203], v[28:31]
	v_mfma_f32_16x16x32_bf16 v[20:23], v[160:163], v[200:203], v[20:23]
	v_mfma_f32_16x16x32_bf16 v[12:15], v[152:155], v[212:215], v[12:15]
	v_mfma_f32_16x16x32_bf16 v[4:7], v[160:163], v[212:215], v[4:7]
	s_setprio 0
	s_setprio 1
	v_mfma_f32_16x16x32_bf16 v[56:59], v[164:167], v[180:183], v[56:59]
	v_mfma_f32_16x16x32_bf16 v[48:51], v[172:175], v[180:183], v[48:51]
	v_mfma_f32_16x16x32_bf16 v[40:43], v[164:167], v[188:191], v[40:43]
	v_mfma_f32_16x16x32_bf16 v[32:35], v[172:175], v[188:191], v[32:35]
	v_mfma_f32_16x16x32_bf16 v[24:27], v[164:167], v[196:199], v[24:27]
	v_mfma_f32_16x16x32_bf16 v[16:19], v[172:175], v[196:199], v[16:19]
	v_mfma_f32_16x16x32_bf16 v[8:11], v[164:167], v[208:211], v[8:11]
	v_mfma_f32_16x16x32_bf16 v[0:3], v[172:175], v[208:211], v[0:3]
	v_mfma_f32_16x16x32_bf16 v[56:59], v[168:171], v[184:187], v[56:59]
	v_mfma_f32_16x16x32_bf16 v[48:51], v[176:179], v[184:187], v[48:51]
	v_mfma_f32_16x16x32_bf16 v[40:43], v[168:171], v[192:195], v[40:43]
	v_mfma_f32_16x16x32_bf16 v[32:35], v[176:179], v[192:195], v[32:35]
	v_mfma_f32_16x16x32_bf16 v[24:27], v[168:171], v[200:203], v[24:27]
	v_mfma_f32_16x16x32_bf16 v[16:19], v[176:179], v[200:203], v[16:19]
	v_mfma_f32_16x16x32_bf16 v[8:11], v[168:171], v[212:215], v[8:11]
	v_mfma_f32_16x16x32_bf16 v[0:3], v[176:179], v[212:215], v[0:3]
	s_setprio 0
	s_barrier
	s_add_i32 s59, 0, 0x18000
	s_add_i32 s60, 0, 0x1c000
	v_add_u32_e32 v160, s59, v143
	v_add_u32_e32 v176, s60, v143
	ds_read_b128 v[148:151], v160
	ds_read_b128 v[152:155], v160 offset:1024
	ds_read_b128 v[156:159], v160 offset:2048
	ds_read_b128 v[160:163], v160 offset:3072
	ds_read_b128 v[164:167], v176
	ds_read_b128 v[168:171], v176 offset:1024
	ds_read_b128 v[172:175], v176 offset:2048
	ds_read_b128 v[176:179], v176 offset:3072
	s_add_u32 s40, s40, 0x40000
	s_addc_u32 s41, s41, 0
	s_mov_b32 m0, s45
	v_lshl_add_u64 v[220:221], s[40:41], 0, v[130:131]
	ds_read_b128 v[180:183], v147 offset:32768
	ds_read_b128 v[184:187], v147 offset:33792
	ds_read_b128 v[188:191], v147 offset:34816
	ds_read_b128 v[192:195], v147 offset:35840
	ds_read_b128 v[196:199], v147 offset:36864
	ds_read_b128 v[200:203], v147 offset:37888
	ds_read_b128 v[208:211], v147 offset:38912
	ds_read_b128 v[212:215], v147 offset:39936
	global_load_lds_dwordx4 v[220:221], off
	v_lshl_add_u64 v[220:221], s[40:41], 0, v[128:129]
	s_mov_b32 m0, s46
	s_nop 0
	global_load_lds_dwordx4 v[220:221], off
	s_waitcnt vmcnt(8)
	s_waitcnt lgkmcnt(0)
	s_barrier
	s_setprio 1
	v_mfma_f32_16x16x32_bf16 v[124:127], v[148:151], v[180:183], v[124:127]
	v_mfma_f32_16x16x32_bf16 v[116:119], v[156:159], v[180:183], v[116:119]
	v_mfma_f32_16x16x32_bf16 v[108:111], v[148:151], v[188:191], v[108:111]
	v_mfma_f32_16x16x32_bf16 v[100:103], v[156:159], v[188:191], v[100:103]
	v_mfma_f32_16x16x32_bf16 v[92:95], v[148:151], v[196:199], v[92:95]
	v_mfma_f32_16x16x32_bf16 v[84:87], v[156:159], v[196:199], v[84:87]
	v_mfma_f32_16x16x32_bf16 v[76:79], v[148:151], v[208:211], v[76:79]
	v_mfma_f32_16x16x32_bf16 v[68:71], v[156:159], v[208:211], v[68:71]
	v_mfma_f32_16x16x32_bf16 v[124:127], v[152:155], v[184:187], v[124:127]
	v_mfma_f32_16x16x32_bf16 v[116:119], v[160:163], v[184:187], v[116:119]
	v_mfma_f32_16x16x32_bf16 v[108:111], v[152:155], v[192:195], v[108:111]
	v_mfma_f32_16x16x32_bf16 v[100:103], v[160:163], v[192:195], v[100:103]
	v_mfma_f32_16x16x32_bf16 v[92:95], v[152:155], v[200:203], v[92:95]
	v_mfma_f32_16x16x32_bf16 v[84:87], v[160:163], v[200:203], v[84:87]
	v_mfma_f32_16x16x32_bf16 v[76:79], v[152:155], v[212:215], v[76:79]
	v_mfma_f32_16x16x32_bf16 v[68:71], v[160:163], v[212:215], v[68:71]
	s_setprio 0
	s_setprio 1
	v_mfma_f32_16x16x32_bf16 v[120:123], v[164:167], v[180:183], v[120:123]
	v_mfma_f32_16x16x32_bf16 v[112:115], v[172:175], v[180:183], v[112:115]
	v_mfma_f32_16x16x32_bf16 v[104:107], v[164:167], v[188:191], v[104:107]
	v_mfma_f32_16x16x32_bf16 v[96:99], v[172:175], v[188:191], v[96:99]
	v_mfma_f32_16x16x32_bf16 v[88:91], v[164:167], v[196:199], v[88:91]
	v_mfma_f32_16x16x32_bf16 v[80:83], v[172:175], v[196:199], v[80:83]
	v_mfma_f32_16x16x32_bf16 v[72:75], v[164:167], v[208:211], v[72:75]
	v_mfma_f32_16x16x32_bf16 v[64:67], v[172:175], v[208:211], v[64:67]
	v_mfma_f32_16x16x32_bf16 v[120:123], v[168:171], v[184:187], v[120:123]
	v_mfma_f32_16x16x32_bf16 v[112:115], v[176:179], v[184:187], v[112:115]
	v_mfma_f32_16x16x32_bf16 v[104:107], v[168:171], v[192:195], v[104:107]
	v_mfma_f32_16x16x32_bf16 v[96:99], v[176:179], v[192:195], v[96:99]
	v_mfma_f32_16x16x32_bf16 v[88:91], v[168:171], v[200:203], v[88:91]
	v_mfma_f32_16x16x32_bf16 v[80:83], v[176:179], v[200:203], v[80:83]
	v_mfma_f32_16x16x32_bf16 v[72:75], v[168:171], v[212:215], v[72:75]
	v_mfma_f32_16x16x32_bf16 v[64:67], v[176:179], v[212:215], v[64:67]
	s_setprio 0
	s_barrier
; #define PG8_STAGE(bufoff, gbase, voff) do { _Pragma("unroll") for (int _i = 0; _i < 2; ++_i) \
;         __builtin_amdgcn_global_load_lds((const unsigned*)((const char*)(gbase) + (voff)[_i]), (LAS unsigned*)(lds + (bufoff) + ldsw + _i * 8192), 16, 0, 0); } while (0)
; #define PG8_LDA(dst, b, h) do { _Pragma("unroll") for (int m = 0; m < 4; ++m) _Pragma("unroll") for (int k = 0; k < 2; ++k) dst[m][k] = *(const LAS bf16x8*)(lds + PG8_SA(b, h) + aoff + m * 2048 + k * 1024); } while (0)
; #define PG8_WAIT_V(n) asm volatile("s_waitcnt vmcnt(" #n ")" ::: "memory")
; #define PG8_WAIT_L(n) asm volatile("s_waitcnt lgkmcnt(" #n ")" ::: "memory")
; #define PG8_BAR __builtin_amdgcn_s_barrier()
; #define PG8_SCHED __builtin_amdgcn_sched_barrier(0)
; template <class Epi, class Sched, bool SWAPD = false>
; __device__ __forceinline__ void gemm_phase(LAS unsigned char* lds, const Gemm g, const Sched& S, const Epi& E) {
;     ...
;             PG8_LDA(At, 1, 1); PG8_STAGE(PG8_SB(1, 0), b3, voffB); PG8_STAGE(PG8_SB(1, 1), b3 + hstepB, voffB); PG8_STAGE(PG8_SA(1, 0), a3, voffA);
;             PG8_WAIT_V(8); PG8_WAIT_L(0); PG8_BAR; PG8_MMA(1, 0, At, B0); PG8_MMA(1, 1, At, B1); PG8_BAR; PG8_SCHED;
;         }
;         if (wr == 0) PG8_BAR;
	s_add_i32 s40, s59, s42
	v_lshl_add_u64 v[140:141], v[140:141], 0, s[8:9]
	s_mov_b32 m0, s40
	ds_read_b128 v[180:183], v147 offset:49152
	ds_read_b128 v[184:187], v147 offset:50176
	ds_read_b128 v[188:191], v147 offset:51200
	ds_read_b128 v[192:195], v147 offset:52224
	ds_read_b128 v[196:199], v147 offset:53248
	ds_read_b128 v[200:203], v147 offset:54272
	ds_read_b128 v[208:211], v147 offset:55296
	ds_read_b128 v[212:215], v147 offset:56320
	global_load_lds_dwordx4 v[140:141], off
	s_add_i32 m0, s40, 0x2000
	s_add_u32 s38, s38, 0x40080
	v_lshl_add_u64 v[140:141], v[204:205], 0, s[8:9]
	s_addc_u32 s39, s39, 0
	s_add_i32 s40, s60, s42
	global_load_lds_dwordx4 v[140:141], off
	v_lshl_add_u64 v[140:141], s[38:39], 0, v[130:131]
	s_mov_b32 m0, s40
	s_nop 0
	global_load_lds_dwordx4 v[140:141], off
	v_lshl_add_u64 v[140:141], s[38:39], 0, v[128:129]
	s_add_i32 m0, s40, 0x2000
	s_nop 0
	global_load_lds_dwordx4 v[140:141], off
	v_lshl_add_u64 v[140:141], v[216:217], 0, s[8:9]
	s_mov_b32 m0, s48
	s_nop 0
	global_load_lds_dwordx4 v[140:141], off
	v_lshl_add_u64 v[140:141], v[218:219], 0, s[8:9]
	s_mov_b32 m0, s49
	s_nop 0
	global_load_lds_dwordx4 v[140:141], off
	s_waitcnt vmcnt(8)
	s_waitcnt lgkmcnt(0)
	s_barrier
	s_setprio 1
	v_mfma_f32_16x16x32_bf16 v[60:63], v[148:151], v[180:183], v[60:63]
	v_mfma_f32_16x16x32_bf16 v[52:55], v[156:159], v[180:183], v[52:55]
	v_mfma_f32_16x16x32_bf16 v[44:47], v[148:151], v[188:191], v[44:47]
	v_mfma_f32_16x16x32_bf16 v[36:39], v[156:159], v[188:191], v[36:39]
	v_mfma_f32_16x16x32_bf16 v[28:31], v[148:151], v[196:199], v[28:31]
	v_mfma_f32_16x16x32_bf16 v[20:23], v[156:159], v[196:199], v[20:23]
	v_mfma_f32_16x16x32_bf16 v[12:15], v[148:151], v[208:211], v[12:15]
	v_mfma_f32_16x16x32_bf16 v[4:7], v[156:159], v[208:211], v[4:7]
	v_mfma_f32_16x16x32_bf16 v[60:63], v[152:155], v[184:187], v[60:63]
	v_mfma_f32_16x16x32_bf16 v[52:55], v[160:163], v[184:187], v[52:55]
	v_mfma_f32_16x16x32_bf16 v[44:47], v[152:155], v[192:195], v[44:47]
	v_mfma_f32_16x16x32_bf16 v[36:39], v[160:163], v[192:195], v[36:39]
	v_mfma_f32_16x16x32_bf16 v[28:31], v[152:155], v[200:203], v[28:31]
	v_mfma_f32_16x16x32_bf16 v[20:23], v[160:163], v[200:203], v[20:23]
	v_mfma_f32_16x16x32_bf16 v[12:15], v[152:155], v[212:215], v[12:15]
	v_mfma_f32_16x16x32_bf16 v[4:7], v[160:163], v[212:215], v[4:7]
	s_setprio 0
	s_setprio 1
	v_mfma_f32_16x16x32_bf16 v[56:59], v[164:167], v[180:183], v[56:59]
	v_mfma_f32_16x16x32_bf16 v[48:51], v[172:175], v[180:183], v[48:51]
	v_mfma_f32_16x16x32_bf16 v[40:43], v[164:167], v[188:191], v[40:43]
	v_mfma_f32_16x16x32_bf16 v[32:35], v[172:175], v[188:191], v[32:35]
	v_mfma_f32_16x16x32_bf16 v[24:27], v[164:167], v[196:199], v[24:27]
	v_mfma_f32_16x16x32_bf16 v[16:19], v[172:175], v[196:199], v[16:19]
	v_mfma_f32_16x16x32_bf16 v[8:11], v[164:167], v[208:211], v[8:11]
	v_mfma_f32_16x16x32_bf16 v[0:3], v[172:175], v[208:211], v[0:3]
	v_mfma_f32_16x16x32_bf16 v[56:59], v[168:171], v[184:187], v[56:59]
	v_mfma_f32_16x16x32_bf16 v[48:51], v[176:179], v[184:187], v[48:51]
	v_mfma_f32_16x16x32_bf16 v[40:43], v[168:171], v[192:195], v[40:43]
	v_mfma_f32_16x16x32_bf16 v[32:35], v[176:179], v[192:195], v[32:35]
	v_mfma_f32_16x16x32_bf16 v[24:27], v[168:171], v[200:203], v[24:27]
	v_mfma_f32_16x16x32_bf16 v[16:19], v[176:179], v[200:203], v[16:19]
	v_mfma_f32_16x16x32_bf16 v[8:11], v[168:171], v[212:215], v[8:11]
	v_mfma_f32_16x16x32_bf16 v[0:3], v[176:179], v[212:215], v[0:3]
	s_setprio 0
	s_barrier
	s_add_i32 s58, s58, 2
	s_add_u32 s36, s36, 0x100
	s_addc_u32 s37, s37, 0
	s_add_u32 s56, s56, 0x100
	s_addc_u32 s57, s57, 0
	s_cmp_gt_u32 s58, 13
	s_cbranch_scc0 .LBB0_1863
	s_and_b64 vcc, exec, s[10:11]
	s_cbranch_vccz .LBB0_1866
	s_barrier

; #define PG8_STAGE(bufoff, gbase, voff) do { _Pragma("unroll") for (int _i = 0; _i < 2; ++_i) \
;         __builtin_amdgcn_global_load_lds((const unsigned*)((const char*)(gbase) + (voff)[_i]), (LAS unsigned*)(lds + (bufoff) + ldsw + _i * 8192), 16, 0, 0); } while (0)
; #define PG8_LDA(dst, b, h) do { _Pragma("unroll") for (int m = 0; m < 4; ++m) _Pragma("unroll") for (int k = 0; k < 2; ++k) dst[m][k] = *(const LAS bf16x8*)(lds + PG8_SA(b, h) + aoff + m * 2048 + k * 1024); } while (0)
; #define PG8_LDB(dst, b, h) do { _Pragma("unroll") for (int n = 0; n < 2; ++n) _Pragma("unroll") for (int k = 0; k < 2; ++k) dst[n][k] = *(const LAS bf16x8*)(lds + PG8_SB(b, h) + boff + n * 2048 + k * 1024); } while (0)
; #define PG8_WAIT_V(n) asm volatile("s_waitcnt vmcnt(" #n ")" ::: "memory")
; #define PG8_WAIT_L(n) asm volatile("s_waitcnt lgkmcnt(" #n ")" ::: "memory")
; #define PG8_BAR __builtin_amdgcn_s_barrier()
; #define PG8_SCHED __builtin_amdgcn_sched_barrier(0)
; template <class Epi, class Sched, bool SWAPD = false>
; __device__ __forceinline__ void gemm_phase(LAS unsigned char* lds, const Gemm g, const Sched& S, const Epi& E) {
;     ...
;             const bool last = (t == nt - 2);
;             const char* a1 = cA + (size_t)(t + 1) * kstepA;
;             const char* a2 = last ? nA : cA + (size_t)(t + 2) * kstepA; const char* b2 = last ? nB : cB + (size_t)(t + 2) * kstep;
;             const char* a3 = a2 + kstepA; const char* b3 = b2 + kstep;
;             PG8_LDB(B0, 0, 0); PG8_LDB(B1, 0, 1); PG8_SCHED; PG8_LDA(At, 0, 0); PG8_STAGE(PG8_SA(1, 1), a1 + hstepA, voffA);
;             PG8_WAIT_V(8); PG8_WAIT_L(0); PG8_BAR; PG8_MMA(0, 0, At, B0); PG8_MMA(0, 1, At, B1); PG8_BAR; PG8_SCHED;
;             PG8_LDA(At, 0, 1); PG8_STAGE(PG8_SB(0, 0), b2, voffB); PG8_STAGE(PG8_SB(0, 1), b2 + hstepB, voffB); PG8_STAGE(PG8_SA(0, 0), a2, voffA);
;             PG8_WAIT_V(8); PG8_WAIT_L(0); PG8_BAR; PG8_MMA(1, 0, At, B0); PG8_MMA(1, 1, At, B1); PG8_BAR; PG8_SCHED;
.LBB0_1940:
	ds_read_b128 v[156:159], v168
	ds_read_b128 v[160:163], v168 offset:1024
	ds_read_b128 v[172:175], v168 offset:2048
	ds_read_b128 v[176:179], v168 offset:3072
	ds_read_b128 v[180:183], v169
	ds_read_b128 v[184:187], v169 offset:1024
	ds_read_b128 v[188:191], v169 offset:2048
	ds_read_b128 v[192:195], v169 offset:3072
	s_add_u32 s22, s20, 0x100
	s_addc_u32 s23, s21, 0
	s_cmp_eq_u32 s53, 40
	s_cselect_b32 s27, s47, s23
	s_cselect_b32 s26, s48, s22
	s_cselect_b32 s25, s49, s52
	s_cselect_b32 s24, s50, s51
	v_lshl_add_u64 v[164:165], s[20:21], 0, v[148:149]
	s_add_i32 m0, s31, 0xc000
	ds_read_b128 v[196:199], v170
	ds_read_b128 v[200:203], v170 offset:1024
	ds_read_b128 v[204:207], v170 offset:2048
	ds_read_b128 v[208:211], v170 offset:3072
	ds_read_b128 v[212:215], v170 offset:4096
	ds_read_b128 v[216:219], v170 offset:5120
	ds_read_b128 v[220:223], v170 offset:6144
	ds_read_b128 v[224:227], v170 offset:7168
	global_load_lds_dwordx4 v[164:165], off
	v_lshl_add_u64 v[164:165], s[20:21], 0, v[150:151]
	s_add_i32 m0, s31, 0xe000
	s_nop 0
	global_load_lds_dwordx4 v[164:165], off
	s_waitcnt vmcnt(8)
	s_waitcnt lgkmcnt(0)
	s_barrier
	s_setprio 1
	v_mfma_f32_16x16x32_bf16 v[124:127], v[156:159], v[196:199], v[124:127]
	v_mfma_f32_16x16x32_bf16 v[120:123], v[172:175], v[196:199], v[120:123]
	v_mfma_f32_16x16x32_bf16 v[108:111], v[156:159], v[204:207], v[108:111]
	v_mfma_f32_16x16x32_bf16 v[104:107], v[172:175], v[204:207], v[104:107]
	v_mfma_f32_16x16x32_bf16 v[92:95], v[156:159], v[212:215], v[92:95]
	v_mfma_f32_16x16x32_bf16 v[88:91], v[172:175], v[212:215], v[88:91]
	v_mfma_f32_16x16x32_bf16 v[76:79], v[156:159], v[220:223], v[76:79]
	v_mfma_f32_16x16x32_bf16 v[72:75], v[172:175], v[220:223], v[72:75]
	v_mfma_f32_16x16x32_bf16 v[124:127], v[160:163], v[200:203], v[124:127]
	v_mfma_f32_16x16x32_bf16 v[120:123], v[176:179], v[200:203], v[120:123]
	v_mfma_f32_16x16x32_bf16 v[108:111], v[160:163], v[208:211], v[108:111]
	v_mfma_f32_16x16x32_bf16 v[104:107], v[176:179], v[208:211], v[104:107]
	v_mfma_f32_16x16x32_bf16 v[92:95], v[160:163], v[216:219], v[92:95]
	v_mfma_f32_16x16x32_bf16 v[88:91], v[176:179], v[216:219], v[88:91]
	v_mfma_f32_16x16x32_bf16 v[76:79], v[160:163], v[224:227], v[76:79]
	v_mfma_f32_16x16x32_bf16 v[72:75], v[176:179], v[224:227], v[72:75]
	s_setprio 0
	s_setprio 1
	v_mfma_f32_16x16x32_bf16 v[116:119], v[180:183], v[196:199], v[116:119]
	v_mfma_f32_16x16x32_bf16 v[112:115], v[188:191], v[196:199], v[112:115]
	v_mfma_f32_16x16x32_bf16 v[100:103], v[180:183], v[204:207], v[100:103]
	v_mfma_f32_16x16x32_bf16 v[96:99], v[188:191], v[204:207], v[96:99]
	v_mfma_f32_16x16x32_bf16 v[84:87], v[180:183], v[212:215], v[84:87]
	v_mfma_f32_16x16x32_bf16 v[80:83], v[188:191], v[212:215], v[80:83]
	v_mfma_f32_16x16x32_bf16 v[68:71], v[180:183], v[220:223], v[68:71]
	v_mfma_f32_16x16x32_bf16 v[64:67], v[188:191], v[220:223], v[64:67]
	v_mfma_f32_16x16x32_bf16 v[116:119], v[184:187], v[200:203], v[116:119]
	v_mfma_f32_16x16x32_bf16 v[112:115], v[192:195], v[200:203], v[112:115]
	v_mfma_f32_16x16x32_bf16 v[100:103], v[184:187], v[208:211], v[100:103]
	v_mfma_f32_16x16x32_bf16 v[96:99], v[192:195], v[208:211], v[96:99]
	v_mfma_f32_16x16x32_bf16 v[84:87], v[184:187], v[216:219], v[84:87]
	v_mfma_f32_16x16x32_bf16 v[80:83], v[192:195], v[216:219], v[80:83]
	v_mfma_f32_16x16x32_bf16 v[68:71], v[184:187], v[224:227], v[68:71]
	v_mfma_f32_16x16x32_bf16 v[64:67], v[192:195], v[224:227], v[64:67]
	s_setprio 0
	s_barrier
	s_add_i32 s20, s41, s30
	v_lshl_add_u64 v[164:165], s[24:25], 0, v[128:129]
	s_mov_b32 m0, s20
	ds_read_b128 v[196:199], v170 offset:16384
	ds_read_b128 v[200:203], v170 offset:17408
	ds_read_b128 v[204:207], v170 offset:18432
	ds_read_b128 v[208:211], v170 offset:19456
	ds_read_b128 v[212:215], v170 offset:20480
	ds_read_b128 v[216:219], v170 offset:21504
	ds_read_b128 v[220:223], v170 offset:22528
	ds_read_b128 v[224:227], v170 offset:23552
	global_load_lds_dwordx4 v[164:165], off
	s_add_i32 m0, s20, 0x2000
	s_add_u32 s20, s24, 0xb0000
	v_lshl_add_u64 v[228:229], s[24:25], 0, v[130:131]
	s_addc_u32 s21, s25, 0
	s_add_i32 s54, s42, s30
	global_load_lds_dwordx4 v[228:229], off
	v_lshl_add_u64 v[230:231], s[20:21], 0, v[128:129]
	s_mov_b32 m0, s54
	v_lshl_add_u64 v[232:233], s[26:27], 0, v[130:131]
	global_load_lds_dwordx4 v[230:231], off
	v_lshl_add_u64 v[230:231], s[20:21], 0, v[130:131]
	s_add_i32 m0, s54, 0x2000
	s_nop 0
	global_load_lds_dwordx4 v[230:231], off
	v_lshl_add_u64 v[230:231], s[26:27], 0, v[128:129]
	s_mov_b32 m0, s31
	s_nop 0
	global_load_lds_dwordx4 v[230:231], off
	s_mov_b32 m0, s33
	s_nop 0
	global_load_lds_dwordx4 v[232:233], off
	s_waitcnt vmcnt(8)
	s_waitcnt lgkmcnt(0)
	s_barrier
; #define PG8_STAGE(bufoff, gbase, voff) do { _Pragma("unroll") for (int _i = 0; _i < 2; ++_i) \
;         __builtin_amdgcn_global_load_lds((const unsigned*)((const char*)(gbase) + (voff)[_i]), (LAS unsigned*)(lds + (bufoff) + ldsw + _i * 8192), 16, 0, 0); } while (0)
; #define PG8_LDA(dst, b, h) do { _Pragma("unroll") for (int m = 0; m < 4; ++m) _Pragma("unroll") for (int k = 0; k < 2; ++k) dst[m][k] = *(const LAS bf16x8*)(lds + PG8_SA(b, h) + aoff + m * 2048 + k * 1024); } while (0)
; #define PG8_LDB(dst, b, h) do { _Pragma("unroll") for (int n = 0; n < 2; ++n) _Pragma("unroll") for (int k = 0; k < 2; ++k) dst[n][k] = *(const LAS bf16x8*)(lds + PG8_SB(b, h) + boff + n * 2048 + k * 1024); } while (0)
; #define PG8_WAIT_V(n) asm volatile("s_waitcnt vmcnt(" #n ")" ::: "memory")
; #define PG8_WAIT_L(n) asm volatile("s_waitcnt lgkmcnt(" #n ")" ::: "memory")
; #define PG8_BAR __builtin_amdgcn_s_barrier()
; #define PG8_SCHED __builtin_amdgcn_sched_barrier(0)
; template <class Epi, class Sched, bool SWAPD = false>
; __device__ __forceinline__ void gemm_phase(LAS unsigned char* lds, const Gemm g, const Sched& S, const Epi& E) {
;     ...
;             PG8_WAIT_V(8); PG8_WAIT_L(0); PG8_BAR; PG8_MMA(1, 0, At, B0); PG8_MMA(1, 1, At, B1); PG8_BAR; PG8_SCHED;
;             PG8_LDB(B0, 1, 0); PG8_LDB(B1, 1, 1); PG8_SCHED; PG8_LDA(At, 1, 0); PG8_STAGE(PG8_SA(0, 1), a2 + hstepA, voffA);
;             PG8_WAIT_V(8); PG8_WAIT_L(0); PG8_BAR; PG8_MMA(0, 0, At, B0); PG8_MMA(0, 1, At, B1); PG8_BAR; PG8_SCHED;
	s_setprio 1
	v_mfma_f32_16x16x32_bf16 v[60:63], v[156:159], v[196:199], v[60:63]
	v_mfma_f32_16x16x32_bf16 v[56:59], v[172:175], v[196:199], v[56:59]
	v_mfma_f32_16x16x32_bf16 v[44:47], v[156:159], v[204:207], v[44:47]
	v_mfma_f32_16x16x32_bf16 v[40:43], v[172:175], v[204:207], v[40:43]
	v_mfma_f32_16x16x32_bf16 v[28:31], v[156:159], v[212:215], v[28:31]
	v_mfma_f32_16x16x32_bf16 v[24:27], v[172:175], v[212:215], v[24:27]
	v_mfma_f32_16x16x32_bf16 v[12:15], v[156:159], v[220:223], v[12:15]
	v_mfma_f32_16x16x32_bf16 v[8:11], v[172:175], v[220:223], v[8:11]
	v_mfma_f32_16x16x32_bf16 v[60:63], v[160:163], v[200:203], v[60:63]
	v_mfma_f32_16x16x32_bf16 v[56:59], v[176:179], v[200:203], v[56:59]
	v_mfma_f32_16x16x32_bf16 v[44:47], v[160:163], v[208:211], v[44:47]
	v_mfma_f32_16x16x32_bf16 v[40:43], v[176:179], v[208:211], v[40:43]
	v_mfma_f32_16x16x32_bf16 v[28:31], v[160:163], v[216:219], v[28:31]
	v_mfma_f32_16x16x32_bf16 v[24:27], v[176:179], v[216:219], v[24:27]
	v_mfma_f32_16x16x32_bf16 v[12:15], v[160:163], v[224:227], v[12:15]
	v_mfma_f32_16x16x32_bf16 v[8:11], v[176:179], v[224:227], v[8:11]
	s_setprio 0
	s_setprio 1
	v_mfma_f32_16x16x32_bf16 v[52:55], v[180:183], v[196:199], v[52:55]
	v_mfma_f32_16x16x32_bf16 v[48:51], v[188:191], v[196:199], v[48:51]
	v_mfma_f32_16x16x32_bf16 v[36:39], v[180:183], v[204:207], v[36:39]
	v_mfma_f32_16x16x32_bf16 v[32:35], v[188:191], v[204:207], v[32:35]
	v_mfma_f32_16x16x32_bf16 v[20:23], v[180:183], v[212:215], v[20:23]
	v_mfma_f32_16x16x32_bf16 v[16:19], v[188:191], v[212:215], v[16:19]
	v_mfma_f32_16x16x32_bf16 v[4:7], v[180:183], v[220:223], v[4:7]
	v_mfma_f32_16x16x32_bf16 v[0:3], v[188:191], v[220:223], v[0:3]
	v_mfma_f32_16x16x32_bf16 v[52:55], v[184:187], v[200:203], v[52:55]
	v_mfma_f32_16x16x32_bf16 v[48:51], v[192:195], v[200:203], v[48:51]
	v_mfma_f32_16x16x32_bf16 v[36:39], v[184:187], v[208:211], v[36:39]
	v_mfma_f32_16x16x32_bf16 v[32:35], v[192:195], v[208:211], v[32:35]
	v_mfma_f32_16x16x32_bf16 v[20:23], v[184:187], v[216:219], v[20:23]
	v_mfma_f32_16x16x32_bf16 v[16:19], v[192:195], v[216:219], v[16:19]
	v_mfma_f32_16x16x32_bf16 v[4:7], v[184:187], v[224:227], v[4:7]
	v_mfma_f32_16x16x32_bf16 v[0:3], v[192:195], v[224:227], v[0:3]
	s_setprio 0
	s_barrier
	s_add_i32 s54, 0, 0x18000
	v_add_u32_e32 v171, s54, v166
	s_add_i32 s55, 0, 0x1c000
	ds_read_b128 v[156:159], v171
	ds_read_b128 v[160:163], v171 offset:1024
	ds_read_b128 v[172:175], v171 offset:2048
	ds_read_b128 v[176:179], v171 offset:3072
	v_add_u32_e32 v171, s55, v166
	ds_read_b128 v[180:183], v171
	ds_read_b128 v[184:187], v171 offset:1024
	ds_read_b128 v[188:191], v171 offset:2048
	ds_read_b128 v[192:195], v171 offset:3072
	s_add_u32 s20, s26, 0xb0000
	s_addc_u32 s21, s27, 0
	s_mov_b32 m0, s34
	v_lshl_add_u64 v[234:235], s[20:21], 0, v[128:129]
	ds_read_b128 v[196:199], v170 offset:32768
	ds_read_b128 v[200:203], v170 offset:33792
	ds_read_b128 v[204:207], v170 offset:34816
	ds_read_b128 v[208:211], v170 offset:35840
	ds_read_b128 v[212:215], v170 offset:36864
	ds_read_b128 v[216:219], v170 offset:37888
	ds_read_b128 v[220:223], v170 offset:38912
	ds_read_b128 v[224:227], v170 offset:39936
	global_load_lds_dwordx4 v[234:235], off
	v_lshl_add_u64 v[234:235], s[20:21], 0, v[130:131]
	s_mov_b32 m0, s35
	s_nop 0
	global_load_lds_dwordx4 v[234:235], off
	s_waitcnt vmcnt(8)
	s_waitcnt lgkmcnt(0)
	s_barrier
	s_setprio 1
	v_mfma_f32_16x16x32_bf16 v[124:127], v[156:159], v[196:199], v[124:127]
	v_mfma_f32_16x16x32_bf16 v[120:123], v[172:175], v[196:199], v[120:123]
	v_mfma_f32_16x16x32_bf16 v[108:111], v[156:159], v[204:207], v[108:111]
	v_mfma_f32_16x16x32_bf16 v[104:107], v[172:175], v[204:207], v[104:107]
	v_mfma_f32_16x16x32_bf16 v[92:95], v[156:159], v[212:215], v[92:95]
	v_mfma_f32_16x16x32_bf16 v[88:91], v[172:175], v[212:215], v[88:91]
	v_mfma_f32_16x16x32_bf16 v[76:79], v[156:159], v[220:223], v[76:79]
	v_mfma_f32_16x16x32_bf16 v[72:75], v[172:175], v[220:223], v[72:75]
	v_mfma_f32_16x16x32_bf16 v[124:127], v[160:163], v[200:203], v[124:127]
	v_mfma_f32_16x16x32_bf16 v[120:123], v[176:179], v[200:203], v[120:123]
	v_mfma_f32_16x16x32_bf16 v[108:111], v[160:163], v[208:211], v[108:111]
	v_mfma_f32_16x16x32_bf16 v[104:107], v[176:179], v[208:211], v[104:107]
	v_mfma_f32_16x16x32_bf16 v[92:95], v[160:163], v[216:219], v[92:95]
	v_mfma_f32_16x16x32_bf16 v[88:91], v[176:179], v[216:219], v[88:91]
	v_mfma_f32_16x16x32_bf16 v[76:79], v[160:163], v[224:227], v[76:79]
	v_mfma_f32_16x16x32_bf16 v[72:75], v[176:179], v[224:227], v[72:75]
	s_setprio 0
	s_setprio 1
	v_mfma_f32_16x16x32_bf16 v[116:119], v[180:183], v[196:199], v[116:119]
	v_mfma_f32_16x16x32_bf16 v[112:115], v[188:191], v[196:199], v[112:115]
	v_mfma_f32_16x16x32_bf16 v[100:103], v[180:183], v[204:207], v[100:103]
	v_mfma_f32_16x16x32_bf16 v[96:99], v[188:191], v[204:207], v[96:99]
	v_mfma_f32_16x16x32_bf16 v[84:87], v[180:183], v[212:215], v[84:87]
	v_mfma_f32_16x16x32_bf16 v[80:83], v[188:191], v[212:215], v[80:83]
	v_mfma_f32_16x16x32_bf16 v[68:71], v[180:183], v[220:223], v[68:71]
	v_mfma_f32_16x16x32_bf16 v[64:67], v[188:191], v[220:223], v[64:67]
	v_mfma_f32_16x16x32_bf16 v[116:119], v[184:187], v[200:203], v[116:119]
	v_mfma_f32_16x16x32_bf16 v[112:115], v[192:195], v[200:203], v[112:115]
	v_mfma_f32_16x16x32_bf16 v[100:103], v[184:187], v[208:211], v[100:103]
	v_mfma_f32_16x16x32_bf16 v[96:99], v[192:195], v[208:211], v[96:99]
	v_mfma_f32_16x16x32_bf16 v[84:87], v[184:187], v[216:219], v[84:87]
	v_mfma_f32_16x16x32_bf16 v[80:83], v[192:195], v[216:219], v[80:83]
	v_mfma_f32_16x16x32_bf16 v[68:71], v[184:187], v[224:227], v[68:71]
	v_mfma_f32_16x16x32_bf16 v[64:67], v[192:195], v[224:227], v[64:67]
	s_setprio 0
	s_barrier
; #define PG8_STAGE(bufoff, gbase, voff) do { _Pragma("unroll") for (int _i = 0; _i < 2; ++_i) \
;         __builtin_amdgcn_global_load_lds((const unsigned*)((const char*)(gbase) + (voff)[_i]), (LAS unsigned*)(lds + (bufoff) + ldsw + _i * 8192), 16, 0, 0); } while (0)
; #define PG8_LDA(dst, b, h) do { _Pragma("unroll") for (int m = 0; m < 4; ++m) _Pragma("unroll") for (int k = 0; k < 2; ++k) dst[m][k] = *(const LAS bf16x8*)(lds + PG8_SA(b, h) + aoff + m * 2048 + k * 1024); } while (0)
; #define PG8_WAIT_V(n) asm volatile("s_waitcnt vmcnt(" #n ")" ::: "memory")
; #define PG8_WAIT_L(n) asm volatile("s_waitcnt lgkmcnt(" #n ")" ::: "memory")
; #define PG8_BAR __builtin_amdgcn_s_barrier()
; #define PG8_SCHED __builtin_amdgcn_sched_barrier(0)
; template <class Epi, class Sched, bool SWAPD = false>
; __device__ __forceinline__ void gemm_phase(LAS unsigned char* lds, const Gemm g, const Sched& S, const Epi& E) {
;     ...
;             PG8_LDA(At, 1, 1); PG8_STAGE(PG8_SB(1, 0), b3, voffB); PG8_STAGE(PG8_SB(1, 1), b3 + hstepB, voffB); PG8_STAGE(PG8_SA(1, 0), a3, voffA);
;             PG8_WAIT_V(8); PG8_WAIT_L(0); PG8_BAR; PG8_MMA(1, 0, At, B0); PG8_MMA(1, 1, At, B1); PG8_BAR; PG8_SCHED;
;         }
;         if (wr == 0) PG8_BAR;
	s_add_i32 s20, s54, s30
	v_lshl_add_u64 v[164:165], v[164:165], 0, s[6:7]
	s_mov_b32 m0, s20
	ds_read_b128 v[196:199], v170 offset:49152
	ds_read_b128 v[200:203], v170 offset:50176
	ds_read_b128 v[204:207], v170 offset:51200
	ds_read_b128 v[208:211], v170 offset:52224
	ds_read_b128 v[212:215], v170 offset:53248
	ds_read_b128 v[216:219], v170 offset:54272
	ds_read_b128 v[220:223], v170 offset:55296
	ds_read_b128 v[224:227], v170 offset:56320
	global_load_lds_dwordx4 v[164:165], off
	s_add_i32 m0, s20, 0x2000
	s_add_u32 s20, s24, 0xb0080
	v_lshl_add_u64 v[164:165], v[228:229], 0, s[6:7]
	s_addc_u32 s21, s25, 0
	s_add_i32 s24, s55, s30
	global_load_lds_dwordx4 v[164:165], off
	v_lshl_add_u64 v[164:165], s[20:21], 0, v[128:129]
	s_mov_b32 m0, s24
	s_nop 0
	global_load_lds_dwordx4 v[164:165], off
	v_lshl_add_u64 v[164:165], s[20:21], 0, v[130:131]
	s_add_i32 m0, s24, 0x2000
	s_nop 0
	global_load_lds_dwordx4 v[164:165], off
	v_lshl_add_u64 v[164:165], v[230:231], 0, s[6:7]
	s_mov_b32 m0, s39
	s_nop 0
	global_load_lds_dwordx4 v[164:165], off
	v_lshl_add_u64 v[164:165], v[232:233], 0, s[6:7]
	s_mov_b32 m0, s40
	s_nop 0
	global_load_lds_dwordx4 v[164:165], off
	s_waitcnt vmcnt(8)
	s_waitcnt lgkmcnt(0)
	s_barrier
	s_setprio 1
	v_mfma_f32_16x16x32_bf16 v[60:63], v[156:159], v[196:199], v[60:63]
	v_mfma_f32_16x16x32_bf16 v[56:59], v[172:175], v[196:199], v[56:59]
	v_mfma_f32_16x16x32_bf16 v[44:47], v[156:159], v[204:207], v[44:47]
	v_mfma_f32_16x16x32_bf16 v[40:43], v[172:175], v[204:207], v[40:43]
	v_mfma_f32_16x16x32_bf16 v[28:31], v[156:159], v[212:215], v[28:31]
	v_mfma_f32_16x16x32_bf16 v[24:27], v[172:175], v[212:215], v[24:27]
	v_mfma_f32_16x16x32_bf16 v[12:15], v[156:159], v[220:223], v[12:15]
	v_mfma_f32_16x16x32_bf16 v[8:11], v[172:175], v[220:223], v[8:11]
	v_mfma_f32_16x16x32_bf16 v[60:63], v[160:163], v[200:203], v[60:63]
	v_mfma_f32_16x16x32_bf16 v[56:59], v[176:179], v[200:203], v[56:59]
	v_mfma_f32_16x16x32_bf16 v[44:47], v[160:163], v[208:211], v[44:47]
	v_mfma_f32_16x16x32_bf16 v[40:43], v[176:179], v[208:211], v[40:43]
	v_mfma_f32_16x16x32_bf16 v[28:31], v[160:163], v[216:219], v[28:31]
	v_mfma_f32_16x16x32_bf16 v[24:27], v[176:179], v[216:219], v[24:27]
	v_mfma_f32_16x16x32_bf16 v[12:15], v[160:163], v[224:227], v[12:15]
	v_mfma_f32_16x16x32_bf16 v[8:11], v[176:179], v[224:227], v[8:11]
	s_setprio 0
	s_setprio 1
	v_mfma_f32_16x16x32_bf16 v[52:55], v[180:183], v[196:199], v[52:55]
	v_mfma_f32_16x16x32_bf16 v[48:51], v[188:191], v[196:199], v[48:51]
	v_mfma_f32_16x16x32_bf16 v[36:39], v[180:183], v[204:207], v[36:39]
	v_mfma_f32_16x16x32_bf16 v[32:35], v[188:191], v[204:207], v[32:35]
	v_mfma_f32_16x16x32_bf16 v[20:23], v[180:183], v[212:215], v[20:23]
	v_mfma_f32_16x16x32_bf16 v[16:19], v[188:191], v[212:215], v[16:19]
	v_mfma_f32_16x16x32_bf16 v[4:7], v[180:183], v[220:223], v[4:7]
	v_mfma_f32_16x16x32_bf16 v[0:3], v[188:191], v[220:223], v[0:3]
	v_mfma_f32_16x16x32_bf16 v[52:55], v[184:187], v[200:203], v[52:55]
	v_mfma_f32_16x16x32_bf16 v[48:51], v[192:195], v[200:203], v[48:51]
	v_mfma_f32_16x16x32_bf16 v[36:39], v[184:187], v[208:211], v[36:39]
	v_mfma_f32_16x16x32_bf16 v[32:35], v[192:195], v[208:211], v[32:35]
	v_mfma_f32_16x16x32_bf16 v[20:23], v[184:187], v[216:219], v[20:23]
	v_mfma_f32_16x16x32_bf16 v[16:19], v[192:195], v[216:219], v[16:19]
	v_mfma_f32_16x16x32_bf16 v[4:7], v[184:187], v[224:227], v[4:7]
	v_mfma_f32_16x16x32_bf16 v[0:3], v[192:195], v[224:227], v[0:3]
	s_setprio 0
	s_barrier
	s_add_i32 s53, s53, 2
	s_add_u32 s51, s51, 0x100
	s_addc_u32 s52, s52, 0
	s_cmp_gt_u32 s53, 41
	s_mov_b64 s[20:21], s[22:23]
	s_cbranch_scc0 .LBB0_1940
	s_and_b64 vcc, exec, s[8:9]
	s_cbranch_vccz .LBB0_1943
	s_barrier
